# attention: 4-slot K/V ring, per-tile barrier between QK and PV for waves 0-3 and after PV for waves 4-7 (half-step stagger, second loop copy), loads issued after the staging writes inside PV
# speedup vs baseline: 1.0545x; 1.0146x over previous
; __device__ __forceinline__ void attn_item(const bf16_t* __restrict__ Qb, const bf16_t* __restrict__ Kh, const bf16_t* __restrict__ Vh, const bf16_t* __restrict__ Zb, ...
;     ...
;   constexpr int SLOT = 32768, KOFF = 16384, WSOFF = 3 * SLOT;
;   float* ws = (float*)(lds + WSOFF) + wid * 64; float* al_l = ws + 32;
; __global__ void __launch_bounds__(512, 2) fwd_megakernel(Args a) {
;     ...
;   const float kmaxg = *(const float*)(a.ws + WS_TAB + 262144);
;   if (PH & 8) for (int it = c; it < 1024; it += G) {
;     const int xx = it & 7, rest = it >> 3, bk = xx >> 1, qb = (xx & 1) * 32 + (rest & 31), hq = rest >> 5, kvh = bk & 1, h = kvh * 4 + hq, b = bk >> 1;
;     const long row0 = (long)b * SEQ + qb * 256;
;     att::attn_item(P1 + row0 * LDP + C_Q + h * 128, P1 + (long)b * SEQ * LDP + C_K + kvh * 128, P1 + (long)b * SEQ * LDP + C_V + kvh * 128,
;                    P1 + row0 * LDP + C_ZA + h * 128, AF + row0 * LDAF + h * 128, SEQ, (char*)lds, wid_s, a.in[3], qb * 256, kmaxg);
.LBB0_449:
	s_or_b64 exec, exec, s[0:1]
	s_waitcnt lgkmcnt(0)
	v_cndmask_b32_e64 v0, 0, 1, s[6:7]
	v_cmp_ne_u32_e64 s[4:5], 1, v0
	s_andn2_b64 vcc, exec, s[6:7]
	s_barrier
	s_cbranch_vccnz .LBB0_479
	v_mov_b32_e32 v0, 0x1f540000
	global_load_dword v216, v0, s[42:43]
	s_lshr_b32 s0, s76, 6
	s_lshl_b32 s1, s33, 2
	s_add_i32 s38, s1, 0
	s_lshl_b32 s1, s0, 5
	s_mul_i32 s39, s0, 0x18000
	s_mul_i32 s50, s0, 0x41000
	s_lshl_b32 s0, s0, 13
	s_add_i32 s38, s38, 0x20000
	s_add_i32 s53, s0, 0
	s_add_u32 s20, s42, 0x1c7a00
	s_movk_i32 s48, 0xc00
	s_mul_hi_u32 s49, s1, 0xc00
	s_movk_i32 s51, 0x2080
	s_mul_hi_u32 s52, s1, 0x2080
	s_addc_u32 s21, s43, 0
	s_lshl_b32 s54, s2, 12
	s_lshl_b32 s55, s34, 12
	s_add_i32 s56, 0, 0x20000
	s_movk_i32 s57, 0xffe0
	v_mov_b32_e32 v1, 0
	v_mov_b32_e32 v217, 0x358637bd
	s_mov_b32 s58, 0x7ffffc
	s_movk_i32 s59, 0xe0
	s_movk_i32 s60, 0xc0
	s_movk_i32 s61, 0x1040
	s_movk_i32 s62, 0x60
	s_movk_i32 s63, 0x80
	s_movk_i32 s64, 0xa0
	s_mov_b32 s65, 0xf800000
	v_mov_b32_e32 v218, 0x260
	s_mov_b32 s66, 0x42b40000
	s_mov_b32 s67, 0xfff3d000
	s_mov_b32 s68, 0xfff7e000
	s_mov_b32 s69, 0x4138aa3b
	s_mov_b64 s[22:23], 0x104000
	s_mov_b32 s70, s2
	s_branch .LBB0_452

; __device__ __forceinline__ int lane_id_asm() { int r; asm volatile("v_mbcnt_lo_u32_b32 %0, -1, 0\n\tv_mbcnt_hi_u32_b32 %0, -1, %0" : "=v"(r)); return r; }
; __device__ __forceinline__ void attn_item(const bf16_t* __restrict__ Qb, const bf16_t* __restrict__ Kh, const bf16_t* __restrict__ Vh, const bf16_t* __restrict__ Zb, ...
;     ...
;     for (int d0 = 0; d0 < 8; ++d0) qw[d0] = *reinterpret_cast<const u32x4*>(Qw + d0 * 16);
;     float ss = 0.f;
; #pragma unroll
;     for (int d0 = 0; d0 < 8; ++d0) { const float a0 = bflo(qw[d0].x), a1 = bfhi(qw[d0].x), a2 = bflo(qw[d0].y), a3 = bfhi(qw[d0].y), a4 = bflo(qw[d0].z), a5 = bfhi(qw[d0].z), a6 = bflo(qw[d0].w), a7 = bfhi(qw[d0].w);
;       ss += (a0 * a0 + a1 * a1) + (a2 * a2 + a3 * a3) + (a4 * a4 + a5 * a5) + (a6 * a6 + a7 * a7); }
;     { auto rr = __builtin_amdgcn_permlane32_swap(__float_as_uint(ss), __float_as_uint(ss), false, false); ss = __uint_as_float(rr[0]) + __uint_as_float(rr[1]); }
;     const float rstd = __builtin_amdgcn_rsqf(ss * (1.0f / 128.0f) + NORM_EPS) * (SCALE * 1.4426950408889634f);
;     const int hq = lane_id_asm() >> 5;
;     const int spos = qpos0 + wid * QBLK + r32; const float prow = (float)(spos >> 6), pcol = (float)(spos & 63);
; #pragma unroll
;     for (int bb = 0; bb < 4; ++bb) { const int d1 = (bb & 1) + 4 * (bb >> 1), d2 = d1 + 2;
;       const float pos = (bb < 2) ? prow : pcol; const float* g1p = qg + d1 * 16 + hq * 8; const float* g2p = qg + d2 * 16 + hq * 8;
;       const f32x4 g1a = *(const f32x4*)g1p, g1b = *(const f32x4*)(g1p + 4), g2a = *(const f32x4*)g2p, g2b = *(const f32x4*)(g2p + 4);
;       float o1[8], o2[8];
; #pragma unroll
;       for (int e = 0; e < 8; ++e) { const unsigned w1 = (e < 2) ? qw[d1].x : (e < 4) ? qw[d1].y : (e < 6) ? qw[d1].z : qw[d1].w, w2 = (e < 2) ? qw[d2].x : (e < 4) ? qw[d2].y : (e < 6) ? qw[d2].z : qw[d2].w;
; __global__ void __launch_bounds__(512, 2) fwd_megakernel(Args a) {
;     ...
;     const int xx = it & 7, rest = it >> 3, bk = xx >> 1, qb = (xx & 1) * 32 + (rest & 31), hq = rest >> 5, kvh = bk & 1, h = kvh * 4 + hq, b = bk >> 1;
;     const long row0 = (long)b * SEQ + qb * 256;
;     att::attn_item(P1 + row0 * LDP + C_Q + h * 128, P1 + (long)b * SEQ * LDP + C_K + kvh * 128, P1 + (long)b * SEQ * LDP + C_V + kvh * 128,
;                    P1 + row0 * LDP + C_ZA + h * 128, AF + row0 * LDAF + h * 128, SEQ, (char*)lds, wid_s, a.in[3], qb * 256, kmaxg);
.LBB0_452:
	s_lshl_b32 s0, s70, 5
	s_and_b32 s0, s0, 32
	s_bfe_u32 s7, s70, 0x50003
	s_or_b32 s7, s0, s7
	s_lshl_b32 s0, s70, 12
	s_and_b32 s0, s0, 0x4000
	s_lshl_b32 s7, s7, 8
	s_bfe_u32 s1, s70, 0x10001
	s_or_b32 s71, s7, s0
	s_bfe_u32 s6, s54, 0x1000e
	s_lshl_b32 s8, s1, 8
	s_mul_i32 s9, s71, 0x2080
	s_add_u32 s9, s42, s9
	s_addc_u32 s36, s43, 0
	s_ashr_i32 s24, s70, 1
	s_lshl_b32 s1, s1, 9
	s_and_b32 s24, s24, 0xffffff80
	s_add_i32 s24, s1, s24
	s_ashr_i32 s25, s24, 31
	s_lshl_b64 s[26:27], s[24:25], 1
	s_add_u32 s24, s9, s26
	v_mbcnt_lo_u32_b32 v0, -1, 0
	v_mbcnt_hi_u32_b32 v0, -1, v0
	s_addc_u32 s25, s36, s27
	v_add_u32_e32 v186, s33, v0
	v_mov_b64_e32 v[2:3], s[24:25]
	v_ashrrev_i32_e32 v0, 1, v186
	v_and_b32_e32 v4, 0xffffffe0, v0
	v_bfi_b32 v0, s57, v0, v186
	v_lshrrev_b32_e32 v188, 1, v186
	v_mad_i64_i32 v[2:3], s[36:37], v0, s51, v[2:3]
	v_and_b32_e32 v212, 16, v188
	v_mov_b32_e32 v213, v1
	v_mov_b32_e32 v16, v1
	v_mov_b32_e32 v17, v1
	v_mov_b32_e32 v18, v1
	v_mov_b32_e32 v19, v1
	v_mov_b32_e32 v20, v1
	v_mov_b32_e32 v21, v1
	v_mov_b32_e32 v22, v1
	v_mov_b32_e32 v23, v1
	v_mov_b32_e32 v24, v1
	v_mov_b32_e32 v25, v1
	v_mov_b32_e32 v26, v1
	v_mov_b32_e32 v27, v1
	v_mov_b32_e32 v28, v1
	v_mov_b32_e32 v29, v1
	v_mov_b32_e32 v30, v1
	v_mov_b32_e32 v31, v1
	v_lshl_add_u64 v[2:3], v[2:3], 0, v[212:213]
	global_load_dwordx4 v[36:39], v[2:3], off
	global_load_dwordx4 v[44:47], v[2:3], off offset:32
	global_load_dwordx4 v[40:43], v[2:3], off offset:64
	global_load_dwordx4 v[48:51], v[2:3], off offset:96
	global_load_dwordx4 v[52:55], v[2:3], off offset:128
	global_load_dwordx4 v[60:63], v[2:3], off offset:160
	global_load_dwordx4 v[56:59], v[2:3], off offset:192
	global_load_dwordx4 v[64:67], v[2:3], off offset:224
	v_mbcnt_lo_u32_b32 v0, -1, 0
	v_mbcnt_hi_u32_b32 v0, -1, v0
	v_and_b32_e32 v187, 31, v186
	v_ashrrev_i32_e32 v0, 2, v0
	v_and_b32_e32 v78, -8, v0
	v_or_b32_e32 v69, 1, v78
	v_cvt_f32_i32_e32 v69, v69
	v_cvt_f32_i32_e32 v6, v78
	v_or_b32_e32 v2, s7, v187
	s_waitcnt vmcnt(22)
	v_add_u32_e32 v136, v2, v4
	v_mul_f32_e32 v69, 0xbed49a78, v69
	v_exp_f32_e32 v69, v69
	v_mul_f32_e32 v6, 0xbed49a78, v6
	v_ashrrev_i32_e32 v2, 6, v136
	v_exp_f32_e32 v68, v6
	v_mul_f32_e32 v138, 0.15915494, v69
	v_or_b32_e32 v69, 2, v78
	s_waitcnt vmcnt(20)
	v_cvt_f32_i32_e32 v145, v2
	v_cvt_f32_i32_e32 v69, v69
	v_ashrrev_i32_e32 v79, 31, v78
	v_lshl_add_u64 v[14:15], v[78:79], 2, s[18:19]
	global_load_dwordx4 v[10:13], v[14:15], off
	global_load_dwordx4 v[2:5], v[14:15], off offset:16
	global_load_dwordx4 v[32:35], v[14:15], off offset:128
	global_load_dwordx4 v[6:9], v[14:15], off offset:144
	v_mul_f32_e32 v137, 0.15915494, v68
	v_mul_f32_e32 v68, v137, v145
	v_mul_f32_e32 v69, 0xbed49a78, v69
	v_floor_f32_e32 v68, v68
	v_exp_f32_e32 v69, v69
	v_fma_f32 v68, v137, v145, -v68
	v_sin_f32_e32 v104, v68
	v_cos_f32_e32 v105, v68
	v_mul_f32_e32 v68, v138, v145
	v_floor_f32_e32 v68, v68
	v_fma_f32 v68, v138, v145, -v68
	v_mul_f32_e32 v139, 0.15915494, v69
	v_sin_f32_e32 v83, v68
	v_cos_f32_e32 v82, v68
	v_or_b32_e32 v68, 3, v78
	v_mul_f32_e32 v69, v139, v145
	v_cvt_f32_i32_e32 v68, v68
	v_floor_f32_e32 v69, v69
	v_fma_f32 v69, v139, v145, -v69
	v_sin_f32_e32 v106, v69
	v_cos_f32_e32 v107, v69
	v_or_b32_e32 v69, 4, v78
	v_cvt_f32_i32_e32 v69, v69
	v_mul_f32_e32 v68, 0xbed49a78, v68
	v_exp_f32_e32 v68, v68
	v_or_b32_e32 v0, 7, v0
	v_mul_f32_e32 v69, 0xbed49a78, v69
	v_exp_f32_e32 v69, v69
	v_mul_f32_e32 v140, 0.15915494, v68
	v_mul_f32_e32 v68, v140, v145
	v_floor_f32_e32 v68, v68
	v_fma_f32 v68, v140, v145, -v68
	v_mul_f32_e32 v141, 0.15915494, v69
	v_sin_f32_e32 v97, v68
	v_cos_f32_e32 v96, v68
	v_or_b32_e32 v68, 5, v78
	v_mul_f32_e32 v69, v141, v145
	v_cvt_f32_i32_e32 v68, v68
	v_floor_f32_e32 v69, v69
	v_fma_f32 v69, v141, v145, -v69
	v_sin_f32_e32 v108, v69
	v_cos_f32_e32 v109, v69
	v_or_b32_e32 v69, 6, v78
	v_cvt_f32_i32_e32 v69, v69
	v_mul_f32_e32 v68, 0xbed49a78, v68
	v_exp_f32_e32 v68, v68
	v_cvt_f32_i32_e32 v0, v0
	v_mul_f32_e32 v69, 0xbed49a78, v69
	v_exp_f32_e32 v69, v69
	v_mul_f32_e32 v142, 0.15915494, v68
	v_mul_f32_e32 v68, v142, v145
	v_floor_f32_e32 v68, v68
	v_fma_f32 v68, v142, v145, -v68
	v_mul_f32_e32 v143, 0.15915494, v69
	v_mul_f32_e32 v0, 0xbed49a78, v0
	v_sin_f32_e32 v101, v68
	v_cos_f32_e32 v100, v68
	v_mul_f32_e32 v68, v143, v145
	v_exp_f32_e32 v0, v0
	v_floor_f32_e32 v68, v68
	v_fma_f32 v68, v143, v145, -v68
	v_sin_f32_e32 v110, v68
	v_cos_f32_e32 v111, v68
	v_add_u32_e32 v68, 16, v78
	v_mul_f32_e32 v144, 0.15915494, v0
	v_cvt_f32_i32_e32 v68, v68
	v_mul_f32_e32 v0, v144, v145
	v_floor_f32_e32 v0, v0
	v_fma_f32 v0, v144, v145, -v0
	v_sin_f32_e32 v99, v0
	v_cos_f32_e32 v98, v0
	v_mul_f32_e32 v0, 0xbed49a78, v68
	s_waitcnt vmcnt(5)
; __device__ __forceinline__ float bflo(unsigned w) { return __uint_as_float(w << 16); }
; __device__ __forceinline__ float bfhi(unsigned w) { return __uint_as_float(w & 0xffff0000u); }
; __device__ __forceinline__ void attn_item(const bf16_t* __restrict__ Qb, const bf16_t* __restrict__ Kh, const bf16_t* __restrict__ Vh, const bf16_t* __restrict__ Zb, ...
;     ...
;     for (int d0 = 0; d0 < 8; ++d0) qw[d0] = *reinterpret_cast<const u32x4*>(Qw + d0 * 16);
;     float ss = 0.f;
; #pragma unroll
;     for (int d0 = 0; d0 < 8; ++d0) { const float a0 = bflo(qw[d0].x), a1 = bfhi(qw[d0].x), a2 = bflo(qw[d0].y), a3 = bfhi(qw[d0].y), a4 = bflo(qw[d0].z), a5 = bfhi(qw[d0].z), a6 = bflo(qw[d0].w), a7 = bfhi(qw[d0].w);
;       ss += (a0 * a0 + a1 * a1) + (a2 * a2 + a3 * a3) + (a4 * a4 + a5 * a5) + (a6 * a6 + a7 * a7); }
;     { auto rr = __builtin_amdgcn_permlane32_swap(__float_as_uint(ss), __float_as_uint(ss), false, false); ss = __uint_as_float(rr[0]) + __uint_as_float(rr[1]); }
	v_lshlrev_b32_e32 v93, 16, v57
	v_and_b32_e32 v91, 0xffff0000, v57
	v_and_b32_e32 v155, 0xffff0000, v43
	v_and_b32_e32 v157, 0xffff0000, v42
	v_exp_f32_e32 v79, v0
	v_mov_b32_e32 v94, v93
	v_mov_b32_e32 v95, v91
	v_mul_f32_e32 v0, v91, v91
	v_lshlrev_b32_e32 v113, 16, v49
	v_and_b32_e32 v123, 0xffff0000, v49
	v_lshlrev_b32_e32 v57, 16, v43
	v_lshlrev_b32_e32 v49, 16, v42
	v_mov_b32_e32 v42, v155
	v_mov_b32_e32 v43, v157
	v_pk_fma_f32 v[150:151], v[94:95], v[94:95], v[0:1] op_sel_hi:[1,1,0]
	v_lshlrev_b32_e32 v103, 16, v56
	v_and_b32_e32 v95, 0xffff0000, v56
	v_lshlrev_b32_e32 v125, 16, v48
	v_and_b32_e32 v117, 0xffff0000, v48
	v_lshlrev_b32_e32 v56, 16, v39
	v_and_b32_e32 v154, 0xffff0000, v39
	v_lshlrev_b32_e32 v48, 16, v38
	v_and_b32_e32 v156, 0xffff0000, v38
	v_mov_b32_e32 v38, v57
	v_mov_b32_e32 v39, v49
	v_pk_mul_f32 v[42:43], v[42:43], v[42:43]
	v_and_b32_e32 v159, 0xffff0000, v41
	v_pk_fma_f32 v[38:39], v[38:39], v[38:39], v[42:43]
	v_lshlrev_b32_e32 v43, 16, v41
	v_and_b32_e32 v41, 0xffff0000, v40
	v_and_b32_e32 v118, 0xffff0000, v47
	v_lshlrev_b32_e32 v161, 16, v40
	v_mov_b32_e32 v162, v41
	v_mov_b32_e32 v163, v159
	v_and_b32_e32 v70, 0xffff0000, v63
	v_lshlrev_b32_e32 v72, 16, v62
	v_and_b32_e32 v62, 0xffff0000, v62
	v_lshlrev_b32_e32 v114, 16, v47
	v_and_b32_e32 v120, 0xffff0000, v46
	v_lshlrev_b32_e32 v42, 16, v37
	v_and_b32_e32 v158, 0xffff0000, v37
	v_lshlrev_b32_e32 v160, 16, v36
	v_and_b32_e32 v40, 0xffff0000, v36
	v_mov_b32_e32 v36, v161
	v_mov_b32_e32 v37, v43
	v_pk_mul_f32 v[162:163], v[162:163], v[162:163]
	v_mov_b32_e32 v164, v154
	v_mov_b32_e32 v165, v118
	v_lshlrev_b32_e32 v68, 16, v63
	v_mov_b32_e32 v74, v70
	v_mov_b32_e32 v75, v62
	v_lshlrev_b32_e32 v126, 16, v46
	v_and_b32_e32 v122, 0xffff0000, v45
	v_pk_fma_f32 v[36:37], v[36:37], v[36:37], v[162:163]
	v_mov_b32_e32 v162, v56
	v_mov_b32_e32 v163, v114
	v_pk_mul_f32 v[164:165], v[164:165], v[164:165]
	v_mov_b32_e32 v166, v156
	v_mov_b32_e32 v167, v120
	s_waitcnt vmcnt(4)
	v_lshlrev_b32_e32 v69, 16, v67
	v_and_b32_e32 v71, 0xffff0000, v67
	v_lshlrev_b32_e32 v73, 16, v66
	v_and_b32_e32 v63, 0xffff0000, v66
	v_mov_b32_e32 v66, v68
	v_mov_b32_e32 v67, v72
	v_pk_mul_f32 v[74:75], v[74:75], v[74:75]
	v_lshlrev_b32_e32 v112, 16, v45
	v_and_b32_e32 v116, 0xffff0000, v44
	v_pk_fma_f32 v[162:163], v[162:163], v[162:163], v[164:165]
	v_mov_b32_e32 v164, v48
	v_mov_b32_e32 v165, v126
	v_pk_mul_f32 v[166:167], v[166:167], v[166:167]
	v_mov_b32_e32 v168, v158
	v_mov_b32_e32 v169, v122
	v_pk_fma_f32 v[80:81], v[66:67], v[66:67], v[74:75]
	v_and_b32_e32 v66, 0xffff0000, v61
	v_lshlrev_b32_e32 v76, 16, v60
	v_and_b32_e32 v60, 0xffff0000, v60
	v_lshlrev_b32_e32 v124, 16, v44
	v_pk_fma_f32 v[164:165], v[164:165], v[164:165], v[166:167]
	v_mov_b32_e32 v166, v42
	v_mov_b32_e32 v167, v112
	v_pk_mul_f32 v[168:169], v[168:169], v[168:169]
	v_mov_b32_e32 v170, v40
	v_mov_b32_e32 v171, v116
	v_lshlrev_b32_e32 v74, 16, v61
	v_mov_b32_e32 v84, v60
	v_mov_b32_e32 v85, v66
	v_pk_fma_f32 v[166:167], v[166:167], v[166:167], v[168:169]
	v_mov_b32_e32 v168, v160
	v_mov_b32_e32 v169, v124
	v_pk_mul_f32 v[170:171], v[170:171], v[170:171]
	v_lshlrev_b32_e32 v75, 16, v65
	v_and_b32_e32 v67, 0xffff0000, v65
	v_lshlrev_b32_e32 v77, 16, v64
	v_and_b32_e32 v61, 0xffff0000, v64
	v_mov_b32_e32 v64, v76
	v_mov_b32_e32 v65, v74
	v_pk_mul_f32 v[84:85], v[84:85], v[84:85]
	v_pk_fma_f32 v[168:169], v[168:169], v[168:169], v[170:171]
	v_pk_fma_f32 v[64:65], v[64:65], v[64:65], v[84:85]
	v_lshlrev_b32_e32 v92, 16, v53
	v_and_b32_e32 v90, 0xffff0000, v53
	v_lshlrev_b32_e32 v102, 16, v52
	v_and_b32_e32 v94, 0xffff0000, v52
	v_mov_b32_e32 v52, v103
	v_mov_b32_e32 v53, v95
	v_mul_f32_e32 v0, v95, v95
	v_pk_add_f32 v[166:167], v[168:169], v[166:167]
	v_pk_add_f32 v[64:65], v[64:65], v[64:65] op_sel:[0,1] op_sel_hi:[1,0]
	v_and_b32_e32 v87, 0xffff0000, v58
	v_and_b32_e32 v86, 0xffff0000, v54
	v_pk_fma_f32 v[52:53], v[52:53], v[52:53], v[0:1] op_sel_hi:[1,1,0]
	v_and_b32_e32 v119, 0xffff0000, v51
	v_mov_b32_e32 v46, v113
	v_mov_b32_e32 v47, v123
	v_mul_f32_e32 v0, v123, v123
	v_pk_add_f32 v[36:37], v[36:37], v[36:37] op_sel:[0,1] op_sel_hi:[1,0]
	v_pk_add_f32 v[164:165], v[164:165], v[166:167]
	v_pk_add_f32 v[64:65], v[80:81], v[64:65] op_sel:[1,0] op_sel_hi:[0,1]
	v_lshlrev_b32_e32 v89, 16, v58
	v_lshlrev_b32_e32 v88, 16, v54
	v_lshlrev_b32_e32 v115, 16, v51
	v_and_b32_e32 v121, 0xffff0000, v50
	v_pk_fma_f32 v[46:47], v[46:47], v[46:47], v[0:1] op_sel_hi:[1,1,0]
	v_mov_b32_e32 v44, v125
	v_mov_b32_e32 v45, v117
	v_mul_f32_e32 v0, v117, v117
	v_pk_add_f32 v[36:37], v[38:39], v[36:37] op_sel:[1,0] op_sel_hi:[0,1]
	v_pk_add_f32 v[162:163], v[162:163], v[164:165]
	v_pk_mov_b32 v[164:165], v[118:119], v[86:87] op_sel:[1,0]
	v_pk_add_f32 v[64:65], v[80:81], v[64:65]
	v_lshlrev_b32_e32 v85, 16, v59
	v_lshlrev_b32_e32 v84, 16, v55
	v_and_b32_e32 v81, 0xffff0000, v59
	v_and_b32_e32 v80, 0xffff0000, v55
	v_pk_mul_f32 v[54:55], v[92:93], v[92:93]
	v_pk_mul_f32 v[58:59], v[90:91], v[90:91]
	v_lshlrev_b32_e32 v127, 16, v50
	v_pk_fma_f32 v[44:45], v[44:45], v[44:45], v[0:1] op_sel_hi:[1,1,0]
	v_pk_add_f32 v[36:37], v[38:39], v[36:37]
	v_pk_add_f32 v[38:39], v[162:163], v[162:163] op_sel:[0,1] op_sel_hi:[1,0]
	v_pk_mov_b32 v[162:163], v[114:115], v[88:89] op_sel:[1,0]
	v_pk_mul_f32 v[164:165], v[164:165], v[164:165]
	v_pk_mov_b32 v[166:167], v[120:121], v[94:95] op_sel:[1,0]
	v_pk_fma_f32 v[162:163], v[162:163], v[162:163], v[164:165]
	v_pk_mov_b32 v[164:165], v[126:127], v[102:103] op_sel:[1,0]
	v_pk_mul_f32 v[166:167], v[166:167], v[166:167]
	v_mov_b32_e32 v45, v54
	v_mov_b32_e32 v47, v58
	v_pk_mul_f32 v[146:147], v[84:85], v[84:85]
	v_pk_mul_f32 v[148:149], v[80:81], v[80:81]
	v_pk_fma_f32 v[164:165], v[164:165], v[164:165], v[166:167]
	v_pk_add_f32 v[44:45], v[44:45], v[46:47]
	v_mov_b32_e32 v39, v146
	v_pk_add_f32 v[44:45], v[164:165], v[44:45]
	v_mov_b32_e32 v37, v148
	v_pk_add_f32 v[44:45], v[162:163], v[44:45]
	v_pk_add_f32 v[36:37], v[38:39], v[36:37]
	v_pk_mul_f32 v[132:133], v[74:75], v[74:75]
	v_pk_add_f32 v[36:37], v[36:37], v[44:45]
	v_mov_b32_e32 v44, v81
	v_mov_b32_e32 v45, v63
	v_pk_mul_f32 v[134:135], v[66:67], v[66:67]
	v_mov_b32_e32 v38, v85
	v_mov_b32_e32 v39, v73
	v_pk_mul_f32 v[44:45], v[44:45], v[44:45]
	v_mov_b32_e32 v46, v87
	v_mov_b32_e32 v47, v61
	v_pk_fma_f32 v[38:39], v[38:39], v[38:39], v[44:45]
	v_mov_b32_e32 v44, v89
	v_mov_b32_e32 v45, v77
	v_pk_mul_f32 v[46:47], v[46:47], v[46:47]
	v_mov_b32_e32 v53, v133
	v_mov_b32_e32 v151, v135
	v_pk_mul_f32 v[128:129], v[68:69], v[68:69]
	v_pk_mul_f32 v[130:131], v[70:71], v[70:71]
	v_pk_add_f32 v[36:37], v[36:37], v[36:37] op_sel:[0,1] op_sel_hi:[1,0]
	v_pk_fma_f32 v[44:45], v[44:45], v[44:45], v[46:47]
	v_pk_add_f32 v[46:47], v[52:53], v[150:151]
	v_mov_b32_e32 v37, v129
	v_pk_add_f32 v[44:45], v[44:45], v[46:47]
	v_mov_b32_e32 v65, v131
	v_pk_add_f32 v[38:39], v[38:39], v[44:45]
	v_pk_add_f32 v[36:37], v[36:37], v[64:65]
	s_waitcnt vmcnt(2)
; __device__ __forceinline__ int lane_id_asm() { int r; asm volatile("v_mbcnt_lo_u32_b32 %0, -1, 0\n\tv_mbcnt_hi_u32_b32 %0, -1, %0" : "=v"(r)); return r; }
; __device__ __forceinline__ float bflo(unsigned w) { return __uint_as_float(w << 16); }
; __device__ __forceinline__ void attn_item(const bf16_t* __restrict__ Qb, const bf16_t* __restrict__ Kh, const bf16_t* __restrict__ Vh, const bf16_t* __restrict__ Zb, ...
;     ...
;     { auto rr = __builtin_amdgcn_permlane32_swap(__float_as_uint(ss), __float_as_uint(ss), false, false); ss = __uint_as_float(rr[0]) + __uint_as_float(rr[1]); }
;     const float rstd = __builtin_amdgcn_rsqf(ss * (1.0f / 128.0f) + NORM_EPS) * (SCALE * 1.4426950408889634f);
;     const int hq = lane_id_asm() >> 5;
;     const int spos = qpos0 + wid * QBLK + r32; const float prow = (float)(spos >> 6), pcol = (float)(spos & 63);
; #pragma unroll
;     for (int bb = 0; bb < 4; ++bb) { const int d1 = (bb & 1) + 4 * (bb >> 1), d2 = d1 + 2;
;       const float pos = (bb < 2) ? prow : pcol; const float* g1p = qg + d1 * 16 + hq * 8; const float* g2p = qg + d2 * 16 + hq * 8;
;       const f32x4 g1a = *(const f32x4*)g1p, g1b = *(const f32x4*)(g1p + 4), g2a = *(const f32x4*)g2p, g2b = *(const f32x4*)(g2p + 4);
;       float o1[8], o2[8];
; #pragma unroll
;       for (int e = 0; e < 8; ++e) { const unsigned w1 = (e < 2) ? qw[d1].x : (e < 4) ? qw[d1].y : (e < 6) ? qw[d1].z : qw[d1].w, w2 = (e < 2) ? qw[d2].x : (e < 4) ? qw[d2].y : (e < 6) ? qw[d2].z : qw[d2].w;
;         const float x1 = (e & 1) ? bfhi(w1) : bflo(w1), x2 = (e & 1) ? bfhi(w2) : bflo(w2); const float ga = (e < 4) ? g1a[e & 3] : g1b[e & 3], gb = (e < 4) ? g2a[e & 3] : g2b[e & 3];
;         const int fi = (d1 & 1) * 16 + hq * 8 + e; float rev = pos * (__builtin_amdgcn_exp2f(-(float)fi * (13.287712379549449f / 32.0f)) * 0.15915494309189535f); rev -= floorf(rev);
;         const float sn = sin_rev(rev), cs = cos_rev(rev), y1 = x1 * rstd * ga, y2 = x2 * rstd * gb; o1[e] = y1 * cs - y2 * sn; o2[e] = y2 * cs + y1 * sn; }
; #pragma unroll
;       for (int e = 0; e < 8; ++e) qn2 += o1[e] * o1[e] + o2[e] * o2[e];
;       u32x4 p1 = {cvtpk(o1[0], o1[1]), cvtpk(o1[2], o1[3]), cvtpk(o1[4], o1[5]), cvtpk(o1[6], o1[7])}, p2 = {cvtpk(o2[0], o2[1]), cvtpk(o2[2], o2[3]), cvtpk(o2[4], o2[5]), cvtpk(o2[6], o2[7])};
;       qr[d1] = *reinterpret_cast<bf16x8*>(&p1); qr[d2] = *reinterpret_cast<bf16x8*>(&p2); }
	v_mov_b32_e32 v50, v2
	v_pk_add_f32 v[36:37], v[36:37], v[38:39]
	v_mov_b32_e32 v128, v12
	v_pk_add_f32 v[36:37], v[36:37], v[36:37] op_sel:[0,1] op_sel_hi:[1,0]
	s_waitcnt vmcnt(1)
	v_mov_b32_e32 v129, v34
	v_mov_b32_e32 v0, v36
	s_nop 1
	v_permlane32_swap_b32_e32 v36, v0
	v_add_f32_e32 v0, v36, v0
	v_fmamk_f32 v0, v0, 0x3c000000, v217
	v_rsq_f32_e32 v0, v0
	v_mov_b32_e32 v36, v10
	v_mov_b32_e32 v37, v32
	v_mov_b32_e32 v32, v11
	v_mul_f32_e32 v0, 0x3e0293ee, v0
	v_pk_mul_f32 v[38:39], v[0:1], v[160:161] op_sel_hi:[0,1]
	v_pk_mul_f32 v[38:39], v[36:37], v[38:39]
	v_mov_b32_e32 v36, v105
	v_mov_b32_e32 v37, v104
	v_mul_f32_e32 v2, v39, v104
	v_pk_mul_f32 v[40:41], v[0:1], v[40:41] op_sel_hi:[0,1]
	v_pk_fma_f32 v[36:37], v[38:39], v[36:37], v[2:3] op_sel_hi:[1,1,0] neg_lo:[0,0,1] neg_hi:[0,0,1]
	v_mul_f32_e32 v2, v39, v105
	v_pk_mul_f32 v[10:11], v[32:33], v[40:41]
	v_pk_fma_f32 v[38:39], v[38:39], v[104:105], v[2:3] op_sel_hi:[1,1,0]
	v_mul_f32_e32 v2, v11, v83
	v_pk_fma_f32 v[32:33], v[10:11], v[82:83], v[2:3] op_sel_hi:[1,1,0] neg_lo:[0,0,1] neg_hi:[0,0,1]
	v_mov_b32_e32 v40, v83
	v_mov_b32_e32 v41, v82
	v_mul_f32_e32 v2, v11, v82
	v_pk_fma_f32 v[40:41], v[10:11], v[40:41], v[2:3] op_sel_hi:[1,1,0]
	v_pk_mul_f32 v[10:11], v[0:1], v[42:43] op_sel_hi:[0,1]
	v_pk_mul_f32 v[10:11], v[128:129], v[10:11]
	v_mov_b32_e32 v42, v107
	v_mov_b32_e32 v43, v106
	v_mul_f32_e32 v2, v11, v106
	v_pk_fma_f32 v[42:43], v[10:11], v[42:43], v[2:3] op_sel_hi:[1,1,0] neg_lo:[0,0,1] neg_hi:[0,0,1]
	v_mul_f32_e32 v2, v11, v107
	v_pk_fma_f32 v[44:45], v[10:11], v[106:107], v[2:3] op_sel_hi:[1,1,0]
	v_pk_mul_f32 v[10:11], v[0:1], v[158:159] op_sel_hi:[0,1]
	v_mov_b32_e32 v34, v13
	v_pk_mul_f32 v[10:11], v[34:35], v[10:11]
	v_mov_b32_e32 v12, v97
	v_mul_f32_e32 v2, v11, v97
	v_pk_fma_f32 v[34:35], v[10:11], v[96:97], v[2:3] op_sel_hi:[1,1,0] neg_lo:[0,0,1] neg_hi:[0,0,1]
	v_mov_b32_e32 v13, v96
	v_mul_f32_e32 v2, v11, v96
	s_waitcnt vmcnt(0)
	v_mov_b32_e32 v51, v6
	v_pk_fma_f32 v[46:47], v[10:11], v[12:13], v[2:3] op_sel_hi:[1,1,0]
	v_pk_mul_f32 v[10:11], v[0:1], v[48:49] op_sel_hi:[0,1]
	v_pk_mul_f32 v[10:11], v[50:51], v[10:11]
	v_mov_b32_e32 v12, v109
	v_mov_b32_e32 v13, v108
	v_mul_f32_e32 v2, v11, v108
	v_pk_fma_f32 v[48:49], v[10:11], v[12:13], v[2:3] op_sel_hi:[1,1,0] neg_lo:[0,0,1] neg_hi:[0,0,1]
	v_mul_f32_e32 v2, v11, v109
	v_pk_fma_f32 v[50:51], v[10:11], v[108:109], v[2:3] op_sel_hi:[1,1,0]
	v_pk_mul_f32 v[10:11], v[0:1], v[156:157] op_sel_hi:[0,1]
	v_mov_b32_e32 v6, v3
	v_pk_mul_f32 v[2:3], v[6:7], v[10:11]
	v_mov_b32_e32 v152, v4
	v_mul_f32_e32 v4, v3, v101
	v_pk_fma_f32 v[52:53], v[2:3], v[100:101], v[4:5] op_sel_hi:[1,1,0] neg_lo:[0,0,1] neg_hi:[0,0,1]
	v_mov_b32_e32 v6, v101
	v_mov_b32_e32 v7, v100
	v_mul_f32_e32 v4, v3, v100
	v_mov_b32_e32 v153, v8
	v_pk_fma_f32 v[54:55], v[2:3], v[6:7], v[4:5] op_sel_hi:[1,1,0]
	v_pk_mul_f32 v[2:3], v[0:1], v[56:57] op_sel_hi:[0,1]
	v_pk_mul_f32 v[2:3], v[152:153], v[2:3]
	v_mov_b32_e32 v6, v111
	v_mov_b32_e32 v7, v110
	v_mul_f32_e32 v4, v3, v110
	v_pk_fma_f32 v[56:57], v[2:3], v[6:7], v[4:5] op_sel_hi:[1,1,0] neg_lo:[0,0,1] neg_hi:[0,0,1]
	v_mul_f32_e32 v4, v3, v111
	v_pk_fma_f32 v[58:59], v[2:3], v[110:111], v[4:5] op_sel_hi:[1,1,0]
	v_pk_mul_f32 v[2:3], v[0:1], v[154:155] op_sel_hi:[0,1]
	v_mov_b32_e32 v8, v5
	v_pk_mul_f32 v[2:3], v[8:9], v[2:3]
	v_cvt_pk_bf16_f32 v152, v36, v32
	v_cvt_pk_bf16_f32 v153, v42, v34
	v_cvt_pk_bf16_f32 v154, v48, v52
	v_add_u32_e32 v96, 17, v78
	v_mul_f32_e32 v4, v3, v99
	v_pk_fma_f32 v[64:65], v[2:3], v[98:99], v[4:5] op_sel_hi:[1,1,0] neg_lo:[0,0,1] neg_hi:[0,0,1]
	v_mov_b32_e32 v4, v99
	v_mov_b32_e32 v5, v98
	v_mul_f32_e32 v6, v3, v98
	v_pk_fma_f32 v[82:83], v[2:3], v[4:5], v[6:7] op_sel_hi:[1,1,0]
	v_cvt_pk_bf16_f32 v155, v56, v64
	v_cvt_pk_bf16_f32 v148, v38, v40
	v_cvt_pk_bf16_f32 v149, v44, v46
	v_cvt_pk_bf16_f32 v150, v50, v54
	v_cvt_f32_i32_e32 v96, v96
	v_cvt_pk_bf16_f32 v151, v58, v82
	global_load_dwordx4 v[2:5], v[14:15], off offset:80
	global_load_dwordx4 v[6:9], v[14:15], off offset:64
	global_load_dwordx4 v[10:13], v[14:15], off offset:192
	global_load_dwordx4 v[128:131], v[14:15], off offset:208
	v_mul_f32_e32 v176, 0.15915494, v79
	v_mul_f32_e32 v96, 0xbed49a78, v96
	v_exp_f32_e32 v98, v96
	v_mul_f32_e32 v79, v176, v145
	v_floor_f32_e32 v79, v79
	v_fma_f32 v79, v176, v145, -v79
	v_mul_f32_e32 v177, 0.15915494, v98
	v_add_u32_e32 v98, 18, v78
	v_cvt_f32_i32_e32 v98, v98
	v_sin_f32_e32 v96, v79
	v_cos_f32_e32 v97, v79
	v_mul_f32_e32 v79, v177, v145
	v_floor_f32_e32 v79, v79
	v_fma_f32 v79, v177, v145, -v79
	v_mul_f32_e32 v98, 0xbed49a78, v98
	v_sin_f32_e32 v99, v79
	v_exp_f32_e32 v100, v98
	v_cos_f32_e32 v98, v79
	v_add_u32_e32 v79, 19, v78
	v_cvt_f32_i32_e32 v79, v79
	v_add_u32_e32 v104, 20, v78
	v_cvt_f32_i32_e32 v104, v104
	v_mul_f32_e32 v178, 0.15915494, v100
	v_mul_f32_e32 v79, 0xbed49a78, v79
	v_exp_f32_e32 v79, v79
	v_mul_f32_e32 v104, 0xbed49a78, v104
	v_exp_f32_e32 v104, v104
	v_mul_f32_e32 v100, v178, v145
	v_mul_f32_e32 v179, 0.15915494, v79
	v_mul_f32_e32 v79, v179, v145
	v_floor_f32_e32 v79, v79
	v_fma_f32 v79, v179, v145, -v79
	v_mul_f32_e32 v180, 0.15915494, v104
	v_sin_f32_e32 v107, v79
	v_cos_f32_e32 v106, v79
	v_add_u32_e32 v79, 21, v78
	v_mul_f32_e32 v104, v180, v145
	v_cvt_f32_i32_e32 v79, v79
	v_floor_f32_e32 v104, v104
	v_fma_f32 v104, v180, v145, -v104
	v_sin_f32_e32 v110, v104
	v_cos_f32_e32 v111, v104
	v_add_u32_e32 v104, 22, v78
	v_add_u32_e32 v78, 23, v78
	v_cvt_f32_i32_e32 v104, v104
	v_cvt_f32_i32_e32 v78, v78
	v_mul_f32_e32 v79, 0xbed49a78, v79
	v_exp_f32_e32 v79, v79
	v_mul_f32_e32 v104, 0xbed49a78, v104
	v_mul_f32_e32 v78, 0xbed49a78, v78
	v_exp_f32_e32 v104, v104
	v_exp_f32_e32 v78, v78
	v_mul_f32_e32 v181, 0.15915494, v79
	v_mul_f32_e32 v79, v181, v145
	v_floor_f32_e32 v79, v79
	v_fma_f32 v79, v181, v145, -v79
	v_mul_f32_e32 v182, 0.15915494, v104
	v_mul_f32_e32 v183, 0.15915494, v78
	v_sin_f32_e32 v133, v79
	v_cos_f32_e32 v132, v79
	v_mul_f32_e32 v79, v182, v145
	v_mul_f32_e32 v78, v183, v145
	v_floor_f32_e32 v79, v79
	v_floor_f32_e32 v78, v78
	v_fma_f32 v79, v182, v145, -v79
	v_fma_f32 v78, v183, v145, -v78
	v_sin_f32_e32 v134, v79
	v_cos_f32_e32 v135, v79
	v_sin_f32_e32 v147, v78
	v_cos_f32_e32 v146, v78
	v_pk_mul_f32 v[78:79], v[0:1], v[124:125] op_sel_hi:[0,1]
	v_floor_f32_e32 v100, v100
	v_fma_f32 v101, v178, v145, -v100
	v_sin_f32_e32 v100, v101
	v_cos_f32_e32 v101, v101
	v_pk_mul_f32 v[102:103], v[0:1], v[102:103] op_sel_hi:[0,1]
	v_pk_mul_f32 v[94:95], v[0:1], v[94:95] op_sel_hi:[0,1]
	s_waitcnt vmcnt(2)
; __device__ __forceinline__ unsigned cvtpk(float lo, float hi) { unsigned r; asm volatile("v_cvt_pk_bf16_f32 %0, %1, %2" : "=v"(r) : "v"(lo), "v"(hi)); return r; }
; __device__ __forceinline__ float bflo(unsigned w) { return __uint_as_float(w << 16); }
; __device__ __forceinline__ float bfhi(unsigned w) { return __uint_as_float(w & 0xffff0000u); }
; __device__ __forceinline__ float sin_rev(float rev) { return __builtin_amdgcn_sinf(rev); }
; __device__ __forceinline__ float cos_rev(float rev) { return __builtin_amdgcn_cosf(rev); }
; __device__ __forceinline__ void attn_item(const bf16_t* __restrict__ Qb, const bf16_t* __restrict__ Kh, const bf16_t* __restrict__ Vh, const bf16_t* __restrict__ Zb, ...
;     ...
;     for (int bb = 0; bb < 4; ++bb) { const int d1 = (bb & 1) + 4 * (bb >> 1), d2 = d1 + 2;
;       const float pos = (bb < 2) ? prow : pcol; const float* g1p = qg + d1 * 16 + hq * 8; const float* g2p = qg + d2 * 16 + hq * 8;
;       const f32x4 g1a = *(const f32x4*)g1p, g1b = *(const f32x4*)(g1p + 4), g2a = *(const f32x4*)g2p, g2b = *(const f32x4*)(g2p + 4);
;       float o1[8], o2[8];
; #pragma unroll
;       for (int e = 0; e < 8; ++e) { const unsigned w1 = (e < 2) ? qw[d1].x : (e < 4) ? qw[d1].y : (e < 6) ? qw[d1].z : qw[d1].w, w2 = (e < 2) ? qw[d2].x : (e < 4) ? qw[d2].y : (e < 6) ? qw[d2].z : qw[d2].w;
;         const float x1 = (e & 1) ? bfhi(w1) : bflo(w1), x2 = (e & 1) ? bfhi(w2) : bflo(w2); const float ga = (e < 4) ? g1a[e & 3] : g1b[e & 3], gb = (e < 4) ? g2a[e & 3] : g2b[e & 3];
;         const int fi = (d1 & 1) * 16 + hq * 8 + e; float rev = pos * (__builtin_amdgcn_exp2f(-(float)fi * (13.287712379549449f / 32.0f)) * 0.15915494309189535f); rev -= floorf(rev);
;         const float sn = sin_rev(rev), cs = cos_rev(rev), y1 = x1 * rstd * ga, y2 = x2 * rstd * gb; o1[e] = y1 * cs - y2 * sn; o2[e] = y2 * cs + y1 * sn; }
; #pragma unroll
;       for (int e = 0; e < 8; ++e) qn2 += o1[e] * o1[e] + o2[e] * o2[e];
;       u32x4 p1 = {cvtpk(o1[0], o1[1]), cvtpk(o1[2], o1[3]), cvtpk(o1[4], o1[5]), cvtpk(o1[6], o1[7])}, p2 = {cvtpk(o2[0], o2[1]), cvtpk(o2[2], o2[3]), cvtpk(o2[4], o2[5]), cvtpk(o2[6], o2[7])};
;       qr[d1] = *reinterpret_cast<bf16x8*>(&p1); qr[d2] = *reinterpret_cast<bf16x8*>(&p2); }
	v_mov_b32_e32 v104, v6
	s_waitcnt vmcnt(1)
	v_mov_b32_e32 v105, v10
	v_pk_mul_f32 v[104:105], v[78:79], v[104:105]
	v_mov_b32_e32 v78, v97
	v_mov_b32_e32 v79, v96
	v_mul_f32_e32 v6, v96, v105
	v_pk_fma_f32 v[78:79], v[78:79], v[104:105], v[6:7] op_sel_hi:[1,1,0] neg_lo:[0,0,1] neg_hi:[0,0,1]
	v_mul_f32_e32 v6, v97, v105
	v_pk_fma_f32 v[96:97], v[96:97], v[104:105], v[6:7] op_sel_hi:[1,1,0]
	v_pk_mul_f32 v[104:105], v[0:1], v[116:117] op_sel_hi:[0,1]
	v_mov_b32_e32 v10, v7
	v_pk_mul_f32 v[6:7], v[104:105], v[10:11]
	v_pk_mul_f32 v[76:77], v[0:1], v[76:77] op_sel_hi:[0,1]
	v_mul_f32_e32 v10, v99, v7
	v_pk_fma_f32 v[104:105], v[98:99], v[6:7], v[10:11] op_sel_hi:[1,1,0] neg_lo:[0,0,1] neg_hi:[0,0,1]
	v_mov_b32_e32 v10, v99
	v_mov_b32_e32 v11, v98
	v_mul_f32_e32 v98, v98, v7
	v_pk_fma_f32 v[108:109], v[10:11], v[6:7], v[98:99] op_sel_hi:[1,1,0]
	v_pk_mul_f32 v[6:7], v[0:1], v[112:113] op_sel_hi:[0,1]
	v_mov_b32_e32 v10, v8
	v_mov_b32_e32 v11, v12
	v_pk_mul_f32 v[6:7], v[6:7], v[10:11]
	v_mov_b32_e32 v10, v101
	v_mov_b32_e32 v11, v100
	v_mul_f32_e32 v8, v100, v7
	v_pk_fma_f32 v[112:113], v[10:11], v[6:7], v[8:9] op_sel_hi:[1,1,0] neg_lo:[0,0,1] neg_hi:[0,0,1]
	v_mul_f32_e32 v8, v101, v7
	v_pk_fma_f32 v[116:117], v[100:101], v[6:7], v[8:9] op_sel_hi:[1,1,0]
	v_pk_mul_f32 v[6:7], v[0:1], v[122:123] op_sel_hi:[0,1]
	v_mov_b32_e32 v12, v9
	v_pk_mul_f32 v[6:7], v[6:7], v[12:13]
	v_cvt_pk_bf16_f32 v160, v78, v104
	s_mulk_i32 s0, 0x2080
	v_mul_f32_e32 v8, v107, v7
	v_pk_fma_f32 v[122:123], v[106:107], v[6:7], v[8:9] op_sel_hi:[1,1,0] neg_lo:[0,0,1] neg_hi:[0,0,1]
	v_mov_b32_e32 v8, v107
	v_mov_b32_e32 v9, v106
	v_mul_f32_e32 v10, v106, v7
	v_pk_fma_f32 v[124:125], v[8:9], v[6:7], v[10:11] op_sel_hi:[1,1,0]
	v_pk_mul_f32 v[6:7], v[0:1], v[126:127] op_sel_hi:[0,1]
	v_mov_b32_e32 v8, v2
	s_waitcnt vmcnt(0)
	v_mov_b32_e32 v9, v128
	v_pk_mul_f32 v[6:7], v[6:7], v[8:9]
	v_mov_b32_e32 v8, v111
	v_mov_b32_e32 v9, v110
	v_mul_f32_e32 v2, v110, v7
	v_pk_fma_f32 v[98:99], v[8:9], v[6:7], v[2:3] op_sel_hi:[1,1,0] neg_lo:[0,0,1] neg_hi:[0,0,1]
	v_mul_f32_e32 v2, v111, v7
	v_pk_fma_f32 v[100:101], v[110:111], v[6:7], v[2:3] op_sel_hi:[1,1,0]
	v_pk_mul_f32 v[6:7], v[0:1], v[120:121] op_sel_hi:[0,1]
	v_mov_b32_e32 v128, v3
	v_pk_mul_f32 v[2:3], v[6:7], v[128:129]
	v_cvt_pk_bf16_f32 v161, v112, v122
	v_and_b32_e32 v128, 63, v136
	v_mul_f32_e32 v6, v133, v3
	v_pk_fma_f32 v[106:107], v[132:133], v[2:3], v[6:7] op_sel_hi:[1,1,0] neg_lo:[0,0,1] neg_hi:[0,0,1]
	v_mov_b32_e32 v6, v133
	v_mov_b32_e32 v7, v132
	v_mul_f32_e32 v8, v132, v3
	v_pk_fma_f32 v[110:111], v[6:7], v[2:3], v[8:9] op_sel_hi:[1,1,0]
	v_pk_mul_f32 v[2:3], v[0:1], v[114:115] op_sel_hi:[0,1]
	v_mov_b32_e32 v6, v4
	v_mov_b32_e32 v7, v130
	v_pk_mul_f32 v[2:3], v[2:3], v[6:7]
	v_mov_b32_e32 v6, v135
	v_mov_b32_e32 v7, v134
	v_mul_f32_e32 v4, v134, v3
	v_pk_fma_f32 v[114:115], v[6:7], v[2:3], v[4:5] op_sel_hi:[1,1,0] neg_lo:[0,0,1] neg_hi:[0,0,1]
	v_mul_f32_e32 v4, v135, v3
	v_pk_fma_f32 v[120:121], v[134:135], v[2:3], v[4:5] op_sel_hi:[1,1,0]
	v_pk_mul_f32 v[2:3], v[0:1], v[118:119] op_sel_hi:[0,1]
	v_mov_b32_e32 v130, v5
	v_pk_mul_f32 v[2:3], v[2:3], v[130:131]
	v_cvt_pk_bf16_f32 v162, v98, v106
	v_cvt_f32_ubyte0_e32 v189, v128
	v_mul_f32_e32 v4, v147, v3
	v_pk_fma_f32 v[118:119], v[146:147], v[2:3], v[4:5] op_sel_hi:[1,1,0] neg_lo:[0,0,1] neg_hi:[0,0,1]
	v_mov_b32_e32 v4, v147
	v_mov_b32_e32 v5, v146
	v_mul_f32_e32 v6, v146, v3
	v_pk_fma_f32 v[126:127], v[4:5], v[2:3], v[6:7] op_sel_hi:[1,1,0]
	v_cvt_pk_bf16_f32 v163, v114, v118
	v_cvt_pk_bf16_f32 v156, v96, v108
	v_cvt_pk_bf16_f32 v157, v116, v124
	v_cvt_pk_bf16_f32 v158, v100, v110
	v_mul_f32_e32 v130, v138, v189
	v_cvt_pk_bf16_f32 v159, v120, v126
	global_load_dwordx4 v[2:5], v[14:15], off offset:256
	global_load_dwordx4 v[6:9], v[14:15], off offset:384
	global_load_dwordx4 v[10:13], v[14:15], off offset:272
	global_load_dwordx4 v[164:167], v[14:15], off offset:400
	v_mul_f32_e32 v128, v137, v189
	v_floor_f32_e32 v130, v130
	v_floor_f32_e32 v128, v128
	v_fma_f32 v130, v138, v189, -v130
	v_mul_f32_e32 v138, v142, v189
	v_fma_f32 v129, v137, v189, -v128
	v_floor_f32_e32 v138, v138
	v_sin_f32_e32 v128, v129
	v_cos_f32_e32 v129, v129
	v_fma_f32 v138, v142, v189, -v138
	v_mul_f32_e32 v142, v144, v189
	v_floor_f32_e32 v142, v142
	v_fma_f32 v142, v144, v189, -v142
	v_sin_f32_e32 v131, v130
	v_cos_f32_e32 v130, v130
	v_mul_f32_e32 v132, v139, v189
	v_floor_f32_e32 v132, v132
	v_fma_f32 v133, v139, v189, -v132
	v_sin_f32_e32 v132, v133
	v_cos_f32_e32 v133, v133
	v_mul_f32_e32 v134, v140, v189
	v_floor_f32_e32 v134, v134
	v_fma_f32 v134, v140, v189, -v134
	v_sin_f32_e32 v135, v134
	v_cos_f32_e32 v134, v134
	v_mul_f32_e32 v136, v141, v189
	v_floor_f32_e32 v136, v136
	v_fma_f32 v137, v141, v189, -v136
	v_sin_f32_e32 v136, v137
	v_cos_f32_e32 v137, v137
	v_sin_f32_e32 v139, v138
	v_cos_f32_e32 v138, v138
	v_mul_f32_e32 v140, v143, v189
	v_floor_f32_e32 v140, v140
	v_fma_f32 v141, v143, v189, -v140
	v_sin_f32_e32 v140, v141
	v_cos_f32_e32 v141, v141
	v_sin_f32_e32 v143, v142
	v_cos_f32_e32 v142, v142
	s_add_u32 s0, s42, s0
	s_addc_u32 s1, s43, 0
	v_lshlrev_b32_e32 v206, 3, v186
	s_add_u32 s0, s0, s8
	s_addc_u32 s1, s1, 0
	v_pk_mul_f32 v[38:39], v[38:39], v[38:39]
	v_lshlrev_b32_e32 v221, 8, v187
	v_pk_fma_f32 v[36:37], v[36:37], v[36:37], v[38:39]
	v_pk_mul_f32 v[38:39], v[40:41], v[40:41]
	v_and_b32_e32 v208, 63, v186
	v_pk_fma_f32 v[32:33], v[32:33], v[32:33], v[38:39]
	v_and_b32_e32 v39, 24, v206
	v_pk_add_f32 v[32:33], v[36:37], v[32:33]
	v_pk_mul_f32 v[36:37], v[44:45], v[44:45]
	s_cmp_lg_u32 0, -1
	v_pk_fma_f32 v[36:37], v[42:43], v[42:43], v[36:37]
	s_mul_i32 s9, s6, 0x8200000
	v_pk_add_f32 v[32:33], v[36:37], v[32:33]
	v_pk_mul_f32 v[36:37], v[46:47], v[46:47]
	s_cselect_b32 s6, 0, 0
	v_pk_fma_f32 v[34:35], v[34:35], v[34:35], v[36:37]
	v_lshrrev_b32_e32 v36, 5, v186
	v_pk_add_f32 v[32:33], v[34:35], v[32:33]
	v_pk_mul_f32 v[34:35], v[50:51], v[50:51]
	v_bfe_u32 v37, v206, 5, 2
	v_pk_fma_f32 v[34:35], v[48:49], v[48:49], v[34:35]
	v_and_or_b32 v36, v36, s58, v37
	v_pk_add_f32 v[32:33], v[34:35], v[32:33]
	v_pk_mul_f32 v[34:35], v[54:55], v[54:55]
	v_mov_b32_e32 v244, 1.0
	v_pk_fma_f32 v[34:35], v[52:53], v[52:53], v[34:35]
	s_mov_b32 s76, 0x10000
	v_pk_add_f32 v[32:33], v[34:35], v[32:33]
	v_pk_mul_f32 v[34:35], v[58:59], v[58:59]
	v_pk_mul_f32 v[58:59], v[120:121], v[120:121]
	v_pk_fma_f32 v[34:35], v[56:57], v[56:57], v[34:35]
	s_mov_b32 s77, 0x8000
	s_waitcnt vmcnt(3)
; __device__ __forceinline__ unsigned cvtpk(float lo, float hi) { unsigned r; asm volatile("v_cvt_pk_bf16_f32 %0, %1, %2" : "=v"(r) : "v"(lo), "v"(hi)); return r; }
; __device__ __forceinline__ float bflo(unsigned w) { return __uint_as_float(w << 16); }
; __device__ __forceinline__ float bfhi(unsigned w) { return __uint_as_float(w & 0xffff0000u); }
; __device__ __forceinline__ float sin_rev(float rev) { return __builtin_amdgcn_sinf(rev); }
; __device__ __forceinline__ void attn_item(const bf16_t* __restrict__ Qb, const bf16_t* __restrict__ Kh, const bf16_t* __restrict__ Vh, const bf16_t* __restrict__ Zb, ...
;     ...
;     for (int bb = 0; bb < 4; ++bb) { const int d1 = (bb & 1) + 4 * (bb >> 1), d2 = d1 + 2;
;       const float pos = (bb < 2) ? prow : pcol; const float* g1p = qg + d1 * 16 + hq * 8; const float* g2p = qg + d2 * 16 + hq * 8;
;       const f32x4 g1a = *(const f32x4*)g1p, g1b = *(const f32x4*)(g1p + 4), g2a = *(const f32x4*)g2p, g2b = *(const f32x4*)(g2p + 4);
;       float o1[8], o2[8];
; #pragma unroll
;       for (int e = 0; e < 8; ++e) { const unsigned w1 = (e < 2) ? qw[d1].x : (e < 4) ? qw[d1].y : (e < 6) ? qw[d1].z : qw[d1].w, w2 = (e < 2) ? qw[d2].x : (e < 4) ? qw[d2].y : (e < 6) ? qw[d2].z : qw[d2].w;
;         const float x1 = (e & 1) ? bfhi(w1) : bflo(w1), x2 = (e & 1) ? bfhi(w2) : bflo(w2); const float ga = (e < 4) ? g1a[e & 3] : g1b[e & 3], gb = (e < 4) ? g2a[e & 3] : g2b[e & 3];
;         const int fi = (d1 & 1) * 16 + hq * 8 + e; float rev = pos * (__builtin_amdgcn_exp2f(-(float)fi * (13.287712379549449f / 32.0f)) * 0.15915494309189535f); rev -= floorf(rev);
;         const float sn = sin_rev(rev), cs = cos_rev(rev), y1 = x1 * rstd * ga, y2 = x2 * rstd * gb; o1[e] = y1 * cs - y2 * sn; o2[e] = y2 * cs + y1 * sn; }
; #pragma unroll
;       for (int e = 0; e < 8; ++e) qn2 += o1[e] * o1[e] + o2[e] * o2[e];
;       u32x4 p1 = {cvtpk(o1[0], o1[1]), cvtpk(o1[2], o1[3]), cvtpk(o1[4], o1[5]), cvtpk(o1[6], o1[7])}, p2 = {cvtpk(o2[0], o2[1]), cvtpk(o2[2], o2[3]), cvtpk(o2[4], o2[5]), cvtpk(o2[6], o2[7])};
;       qr[d1] = *reinterpret_cast<bf16x8*>(&p1); qr[d2] = *reinterpret_cast<bf16x8*>(&p2); }
;   }
;   const int sr = tid >> 4, sc = (tid & 15) * 8, vst0 = v_st_nat(sr, sc), vst1 = v_st_nat(32 + sr, sc), kst0 = KOFF + KSWZ(sr, sc * 2), kst1 = KOFF + KSWZ(32 + sr, sc * 2);
	v_mov_b32_e32 v144, v2
	s_waitcnt vmcnt(2)
	v_mov_b32_e32 v145, v6
	v_pk_mul_f32 v[144:145], v[102:103], v[144:145]
	v_mov_b32_e32 v102, v129
	v_mov_b32_e32 v103, v128
	v_mul_f32_e32 v2, v128, v145
	v_pk_fma_f32 v[102:103], v[102:103], v[144:145], v[2:3] op_sel_hi:[1,1,0] neg_lo:[0,0,1] neg_hi:[0,0,1]
	v_mul_f32_e32 v2, v129, v145
	v_mov_b32_e32 v6, v3
	v_pk_fma_f32 v[128:129], v[128:129], v[144:145], v[2:3] op_sel_hi:[1,1,0]
	v_pk_mul_f32 v[2:3], v[94:95], v[6:7]
	v_mul_f32_e32 v144, v177, v189
	v_mul_f32_e32 v6, v131, v3
	v_pk_fma_f32 v[94:95], v[130:131], v[2:3], v[6:7] op_sel_hi:[1,1,0] neg_lo:[0,0,1] neg_hi:[0,0,1]
	v_mov_b32_e32 v6, v131
	v_mov_b32_e32 v7, v130
	v_mul_f32_e32 v130, v130, v3
	v_pk_fma_f32 v[130:131], v[6:7], v[2:3], v[130:131] op_sel_hi:[1,1,0]
	v_pk_mul_f32 v[2:3], v[0:1], v[92:93] op_sel_hi:[0,1]
	v_mov_b32_e32 v6, v4
	v_mov_b32_e32 v7, v8
	v_pk_mul_f32 v[2:3], v[2:3], v[6:7]
	v_mov_b32_e32 v6, v133
	v_mov_b32_e32 v7, v132
	v_mul_f32_e32 v4, v132, v3
	v_pk_fma_f32 v[92:93], v[6:7], v[2:3], v[4:5] op_sel_hi:[1,1,0] neg_lo:[0,0,1] neg_hi:[0,0,1]
	v_mul_f32_e32 v4, v133, v3
	v_pk_fma_f32 v[132:133], v[132:133], v[2:3], v[4:5] op_sel_hi:[1,1,0]
	v_pk_mul_f32 v[2:3], v[0:1], v[90:91] op_sel_hi:[0,1]
	v_mov_b32_e32 v8, v5
	v_pk_mul_f32 v[2:3], v[2:3], v[8:9]
	v_cvt_pk_bf16_f32 v168, v102, v94
	v_floor_f32_e32 v144, v144
	v_mul_f32_e32 v4, v135, v3
	v_pk_fma_f32 v[90:91], v[134:135], v[2:3], v[4:5] op_sel_hi:[1,1,0] neg_lo:[0,0,1] neg_hi:[0,0,1]
	v_mov_b32_e32 v4, v135
	v_mov_b32_e32 v5, v134
	v_mul_f32_e32 v6, v134, v3
	v_pk_fma_f32 v[134:135], v[4:5], v[2:3], v[6:7] op_sel_hi:[1,1,0]
	v_pk_mul_f32 v[2:3], v[0:1], v[88:89] op_sel_hi:[0,1]
	s_waitcnt vmcnt(1)
	v_mov_b32_e32 v4, v10
	s_waitcnt vmcnt(0)
	v_mov_b32_e32 v5, v164
	v_pk_mul_f32 v[2:3], v[2:3], v[4:5]
	v_mov_b32_e32 v4, v137
	v_mov_b32_e32 v5, v136
	v_mul_f32_e32 v6, v136, v3
	v_pk_fma_f32 v[88:89], v[4:5], v[2:3], v[6:7] op_sel_hi:[1,1,0] neg_lo:[0,0,1] neg_hi:[0,0,1]
	v_mul_f32_e32 v4, v137, v3
	v_pk_fma_f32 v[136:137], v[136:137], v[2:3], v[4:5] op_sel_hi:[1,1,0]
	v_pk_mul_f32 v[2:3], v[0:1], v[86:87] op_sel_hi:[0,1]
	v_mov_b32_e32 v164, v11
	v_pk_mul_f32 v[2:3], v[2:3], v[164:165]
	v_cvt_pk_bf16_f32 v169, v92, v90
	v_fma_f32 v144, v177, v189, -v144
	v_mul_f32_e32 v4, v139, v3
	v_pk_fma_f32 v[86:87], v[138:139], v[2:3], v[4:5] op_sel_hi:[1,1,0] neg_lo:[0,0,1] neg_hi:[0,0,1]
	v_mov_b32_e32 v4, v139
	v_mov_b32_e32 v5, v138
	v_mul_f32_e32 v6, v138, v3
	v_pk_fma_f32 v[138:139], v[4:5], v[2:3], v[6:7] op_sel_hi:[1,1,0]
	v_pk_mul_f32 v[2:3], v[0:1], v[84:85] op_sel_hi:[0,1]
	v_mov_b32_e32 v4, v12
	v_mov_b32_e32 v5, v166
	v_pk_mul_f32 v[2:3], v[2:3], v[4:5]
	v_mov_b32_e32 v4, v141
	v_mov_b32_e32 v5, v140
	v_mul_f32_e32 v6, v140, v3
	v_pk_fma_f32 v[84:85], v[4:5], v[2:3], v[6:7] op_sel_hi:[1,1,0] neg_lo:[0,0,1] neg_hi:[0,0,1]
	v_mul_f32_e32 v4, v141, v3
	v_pk_fma_f32 v[140:141], v[140:141], v[2:3], v[4:5] op_sel_hi:[1,1,0]
	v_pk_mul_f32 v[2:3], v[0:1], v[80:81] op_sel_hi:[0,1]
	v_mov_b32_e32 v166, v13
	v_pk_mul_f32 v[2:3], v[2:3], v[166:167]
	v_cvt_pk_bf16_f32 v170, v88, v86
	v_sin_f32_e32 v147, v144
	v_mul_f32_e32 v4, v143, v3
	v_pk_fma_f32 v[80:81], v[142:143], v[2:3], v[4:5] op_sel_hi:[1,1,0] neg_lo:[0,0,1] neg_hi:[0,0,1]
	v_mov_b32_e32 v4, v143
	v_mov_b32_e32 v5, v142
	v_mul_f32_e32 v6, v142, v3
	v_pk_fma_f32 v[142:143], v[4:5], v[2:3], v[6:7] op_sel_hi:[1,1,0]
	v_cvt_pk_bf16_f32 v171, v84, v80
	v_cvt_pk_bf16_f32 v164, v128, v130
	v_cvt_pk_bf16_f32 v165, v132, v134
	v_cvt_pk_bf16_f32 v166, v136, v138
	v_cos_f32_e32 v146, v144
	v_cvt_pk_bf16_f32 v167, v140, v142
	global_load_dwordx4 v[2:5], v[14:15], off offset:320
	global_load_dwordx4 v[6:9], v[14:15], off offset:448
	global_load_dwordx4 v[10:13], v[14:15], off offset:336
	global_load_dwordx4 v[172:175], v[14:15], off offset:464
	v_mul_f32_e32 v144, v178, v189
	v_mul_f32_e32 v14, v176, v189
	v_floor_f32_e32 v144, v144
	v_floor_f32_e32 v14, v14
	v_fma_f32 v144, v178, v189, -v144
	v_fma_f32 v15, v176, v189, -v14
	v_sin_f32_e32 v176, v144
	v_cos_f32_e32 v177, v144
	v_mul_f32_e32 v144, v179, v189
	v_floor_f32_e32 v144, v144
	v_fma_f32 v144, v179, v189, -v144
	v_sin_f32_e32 v179, v144
	v_cos_f32_e32 v178, v144
	v_mul_f32_e32 v144, v180, v189
	v_floor_f32_e32 v144, v144
	v_fma_f32 v144, v180, v189, -v144
	v_sin_f32_e32 v184, v144
	v_cos_f32_e32 v185, v144
	v_mul_f32_e32 v144, v181, v189
	v_floor_f32_e32 v144, v144
	v_fma_f32 v144, v181, v189, -v144
	v_sin_f32_e32 v191, v144
	v_cos_f32_e32 v190, v144
	v_mul_f32_e32 v144, v182, v189
	v_floor_f32_e32 v144, v144
	v_fma_f32 v144, v182, v189, -v144
	v_sin_f32_e32 v192, v144
	v_cos_f32_e32 v193, v144
	v_mul_f32_e32 v144, v183, v189
	v_sin_f32_e32 v14, v15
	v_cos_f32_e32 v15, v15
	v_floor_f32_e32 v144, v144
	v_fma_f32 v144, v183, v189, -v144
	v_sin_f32_e32 v195, v144
	v_cos_f32_e32 v194, v144
	v_ashrrev_i32_e32 v189, 4, v186
	v_add_u32_e32 v207, 32, v189
	v_pk_add_f32 v[32:33], v[34:35], v[32:33]
	v_pk_mul_f32 v[34:35], v[82:83], v[82:83]
	v_lshlrev_b32_e32 v38, 5, v189
	v_pk_fma_f32 v[34:35], v[64:65], v[64:65], v[34:35]
	v_and_or_b32 v38, v38, s59, v39
	v_pk_add_f32 v[32:33], v[34:35], v[32:33]
	v_pk_mul_f32 v[34:35], v[96:97], v[96:97]
	v_lshlrev_b32_e32 v38, 1, v38
	v_pk_fma_f32 v[34:35], v[78:79], v[78:79], v[34:35]
	v_lshl_or_b32 v228, v36, 9, v38
	v_pk_add_f32 v[32:33], v[34:35], v[32:33]
	v_pk_mul_f32 v[34:35], v[108:109], v[108:109]
	v_lshrrev_b32_e32 v36, 1, v207
	v_pk_fma_f32 v[34:35], v[104:105], v[104:105], v[34:35]
	v_and_or_b32 v36, v36, s58, v37
	v_lshlrev_b32_e32 v82, 4, v186
	v_add_u32_e32 v108, 0, v228
	v_pk_add_f32 v[32:33], v[34:35], v[32:33]
	v_pk_mul_f32 v[34:35], v[116:117], v[116:117]
	v_lshl_or_b32 v229, v36, 9, v38
	v_lshlrev_b32_e32 v36, 8, v189
	v_and_b32_e32 v38, 0xf0, v186
	v_lshlrev_b32_e32 v39, 8, v207
	v_pk_fma_f32 v[34:35], v[112:113], v[112:113], v[34:35]
	v_add_u32_e32 v83, 0, v221
	v_pk_add_f32 v[32:33], v[34:35], v[32:33]
	v_pk_mul_f32 v[34:35], v[124:125], v[124:125]
	v_add_u32_e32 v109, 0, v229
	v_pk_fma_f32 v[34:35], v[122:123], v[122:123], v[34:35]
	v_pk_mul_f32 v[78:79], v[126:127], v[126:127]
	v_pk_add_f32 v[32:33], v[34:35], v[32:33]
	v_pk_mul_f32 v[34:35], v[100:101], v[100:101]
	s_mov_b32 s78, -1
	v_pk_fma_f32 v[34:35], v[98:99], v[98:99], v[34:35]
	v_mov_b32_e32 v219, 0
	v_pk_add_f32 v[32:33], v[34:35], v[32:33]
	v_pk_mul_f32 v[34:35], v[110:111], v[110:111]
	s_waitcnt vmcnt(3)
; __device__ __forceinline__ unsigned cvtpk(float lo, float hi) { unsigned r; asm volatile("v_cvt_pk_bf16_f32 %0, %1, %2" : "=v"(r) : "v"(lo), "v"(hi)); return r; }
; __device__ __forceinline__ void attn_item(const bf16_t* __restrict__ Qb, const bf16_t* __restrict__ Kh, const bf16_t* __restrict__ Vh, const bf16_t* __restrict__ Zb, ...
;     ...
;     for (int bb = 0; bb < 4; ++bb) { const int d1 = (bb & 1) + 4 * (bb >> 1), d2 = d1 + 2;
;       const float pos = (bb < 2) ? prow : pcol; const float* g1p = qg + d1 * 16 + hq * 8; const float* g2p = qg + d2 * 16 + hq * 8;
;       const f32x4 g1a = *(const f32x4*)g1p, g1b = *(const f32x4*)(g1p + 4), g2a = *(const f32x4*)g2p, g2b = *(const f32x4*)(g2p + 4);
;       float o1[8], o2[8];
; #pragma unroll
;       for (int e = 0; e < 8; ++e) { const unsigned w1 = (e < 2) ? qw[d1].x : (e < 4) ? qw[d1].y : (e < 6) ? qw[d1].z : qw[d1].w, w2 = (e < 2) ? qw[d2].x : (e < 4) ? qw[d2].y : (e < 6) ? qw[d2].z : qw[d2].w;
;         const float x1 = (e & 1) ? bfhi(w1) : bflo(w1), x2 = (e & 1) ? bfhi(w2) : bflo(w2); const float ga = (e < 4) ? g1a[e & 3] : g1b[e & 3], gb = (e < 4) ? g2a[e & 3] : g2b[e & 3];
;         const int fi = (d1 & 1) * 16 + hq * 8 + e; float rev = pos * (__builtin_amdgcn_exp2f(-(float)fi * (13.287712379549449f / 32.0f)) * 0.15915494309189535f); rev -= floorf(rev);
;         const float sn = sin_rev(rev), cs = cos_rev(rev), y1 = x1 * rstd * ga, y2 = x2 * rstd * gb; o1[e] = y1 * cs - y2 * sn; o2[e] = y2 * cs + y1 * sn; }
; #pragma unroll
;       for (int e = 0; e < 8; ++e) qn2 += o1[e] * o1[e] + o2[e] * o2[e];
;       u32x4 p1 = {cvtpk(o1[0], o1[1]), cvtpk(o1[2], o1[3]), cvtpk(o1[4], o1[5]), cvtpk(o1[6], o1[7])}, p2 = {cvtpk(o2[0], o2[1]), cvtpk(o2[2], o2[3]), cvtpk(o2[4], o2[5]), cvtpk(o2[6], o2[7])};
;       qr[d1] = *reinterpret_cast<bf16x8*>(&p1); qr[d2] = *reinterpret_cast<bf16x8*>(&p2); }
;   }
;   const int sr = tid >> 4, sc = (tid & 15) * 8, vst0 = v_st_nat(sr, sc), vst1 = v_st_nat(32 + sr, sc), kst0 = KOFF + KSWZ(sr, sc * 2), kst1 = KOFF + KSWZ(32 + sr, sc * 2);
;   const int vb0 = (int)(uintptr_t)lds + v_rd_base(lane);
;   struct { bf16x8 vs0, vs1, ks0, ks1; } sr_;
;     ...
;   f32x16 pA0, pA1, pB0, pB1; float alA, alB; VF8 vfa; bf16x8 pa0, pa1, pa2, pa3; const int NT = seq / KVBLK;
;   int s_prev = 0, s_cur = SLOT, s_next = 2 * SLOT;
;   SLOAD(0); SWAIT(); SWRITE(0); __syncthreads();
	v_mov_b32_e32 v144, v2
	s_waitcnt vmcnt(2)
	v_mov_b32_e32 v145, v6
	v_pk_mul_f32 v[144:145], v[76:77], v[144:145]
	v_mov_b32_e32 v76, v15
	v_mov_b32_e32 v77, v14
	v_mul_f32_e32 v2, v14, v145
	v_pk_fma_f32 v[76:77], v[76:77], v[144:145], v[2:3] op_sel_hi:[1,1,0] neg_lo:[0,0,1] neg_hi:[0,0,1]
	v_mul_f32_e32 v2, v15, v145
	v_pk_fma_f32 v[144:145], v[14:15], v[144:145], v[2:3] op_sel_hi:[1,1,0]
	v_pk_mul_f32 v[14:15], v[0:1], v[60:61] op_sel_hi:[0,1]
	v_mov_b32_e32 v6, v3
	v_pk_mul_f32 v[2:3], v[14:15], v[6:7]
	v_pk_fma_f32 v[34:35], v[106:107], v[106:107], v[34:35]
	v_mul_f32_e32 v6, v147, v3
	v_pk_fma_f32 v[60:61], v[146:147], v[2:3], v[6:7] op_sel_hi:[1,1,0] neg_lo:[0,0,1] neg_hi:[0,0,1]
	v_mov_b32_e32 v6, v147
	v_mov_b32_e32 v7, v146
	v_mul_f32_e32 v14, v146, v3
	v_pk_fma_f32 v[146:147], v[6:7], v[2:3], v[14:15] op_sel_hi:[1,1,0]
	v_pk_mul_f32 v[2:3], v[0:1], v[74:75] op_sel_hi:[0,1]
	v_mov_b32_e32 v6, v4
	v_mov_b32_e32 v7, v8
	v_pk_mul_f32 v[2:3], v[2:3], v[6:7]
	v_mov_b32_e32 v6, v177
	v_mov_b32_e32 v7, v176
	v_mul_f32_e32 v4, v176, v3
	v_pk_fma_f32 v[74:75], v[6:7], v[2:3], v[4:5] op_sel_hi:[1,1,0] neg_lo:[0,0,1] neg_hi:[0,0,1]
	v_mul_f32_e32 v4, v177, v3
	v_pk_fma_f32 v[180:181], v[176:177], v[2:3], v[4:5] op_sel_hi:[1,1,0]
	v_pk_mul_f32 v[2:3], v[0:1], v[66:67] op_sel_hi:[0,1]
	v_mov_b32_e32 v8, v5
	v_pk_mul_f32 v[2:3], v[2:3], v[8:9]
	s_waitcnt vmcnt(0)
	v_mov_b32_e32 v15, v174
	v_mul_f32_e32 v4, v179, v3
	v_pk_fma_f32 v[66:67], v[178:179], v[2:3], v[4:5] op_sel_hi:[1,1,0] neg_lo:[0,0,1] neg_hi:[0,0,1]
	v_mov_b32_e32 v4, v179
	v_mov_b32_e32 v5, v178
	v_mul_f32_e32 v6, v178, v3
	v_pk_fma_f32 v[182:183], v[4:5], v[2:3], v[6:7] op_sel_hi:[1,1,0]
	v_pk_mul_f32 v[2:3], v[0:1], v[72:73] op_sel_hi:[0,1]
	v_mov_b32_e32 v4, v10
	v_mov_b32_e32 v5, v172
	v_pk_mul_f32 v[6:7], v[0:1], v[62:63] op_sel_hi:[0,1]
	v_mov_b32_e32 v172, v11
	v_pk_mul_f32 v[2:3], v[2:3], v[4:5]
	v_mov_b32_e32 v4, v185
	v_mov_b32_e32 v5, v184
	v_pk_mul_f32 v[6:7], v[6:7], v[172:173]
	v_mov_b32_e32 v10, v191
	v_mov_b32_e32 v11, v190
	v_pk_mul_f32 v[62:63], v[0:1], v[70:71] op_sel_hi:[0,1]
	v_mov_b32_e32 v174, v13
	v_pk_mul_f32 v[4:5], v[4:5], v[2:3]
	v_pk_mul_f32 v[8:9], v[190:191], v[6:7]
	v_pk_mul_f32 v[6:7], v[10:11], v[6:7]
	v_pk_mul_f32 v[10:11], v[0:1], v[68:69] op_sel_hi:[0,1]
	v_mov_b32_e32 v14, v12
	v_pk_mul_f32 v[12:13], v[62:63], v[174:175]
	v_mov_b32_e32 v62, v195
	v_mov_b32_e32 v63, v194
	v_pk_mul_f32 v[2:3], v[184:185], v[2:3]
	v_pk_mul_f32 v[10:11], v[10:11], v[14:15]
	v_mov_b32_e32 v14, v193
	v_mov_b32_e32 v15, v192
	v_pk_mul_f32 v[68:69], v[194:195], v[12:13]
	v_pk_mul_f32 v[12:13], v[62:63], v[12:13]
	v_mov_b32_e32 v62, v8
	v_mov_b32_e32 v63, v4
	v_mov_b32_e32 v4, v9
	v_pk_mul_f32 v[14:15], v[14:15], v[10:11]
	v_pk_add_f32 v[62:63], v[62:63], v[4:5] neg_lo:[0,1] neg_hi:[0,1]
	v_mov_b32_e32 v4, v6
	v_mov_b32_e32 v5, v2
	v_mov_b32_e32 v2, v7
	v_pk_mul_f32 v[10:11], v[192:193], v[10:11]
	v_pk_add_f32 v[72:73], v[4:5], v[2:3]
	v_mov_b32_e32 v2, v68
	v_mov_b32_e32 v3, v14
	v_mov_b32_e32 v14, v69
	v_pk_add_f32 v[68:69], v[2:3], v[14:15] neg_lo:[0,1] neg_hi:[0,1]
	v_mov_b32_e32 v2, v12
	v_mov_b32_e32 v3, v10
	v_mov_b32_e32 v10, v13
	v_and_b32_e32 v70, 0x78, v206
	v_mov_b32_e32 v71, v1
	v_pk_add_f32 v[184:185], v[2:3], v[10:11]
	v_mad_i64_i32 v[2:3], s[36:37], v189, s61, v[70:71]
	v_lshl_add_u64 v[2:3], v[2:3], 1, s[0:1]
	v_cvt_pk_bf16_f32 v176, v76, v60
	v_cvt_pk_bf16_f32 v177, v74, v66
	v_cvt_pk_bf16_f32 v178, v63, v62
	v_cvt_pk_bf16_f32 v179, v69, v68
	v_cvt_pk_bf16_f32 v172, v144, v146
	v_cvt_pk_bf16_f32 v173, v180, v182
	v_cvt_pk_bf16_f32 v174, v73, v72
	v_cvt_pk_bf16_f32 v175, v185, v184
	global_load_dwordx4 v[190:193], v[2:3], off offset:2560
	v_mad_i64_i32 v[4:5], s[36:37], v207, s61, v[70:71]
	v_lshl_add_u64 v[4:5], v[4:5], 1, s[0:1]
	global_load_dwordx4 v[194:197], v[4:5], off offset:2560
	global_load_dwordx4 v[198:201], v[2:3], off offset:2048
	global_load_dwordx4 v[202:205], v[4:5], off offset:2048
	v_lshlrev_b32_e32 v37, 1, v70
	s_waitcnt vmcnt(0)
	v_bitop3_b32 v231, v37, v36, v38 bitop3:0xde
	v_bitop3_b32 v232, v39, v37, v38 bitop3:0xf6
	v_add_u32_e32 v112, 0, v231
	v_add_u32_e32 v113, 0, v232
	v_pk_add_f32 v[56:57], v[34:35], v[32:33]
	v_and_b32_e32 v0, 0x3fffffc0, v186
	v_mov_b32_e32 v14, v1
	v_mov_b32_e32 v15, v1
	v_lshl_add_u32 v213, v0, 2, s56
	v_mov_b32_e32 v0, v1
	v_mov_b32_e32 v2, v1
	v_mov_b32_e32 v3, v1
	v_mov_b32_e32 v4, v1
	v_mov_b32_e32 v5, v1
	v_mov_b32_e32 v6, v1
	v_mov_b32_e32 v7, v1
	v_mov_b32_e32 v8, v1
	v_mov_b32_e32 v9, v1
	v_mov_b32_e32 v10, v1
	v_mov_b32_e32 v11, v1
	v_mov_b32_e32 v12, v1
	v_mov_b32_e32 v13, v1
	v_or_b32_e32 v106, 0xc0, v212
	v_or_b32_e32 v107, 0xe0, v212
	v_lshl_add_u32 v220, v187, 2, v213
	s_waitcnt vmcnt(3)
	ds_write_b128 v108, v[190:193]
	v_and_b32_e32 v190, 0xf0, v82
	v_bitop3_b32 v234, v188, v190, 16 bitop3:0x6c
	v_add_u32_e32 v36, v83, v234
	s_waitcnt vmcnt(2)
	ds_write_b128 v109, v[194:197]
	s_waitcnt vmcnt(1)
	ds_write_b128 v112, v[198:201] offset:16384
	s_waitcnt vmcnt(0)
	ds_write_b128 v113, v[202:205] offset:16384
	s_waitcnt lgkmcnt(0)
	s_barrier
; #define SLOAD(k0) do { sr_.vs0 = *(const bf16x8*)(&Vh[(long)((k0) + sr) * LDK + sc]); sr_.vs1 = *(const bf16x8*)(&Vh[(long)((k0) + 32 + sr) * LDK + sc]); \
;     sr_.ks0 = *(const bf16x8*)(&Kh[(long)((k0) + sr) * LDK + sc]); sr_.ks1 = *(const bf16x8*)(&Kh[(long)((k0) + 32 + sr) * LDK + sc]); } while (0)
; __device__ __forceinline__ void qkt(f32x16& p0, f32x16& p1, const bf16_t* Ks, const bf16x8* qr, const f32x16& negm, int r32, int hi) {
; #pragma unroll
;   for (int d0 = 0; d0 < 8; ++d0) { int cb = (d0 * 16 + hi * 8) * 2;
;     bf16x8 b0 = *reinterpret_cast<const bf16x8*>((const char*)Ks + KSWZ(r32, cb));
;     bf16x8 b1 = *reinterpret_cast<const bf16x8*>((const char*)Ks + KSWZ(32 + r32, cb));
;     if (d0 == 0) { p0 = __builtin_amdgcn_mfma_f32_32x32x16_bf16(b0, qr[0], negm, 0, 0, 0); p1 = __builtin_amdgcn_mfma_f32_32x32x16_bf16(b1, qr[0], negm, 0, 0, 0); }
;     else { p0 = __builtin_amdgcn_mfma_f32_32x32x16_bf16(b0, qr[d0], p0, 0, 0, 0); p1 = __builtin_amdgcn_mfma_f32_32x32x16_bf16(b1, qr[d0], p1, 0, 0, 0); } }
; }
; __device__ __forceinline__ void attn_item(const bf16_t* __restrict__ Qb, const bf16_t* __restrict__ Kh, const bf16_t* __restrict__ Vh, const bf16_t* __restrict__ Zb, ...
;     ...
;   SLOAD(KVBLK);
;   qkt(pA0, pA1, (const bf16_t*)(lds + KOFF), qr, negm, r32, hi); partialSM<true>(pA0, pA1, m_reg, negm, alA);
	ds_read_b128 v[48:51], v36 offset:24576
	ds_read_b128 v[52:55], v36 offset:16384
	s_waitcnt lgkmcnt(0)
	v_mfma_f32_32x32x16_bf16 v[32:47], v[52:55], v[152:155], v[16:31]
	v_fma_f32 v52, v114, v114, v58
	v_fma_f32 v53, v115, v115, v59
	v_bitop3_b32 v233, v212, v190, 32 bitop3:0x36
	v_add_f32_e64 v64, v52, v56
	v_add_f32_e64 v65, v53, v57
	v_add_u32_e32 v56, v83, v233
	ds_read_b128 v[52:55], v56 offset:24576
	ds_read_b128 v[56:59], v56 offset:16384
	v_bitop3_b32 v230, v212, v190, 64 bitop3:0x36
	v_bitop3_b32 v227, v212, v190, s62 bitop3:0x36
	v_mfma_f32_32x32x16_bf16 v[16:31], v[48:51], v[152:155], v[16:31]
	v_fma_f32 v48, v118, v118, v78
	v_fma_f32 v49, v119, v119, v79
	v_mul_f32_e64 v50, v128, v128
	v_mul_f32_e64 v51, v129, v129
	v_add_f32_e64 v48, v48, v64
	v_add_f32_e64 v49, v49, v65
	v_pk_fma_f32 v[50:51], v[102:103], v[102:103], v[50:51]
	v_bitop3_b32 v226, v212, v190, s63 bitop3:0x36
	v_pk_add_f32 v[48:49], v[48:49], v[50:51]
	v_pk_mul_f32 v[50:51], v[130:131], v[130:131]
	s_waitcnt lgkmcnt(0)
	v_mfma_f32_32x32x16_bf16 v[32:47], v[56:59], v[160:163], v[32:47]
	v_fma_f32 v50, v94, v94, v50
	v_fma_f32 v51, v95, v95, v51
	v_add_u32_e32 v56, v83, v230
	v_add_f32_e64 v64, v50, v48
	v_add_f32_e64 v65, v51, v49
	v_pk_mul_f32 v[48:49], v[132:133], v[132:133]
	v_bitop3_b32 v225, v212, v190, s64 bitop3:0x36
	v_pk_fma_f32 v[78:79], v[92:93], v[92:93], v[48:49]
	ds_read_b128 v[48:51], v56 offset:24576
	ds_read_b128 v[56:59], v56 offset:16384
	v_mfma_f32_32x32x16_bf16 v[16:31], v[52:55], v[160:163], v[16:31]
	v_mul_f32_e64 v54, v134, v134
	v_mul_f32_e64 v55, v135, v135
	v_add_f32_e64 v52, v78, v64
	v_add_f32_e64 v53, v79, v65
	v_fma_f32 v54, v90, v90, v54
	v_fma_f32 v55, v91, v91, v55
	v_bitop3_b32 v224, v212, v190, s60 bitop3:0x36
	v_pk_add_f32 v[52:53], v[54:55], v[52:53]
	v_pk_mul_f32 v[54:55], v[136:137], v[136:137]
	v_bitop3_b32 v223, v212, v190, s59 bitop3:0x36
	v_pk_fma_f32 v[54:55], v[88:89], v[88:89], v[54:55]
	s_waitcnt lgkmcnt(0)
	v_mfma_f32_32x32x16_bf16 v[32:47], v[56:59], v[148:151], v[32:47]
	v_add_f32_e64 v52, v54, v52
	v_add_f32_e64 v53, v55, v53
	v_mul_f32_e64 v54, v138, v138
	v_mul_f32_e64 v55, v139, v139
	v_add_u32_e32 v56, v83, v227
	v_pk_fma_f32 v[54:55], v[86:87], v[86:87], v[54:55]
	v_bitop3_b32 v236, v212, v221, v190 bitop3:0xde
	v_pk_add_f32 v[64:65], v[54:55], v[52:53]
	ds_read_b128 v[52:55], v56 offset:24576
	ds_read_b128 v[56:59], v56 offset:16384
	v_mfma_f32_32x32x16_bf16 v[16:31], v[48:51], v[148:151], v[16:31]
	v_mul_f32_e64 v48, v140, v140
	v_mul_f32_e64 v49, v141, v141
	v_mul_f32_e64 v50, v142, v142
	v_mul_f32_e64 v51, v143, v143
	v_fma_f32 v48, v84, v84, v48
	v_fma_f32 v49, v85, v85, v49
	v_pk_fma_f32 v[50:51], v[80:81], v[80:81], v[50:51]
	v_pk_add_f32 v[48:49], v[48:49], v[64:65]
	v_bitop3_b32 v242, v106, v221, v190 bitop3:0xde
	v_pk_add_f32 v[48:49], v[50:51], v[48:49]
	s_waitcnt lgkmcnt(0)
	v_mfma_f32_32x32x16_bf16 v[32:47], v[56:59], v[156:159], v[32:47]
	v_mul_f32_e64 v50, v144, v144
	v_mul_f32_e64 v51, v145, v145
	v_add_u32_e32 v56, v83, v226
	v_fma_f32 v50, v76, v76, v50
	v_fma_f32 v51, v77, v77, v51
	v_pk_mul_f32 v[76:77], v[146:147], v[146:147]
	v_pk_add_f32 v[64:65], v[48:49], v[50:51]
	ds_read_b128 v[48:51], v56 offset:24576
	ds_read_b128 v[56:59], v56 offset:16384
	v_bitop3_b32 v243, v107, v221, v190 bitop3:0xde
	v_mfma_f32_32x32x16_bf16 v[16:31], v[52:55], v[156:159], v[16:31]
	v_fma_f32 v52, v60, v60, v76
	v_fma_f32 v53, v61, v61, v77
	v_mul_f32_e64 v54, v180, v180
	v_mul_f32_e64 v55, v181, v181
	v_add_f32_e64 v52, v52, v64
	v_add_f32_e64 v53, v53, v65
	v_pk_fma_f32 v[54:55], v[74:75], v[74:75], v[54:55]
	s_nop 0
	v_pk_add_f32 v[52:53], v[54:55], v[52:53]
	v_pk_mul_f32 v[54:55], v[182:183], v[182:183]
	s_waitcnt lgkmcnt(0)
	v_mfma_f32_32x32x16_bf16 v[32:47], v[56:59], v[168:171], v[32:47]
	v_fma_f32 v54, v66, v66, v54
	v_fma_f32 v55, v67, v67, v55
	v_add_u32_e32 v56, v83, v225
	v_add_f32_e64 v60, v54, v52
	v_add_f32_e64 v61, v55, v53
	v_pk_mul_f32 v[52:53], v[72:73], v[72:73]
	s_nop 0
	v_pk_fma_f32 v[62:63], v[62:63], v[62:63], v[52:53]
	ds_read_b128 v[52:55], v56 offset:24576
	ds_read_b128 v[56:59], v56 offset:16384
	v_mfma_f32_32x32x16_bf16 v[16:31], v[48:51], v[168:171], v[16:31]
	v_add_f32_e64 v48, v63, v60
	v_add_f32_e64 v49, v62, v61
	v_mul_f32_e64 v50, v184, v184
	v_mul_f32_e64 v51, v185, v185
	v_add_f32_e64 v48, v62, v48
	v_add_f32_e64 v49, v63, v49
	v_pk_fma_f32 v[50:51], v[68:69], v[68:69], v[50:51]
	v_lshlrev_b32_e32 v60, 3, v208
	v_pk_add_f32 v[48:49], v[50:51], v[48:49] op_sel:[1,0] op_sel_hi:[0,1]
	v_pk_add_f32 v[64:65], v[50:51], v[48:49]
	s_waitcnt lgkmcnt(0)
	v_mfma_f32_32x32x16_bf16 v[32:47], v[56:59], v[176:179], v[32:47]
	v_and_b32_e32 v48, 0xc0, v82
	v_add_u32_e32 v56, v83, v224
	v_and_or_b32 v61, v60, 24, v48
	v_lshlrev_b32_e32 v62, 1, v186
	ds_read_b128 v[48:51], v56 offset:24576
	ds_read_b128 v[56:59], v56 offset:16384
	v_or_b32_e32 v65, 0xa0, v212
	v_bitop3_b32 v241, v65, v221, v190 bitop3:0xde
	v_mfma_f32_32x32x16_bf16 v[16:31], v[52:55], v[176:179], v[16:31]
	v_and_b32_e32 v52, 32, v62
	v_and_b32_e32 v53, 0x100, v60
	v_or3_b32 v52, v61, v52, v53
	v_add_u32_e32 v235, s6, v52
	v_add_u32_e32 v52, 64, v189
	v_mad_i64_i32 v[52:53], s[6:7], v52, s61, v[70:71]
	v_add_u32_e32 v62, 0x60, v189
	s_waitcnt lgkmcnt(0)
	v_mfma_f32_32x32x16_bf16 v[32:47], v[56:59], v[164:167], v[32:47]
	v_lshl_add_u64 v[60:61], v[52:53], 1, s[0:1]
	v_add_u32_e32 v56, v83, v223
	ds_read_b128 v[52:55], v56 offset:24576
	ds_read_b128 v[56:59], v56 offset:16384
	v_mfma_f32_32x32x16_bf16 v[16:31], v[48:51], v[164:167], v[16:31]
	v_mad_i64_i32 v[48:49], s[6:7], v62, s61, v[70:71]
	v_lshl_add_u64 v[66:67], v[48:49], 1, s[0:1]
	global_load_dwordx4 v[48:51], v[60:61], off offset:2560
	s_nop 0
	global_load_dwordx4 v[60:63], v[60:61], off offset:2048
	s_nop 0
	global_load_dwordx4 v[98:101], v[66:67], off offset:2560
	global_load_dwordx4 v[102:105], v[66:67], off offset:2048
	v_cmp_gt_u32_e64 s[6:7], 32, v208
	s_waitcnt lgkmcnt(0)
; #define SWRITE(so) do { *(bf16x8*)(lds + (so) + vst0) = sr_.vs0; *(bf16x8*)(lds + (so) + vst1) = sr_.vs1;          \
;     *(bf16x8*)(lds + (so) + kst0) = sr_.ks0; *(bf16x8*)(lds + (so) + kst1) = sr_.ks1; } while (0)
; #define SWAIT() asm volatile("s_waitcnt vmcnt(0)" ::: "memory")
; template <bool FIRST, bool DOEXP = true>
; __device__ __forceinline__ void partialSM(f32x16& p0, f32x16& p1, float& m_reg, f32x16& negm, float& alpha, const bool track = true) {
;     ...
;   float pmax = p0[0];
; #pragma unroll
;   for (int r = 1; r < 16; ++r) pmax = fmaxf(pmax, p0[r]);
; #pragma unroll
;   for (int r = 0; r < 16; ++r) pmax = fmaxf(pmax, p1[r]);
;   { auto rr = __builtin_amdgcn_permlane32_swap(__float_as_uint(pmax), __float_as_uint(pmax), false, false);
;     pmax = fmaxf(__uint_as_float(rr[0]), __uint_as_float(rr[1])); }
;   if (!FIRST && __builtin_expect(__all(pmax <= THRL), 1)) { alpha = 1.f; }
;   else { const float dl = FIRST ? pmax : fmaxf(pmax, 0.f); m_reg += dl; alpha = FIRST ? 1.f : __builtin_amdgcn_exp2f(-dl);
; #pragma unroll
;     for (int r = 0; r < 16; ++r) { p0[r] -= dl; p1[r] -= dl; }
; #pragma unroll
;     for (int r = 0; r < 16; ++r) negm[r] = -m_reg;
;     asm volatile("" : "+v"(negm)); }
;   if (DOEXP) {
; #pragma unroll
;     for (int r = 0; r < 16; ++r) p0[r] = __builtin_amdgcn_exp2f(p0[r]); }
; __device__ __forceinline__ void attn_item(const bf16_t* __restrict__ Qb, const bf16_t* __restrict__ Kh, const bf16_t* __restrict__ Vh, const bf16_t* __restrict__ Zb, ...
;     ...
;   { auto rr = __builtin_amdgcn_permlane32_swap(__float_as_uint(qn2), __float_as_uint(qn2), false, false); qn2 = __uint_as_float(rr[0]) + __uint_as_float(rr[1]); }
;   const bool track = !__all(__builtin_sqrtf(qn2) * kmaxg - m_reg <= 90.f);
;   SWAIT(); SWRITE(SLOT); __syncthreads();
;   for (int j = 1; j + 1 < NT; j += 2) {
	v_mfma_f32_32x32x16_bf16 v[32:47], v[56:59], v[172:175], v[32:47]
	v_or_b32_e32 v56, 32, v212
	v_or_b32_e32 v57, 64, v212
	v_or_b32_e32 v58, 0x60, v212
	v_or_b32_e32 v59, 0x80, v212
	v_bitop3_b32 v237, v56, v221, v190 bitop3:0xde
	v_bitop3_b32 v238, v57, v221, v190 bitop3:0xde
	v_bitop3_b32 v239, v58, v221, v190 bitop3:0xde
	v_mfma_f32_32x32x16_bf16 v[16:31], v[52:55], v[172:175], v[16:31]
	s_nop 3
	v_max_f32_e32 v52, v33, v33
	v_max_f32_e32 v53, v32, v32
	v_max_f32_e32 v52, v53, v52
	v_max3_f32 v52, v52, v34, v35
	v_max3_f32 v52, v52, v36, v37
	v_max3_f32 v52, v52, v38, v39
	v_max3_f32 v52, v52, v40, v41
	v_max3_f32 v52, v52, v42, v43
	v_max3_f32 v52, v52, v44, v45
	v_max3_f32 v52, v52, v46, v47
	v_max3_f32 v52, v52, v16, v17
	v_max3_f32 v52, v52, v18, v19
	v_max3_f32 v52, v52, v20, v21
	v_max3_f32 v52, v52, v22, v23
	v_max3_f32 v52, v52, v24, v25
	v_max3_f32 v52, v52, v26, v27
	v_max3_f32 v52, v52, v28, v29
	v_max3_f32 v52, v52, v30, v31
	v_mov_b32_e32 v53, v52
	s_nop 1
	v_permlane32_swap_b32_e32 v52, v53
	v_max_f32_e32 v53, v53, v53
	v_max_f32_e32 v52, v52, v52
	v_max_f32_e32 v52, v52, v53
	v_sub_f32_e32 v82, v16, v52
	v_mov_b32_e32 v16, v64
	s_nop 1
	v_permlane32_swap_b32_e32 v64, v16
	v_add_f32_e32 v16, v64, v16
	v_sub_f32_e32 v83, v17, v52
	v_mul_f32_e32 v17, 0x4f800000, v16
	v_cmp_gt_f32_e32 vcc, s65, v16
	v_sub_f32_e32 v84, v18, v52
	v_sub_f32_e32 v85, v19, v52
	v_cndmask_b32_e32 v16, v16, v17, vcc
	v_sqrt_f32_e32 v17, v16
	v_add_f32_e32 v222, 0, v52
	v_sub_f32_e32 v32, v32, v52
	v_sub_f32_e32 v33, v33, v52
	v_add_u32_e32 v18, -1, v17
	v_fma_f32 v19, -v18, v17, v16
	v_cmp_ge_f32_e64 s[0:1], 0, v19
	v_add_u32_e32 v19, 1, v17
	v_sub_f32_e32 v34, v34, v52
	v_cndmask_b32_e64 v18, v17, v18, s[0:1]
	v_fma_f32 v17, -v19, v17, v16
	v_cmp_lt_f32_e64 s[0:1], 0, v17
	v_sub_f32_e32 v35, v35, v52
	v_sub_f32_e32 v36, v36, v52
	v_cndmask_b32_e64 v17, v18, v19, s[0:1]
	v_mul_f32_e32 v18, 0x37800000, v17
	v_cndmask_b32_e32 v17, v17, v18, vcc
	v_cmp_class_f32_e32 vcc, v16, v218
	v_sub_f32_e32 v37, v37, v52
	v_sub_f32_e32 v38, v38, v52
	v_cndmask_b32_e32 v16, v17, v16, vcc
	v_fma_f32 v16, v216, v16, -v222
	v_cmp_ge_f32_e32 vcc, s66, v16
	s_cmp_lg_u64 vcc, exec
	s_cselect_b64 s[0:1], -1, 0
	s_or_b32 s8, s9, s8
	v_sub_f32_e32 v39, v39, v52
	v_sub_f32_e32 v40, v40, v52
	v_sub_f32_e32 v41, v41, v52
	v_sub_f32_e32 v42, v42, v52
	v_sub_f32_e32 v43, v43, v52
	v_sub_f32_e32 v44, v44, v52
	v_sub_f32_e32 v45, v45, v52
	v_sub_f32_e32 v46, v46, v52
	v_sub_f32_e32 v47, v47, v52
	v_xor_b32_e32 v66, 0x80000000, v222
	v_mov_b32_e32 v16, s8
	v_mov_b32_e32 v17, v1
	v_and_b32_e32 v18, 15, v186
	v_mov_b32_e32 v67, v66
	v_mov_b32_e32 v68, v66
	v_mov_b32_e32 v69, v66
	v_mov_b32_e32 v70, v66
	v_mov_b32_e32 v71, v66
	v_mov_b32_e32 v72, v66
	v_mov_b32_e32 v73, v66
	v_mov_b32_e32 v74, v66
	v_mov_b32_e32 v75, v66
	v_mov_b32_e32 v76, v66
	v_mov_b32_e32 v77, v66
	v_mov_b32_e32 v78, v66
	v_mov_b32_e32 v79, v66
	v_mov_b32_e32 v80, v66
	v_mov_b32_e32 v81, v66
	v_exp_f32_e32 v114, v32
	v_exp_f32_e32 v115, v33
	v_exp_f32_e32 v116, v34
	v_exp_f32_e32 v117, v35
	v_exp_f32_e32 v118, v36
	v_exp_f32_e32 v119, v37
	v_exp_f32_e32 v120, v38
	v_exp_f32_e32 v121, v39
	v_exp_f32_e32 v122, v40
	v_exp_f32_e32 v123, v41
	v_exp_f32_e32 v124, v42
	v_exp_f32_e32 v125, v43
	v_exp_f32_e32 v126, v44
	v_exp_f32_e32 v127, v45
	v_exp_f32_e32 v128, v46
	v_exp_f32_e32 v129, v47
	v_mad_i64_i32 v[16:17], s[8:9], v189, s51, v[16:17]
	v_lshlrev_b32_e32 v18, 4, v18
	v_mov_b32_e32 v19, v1
	v_sub_f32_e32 v97, v31, v52
	v_sub_f32_e32 v96, v30, v52
	v_sub_f32_e32 v95, v29, v52
	v_sub_f32_e32 v94, v28, v52
	v_sub_f32_e32 v93, v27, v52
	v_sub_f32_e32 v92, v26, v52
	v_sub_f32_e32 v91, v25, v52
	v_sub_f32_e32 v90, v24, v52
	v_sub_f32_e32 v89, v23, v52
	v_sub_f32_e32 v88, v22, v52
	v_sub_f32_e32 v87, v21, v52
	v_sub_f32_e32 v86, v20, v52
	s_waitcnt vmcnt(0)
	s_waitcnt vmcnt(3)
	ds_write_b128 v108, v[48:51] offset:32768
	s_waitcnt vmcnt(1)
	ds_write_b128 v109, v[98:101] offset:32768
	ds_write_b128 v112, v[60:63] offset:49152
	s_waitcnt vmcnt(0)
	ds_write_b128 v113, v[102:105] offset:49152
	v_bitop3_b32 v240, v59, v221, v190 bitop3:0xde
	v_lshl_add_u64 v[16:17], v[16:17], 0, v[18:19]
	v_mov_b64_e32 v[64:65], v[14:15]
	v_mov_b64_e32 v[48:49], v[14:15]
	v_mov_b64_e32 v[32:33], v[14:15]
	v_lshl_add_u64 v[214:215], s[20:21], 0, v[16:17]
	v_mov_b64_e32 v[62:63], v[12:13]
	v_mov_b64_e32 v[60:61], v[10:11]
	v_mov_b64_e32 v[58:59], v[8:9]
	v_mov_b64_e32 v[56:57], v[6:7]
	v_mov_b64_e32 v[54:55], v[4:5]
	v_mov_b64_e32 v[52:53], v[2:3]
	v_mov_b64_e32 v[50:51], v[0:1]
	v_mov_b64_e32 v[46:47], v[12:13]
	v_mov_b64_e32 v[44:45], v[10:11]
	v_mov_b64_e32 v[42:43], v[8:9]
	v_mov_b64_e32 v[40:41], v[6:7]
	v_mov_b64_e32 v[38:39], v[4:5]
	v_mov_b64_e32 v[36:37], v[2:3]
	v_mov_b64_e32 v[34:35], v[0:1]
	v_mov_b64_e32 v[30:31], v[12:13]
	v_mov_b64_e32 v[28:29], v[10:11]
	v_mov_b64_e32 v[26:27], v[8:9]
	v_mov_b64_e32 v[24:25], v[6:7]
	v_mov_b64_e32 v[22:23], v[4:5]
	v_mov_b64_e32 v[20:21], v[2:3]
	v_mov_b64_e32 v[18:19], v[0:1]
	v_mov_b64_e32 v[16:17], v[14:15]
	v_mov_b64_e32 v[14:15], v[12:13]
	v_mov_b64_e32 v[12:13], v[10:11]
	v_mov_b64_e32 v[10:11], v[8:9]
	v_mov_b64_e32 v[8:9], v[6:7]
	v_mov_b64_e32 v[6:7], v[4:5]
	v_mov_b64_e32 v[4:5], v[2:3]
	v_mov_b64_e32 v[2:3], v[0:1]
	v_add_co_u32_e32 v248, vcc, s67, v214
	s_nop 1
	v_addc_co_u32_e32 v249, vcc, -1, v215, vcc
	v_add_co_u32_e32 v250, vcc, s68, v214
	s_nop 1
	v_addc_co_u32_e32 v251, vcc, -1, v215, vcc
	global_load_dwordx4 v[180:183], v[248:249], off
	global_load_dwordx4 v[184:187], v[248:249], off offset:-512
	global_load_dwordx4 v[192:195], v[250:251], off
	global_load_dwordx4 v[188:191], v[250:251], off offset:-512
	s_cmp_ge_u32 s33, 0x100
	s_cbranch_scc1 .Lh2_pro
	v_add_u32_e32 v252, 0x10000, v228
	v_add_u32_e32 v253, 0x10000, v229
	v_add_u32_e32 v254, 0x10000, v231
	v_add_u32_e32 v255, 0x10000, v232
	v_add_co_u32_e32 v248, vcc, 0xfffbf000, v214
	s_nop 1
	v_addc_co_u32_e32 v249, vcc, -1, v215, vcc
	s_waitcnt vmcnt(0)
	ds_write_b128 v252, v[180:183]
	ds_write_b128 v253, v[192:195]
	ds_write_b128 v254, v[184:187] offset:16384
	ds_write_b128 v255, v[188:191] offset:16384
	s_nop 1
	global_load_dwordx4 v[180:183], v[248:249], off
	global_load_dwordx4 v[184:187], v[248:249], off offset:-512
	global_load_dwordx4 v[192:195], v[214:215], off
	global_load_dwordx4 v[188:191], v[214:215], off offset:-512
	s_mov_b32 s96, 0x8000
	s_mov_b32 s8, 0
	s_waitcnt lgkmcnt(0)
	s_barrier
; #define SBAR() __builtin_amdgcn_sched_barrier(0)
; __device__ __forceinline__ unsigned cvtpk(float lo, float hi) { unsigned r; asm volatile("v_cvt_pk_bf16_f32 %0, %1, %2" : "=v"(r) : "v"(lo), "v"(hi)); return r; }
; #define SLOAD(k0) do { sr_.vs0 = *(const bf16x8*)(&Vh[(long)((k0) + sr) * LDK + sc]); sr_.vs1 = *(const bf16x8*)(&Vh[(long)((k0) + 32 + sr) * LDK + sc]); \
;     sr_.ks0 = *(const bf16x8*)(&Kh[(long)((k0) + sr) * LDK + sc]); sr_.ks1 = *(const bf16x8*)(&Kh[(long)((k0) + 32 + sr) * LDK + sc]); } while (0)
; __device__ __forceinline__ void qkt_fin(f32x16& n0, f32x16& n1, const bf16_t* Ks, const bf16x8* qr, const f32x16& negm, int r32, int hi, ...
;   float psa = 0.f, psb = 0.f; u32x4 wa, wb, wc, wd;
;     ...
; #pragma unroll
;   for (int d0 = 0; d0 < 8; ++d0) { int cb = (d0 * 16 + hi * 8) * 2;
;     bf16x8 b0 = *reinterpret_cast<const bf16x8*>((const char*)Ks + KSWZ(r32, cb));
;     bf16x8 b1 = *reinterpret_cast<const bf16x8*>((const char*)Ks + KSWZ(32 + r32, cb));
;     SBAR(); if (d0 == 0) n0 = __builtin_amdgcn_mfma_f32_32x32x16_bf16(b0, qr[0], negm, 0, 0, 0); else n0 = __builtin_amdgcn_mfma_f32_32x32x16_bf16(b0, qr[d0], n0, 0, 0, 0);
;     SBAR(); QF_CHUNK(2 * d0); SBAR();
;     if (d0 == 0) n1 = __builtin_amdgcn_mfma_f32_32x32x16_bf16(b1, qr[0], negm, 0, 0, 0); else n1 = __builtin_amdgcn_mfma_f32_32x32x16_bf16(b1, qr[d0], n1, 0, 0, 0);
;     SBAR(); QF_CHUNK(2 * d0 + 1); SBAR();
;     if (d0 == 7) { vf8_read<0>(vf0, vbv); SBAR(); } }
;     ...
;   psb += P1[15]; wd[3] = cvtpk(P1[14], P1[15]);
;   l_reg = l_reg * alpha + (psa + psb);
;   pa0 = *reinterpret_cast<bf16x8*>(&wa); pa1 = *reinterpret_cast<bf16x8*>(&wb); pa2 = *reinterpret_cast<bf16x8*>(&wc); pa3 = *reinterpret_cast<bf16x8*>(&wd);
; }
; __device__ __forceinline__ void attn_item(const bf16_t* __restrict__ Qb, const bf16_t* __restrict__ Kh, const bf16_t* __restrict__ Vh, const bf16_t* __restrict__ Zb, ...
;     ...
;     SBAR(); SLOAD((j + 1) * KVBLK); SBAR();
;     qkt_fin(pB0, pB1, (const bf16_t*)(lds + s_cur + KOFF), qr, negm, r32, hi, pA0, pA1, alA, l_reg, pa0, pa1, pa2, pa3, vfa, vb0 + s_prev); SBAR();
.LBB0_453:
	s_add_i32 s97, s96, 0xffff8000
	s_xor_b32 s98, s96, 0x10000
	s_add_i32 s99, s96, 0x8000
	s_and_b32 s99, s99, 0x18000
	v_add_u32_e32 v196, s96, v236
	ds_read_b128 v[98:101], v196 offset:16384
	ds_read_b128 v[196:199], v196 offset:24576
	v_add_u32_e32 v252, s96, v237
	ds_read_b128 v[248:251], v252 offset:16384
	ds_read_b128 v[252:255], v252 offset:24576
	v_add_u32_e32 v0, s97, v235
	s_waitcnt lgkmcnt(3)
	v_mfma_f32_32x32x16_bf16 v[132:147], v[98:101], v[152:155], v[66:81]
	v_exp_f32_e32 v82, v82
	s_waitcnt lgkmcnt(2)
	v_mfma_f32_32x32x16_bf16 v[98:113], v[196:199], v[152:155], v[66:81]
	v_exp_f32_e32 v83, v83
	v_add_f32_e32 v245, v115, v114
	v_cvt_pk_bf16_f32 v196, v114, v115
	v_add_u32_e32 v206, s96, v238
	ds_read_b128 v[202:205], v206 offset:16384
	ds_read_b128 v[206:209], v206 offset:24576
	s_waitcnt lgkmcnt(3)
	v_mfma_f32_32x32x16_bf16 v[132:147], v[248:251], v[160:163], v[132:147]
	v_exp_f32_e32 v84, v84
	v_add_f32_e32 v245, v116, v245
	v_add_f32_e32 v246, v82, v83
	s_waitcnt lgkmcnt(2)
	v_mfma_f32_32x32x16_bf16 v[98:113], v[252:255], v[160:163], v[98:113]
	v_exp_f32_e32 v85, v85
	v_add_f32_e32 v245, v117, v245
	v_add_f32_e32 v246, v246, v84
	v_cvt_pk_bf16_f32 v197, v116, v117
	v_cvt_pk_bf16_f32 v200, v82, v83
	v_add_u32_e32 v252, s96, v239
	ds_read_b128 v[248:251], v252 offset:16384
	ds_read_b128 v[252:255], v252 offset:24576
	s_waitcnt lgkmcnt(3)
	v_mfma_f32_32x32x16_bf16 v[132:147], v[202:205], v[148:151], v[132:147]
	v_exp_f32_e32 v86, v86
	v_add_f32_e32 v245, v118, v245
	v_add_f32_e32 v246, v246, v85
	s_waitcnt lgkmcnt(2)
	v_mfma_f32_32x32x16_bf16 v[98:113], v[206:209], v[148:151], v[98:113]
	v_exp_f32_e32 v87, v87
	v_add_f32_e32 v245, v119, v245
	v_add_f32_e32 v246, v246, v86
	v_cvt_pk_bf16_f32 v198, v118, v119
	v_cvt_pk_bf16_f32 v201, v84, v85
	v_add_u32_e32 v208, s96, v240
	ds_read_b128 v[204:207], v208 offset:16384
	ds_read_b128 v[208:211], v208 offset:24576
	s_waitcnt lgkmcnt(3)
	v_mfma_f32_32x32x16_bf16 v[132:147], v[248:251], v[156:159], v[132:147]
	v_exp_f32_e32 v88, v88
	v_add_f32_e32 v245, v120, v245
	v_add_f32_e32 v246, v246, v87
	s_waitcnt lgkmcnt(2)
	v_mfma_f32_32x32x16_bf16 v[98:113], v[252:255], v[156:159], v[98:113]
	v_exp_f32_e32 v89, v89
	v_add_f32_e32 v245, v121, v245
	v_add_f32_e32 v246, v246, v88
	v_cvt_pk_bf16_f32 v199, v120, v121
	v_cvt_pk_bf16_f32 v202, v86, v87
	v_add_u32_e32 v252, s96, v241
	ds_read_b128 v[248:251], v252 offset:16384
	ds_read_b128 v[252:255], v252 offset:24576
	s_waitcnt lgkmcnt(3)
	v_mfma_f32_32x32x16_bf16 v[132:147], v[204:207], v[168:171], v[132:147]
	v_exp_f32_e32 v90, v90
	v_add_f32_e32 v245, v122, v245
	v_add_f32_e32 v246, v246, v89
	s_waitcnt lgkmcnt(2)
	v_mfma_f32_32x32x16_bf16 v[98:113], v[208:211], v[168:171], v[98:113]
	v_exp_f32_e32 v91, v91
	v_add_f32_e32 v245, v123, v245
	v_add_f32_e32 v246, v246, v90
	v_cvt_pk_bf16_f32 v204, v122, v123
	v_cvt_pk_bf16_f32 v203, v88, v89
	v_add_u32_e32 v118, s96, v242
	ds_read_b128 v[114:117], v118 offset:16384
	ds_read_b128 v[118:121], v118 offset:24576
	s_waitcnt lgkmcnt(3)
	v_mfma_f32_32x32x16_bf16 v[132:147], v[248:251], v[176:179], v[132:147]
	v_exp_f32_e32 v92, v92
	v_add_f32_e32 v245, v124, v245
	v_add_f32_e32 v246, v246, v91
	s_waitcnt lgkmcnt(2)
	v_mfma_f32_32x32x16_bf16 v[98:113], v[252:255], v[176:179], v[98:113]
	v_exp_f32_e32 v93, v93
	v_add_f32_e32 v245, v125, v245
	v_add_f32_e32 v246, v246, v92
	v_cvt_pk_bf16_f32 v205, v124, v125
	v_cvt_pk_bf16_f32 v208, v90, v91
	v_add_u32_e32 v252, s96, v243
	ds_read_b128 v[248:251], v252 offset:16384
	ds_read_b128 v[252:255], v252 offset:24576
	s_waitcnt lgkmcnt(3)
	v_mfma_f32_32x32x16_bf16 v[132:147], v[114:117], v[164:167], v[132:147]
	v_exp_f32_e32 v94, v94
	v_add_f32_e32 v245, v126, v245
	v_add_f32_e32 v246, v246, v93
	s_waitcnt lgkmcnt(2)
	v_mfma_f32_32x32x16_bf16 v[98:113], v[118:121], v[164:167], v[98:113]
	v_exp_f32_e32 v95, v95
	v_add_f32_e32 v245, v127, v245
	v_add_f32_e32 v246, v246, v94
	v_cvt_pk_bf16_f32 v206, v126, v127
	v_cvt_pk_bf16_f32 v209, v92, v93
	s_waitcnt lgkmcnt(1)
	v_mfma_f32_32x32x16_bf16 v[132:147], v[248:251], v[172:175], v[132:147]
	v_exp_f32_e32 v96, v96
	v_add_f32_e32 v245, v128, v245
	v_add_f32_e32 v246, v246, v95
	s_waitcnt lgkmcnt(0)
	v_mfma_f32_32x32x16_bf16 v[98:113], v[252:255], v[172:175], v[98:113]
	v_exp_f32_e32 v97, v97
	v_add_f32_e32 v245, v129, v245
	v_add_f32_e32 v246, v246, v96
	v_cvt_pk_bf16_f32 v207, v128, v129
	v_cvt_pk_bf16_f32 v210, v94, v95
	v_mov_b32_e32 v131, v97
	v_cvt_pk_bf16_f32 v211, v96, v97
	ds_read_b64_tr_b16 v[94:95], v0 offset:0
	ds_read_b64_tr_b16 v[96:97], v0 offset:2048
	ds_read_b64_tr_b16 v[90:91], v0 offset:4096
	ds_read_b64_tr_b16 v[92:93], v0 offset:6144
	ds_read_b64_tr_b16 v[86:87], v0 offset:8192
	ds_read_b64_tr_b16 v[88:89], v0 offset:10240
	ds_read_b64_tr_b16 v[82:83], v0 offset:12288
	ds_read_b64_tr_b16 v[84:85], v0 offset:14336
	v_cndmask_b32_e64 v114, 0, 1, s[0:1]
	v_cmp_ne_u32_e64 s[8:9], 1, v114
	s_andn2_b64 vcc, exec, s[0:1]
	s_cbranch_vccnz .LBB0_456
; template <bool FIRST, bool DOEXP = true>
; __device__ __forceinline__ void partialSM(f32x16& p0, f32x16& p1, float& m_reg, f32x16& negm, float& alpha, const bool track = true) {
;     ...
;   float pmax = p0[0];
; #pragma unroll
;   for (int r = 1; r < 16; ++r) pmax = fmaxf(pmax, p0[r]);
; #pragma unroll
;   for (int r = 0; r < 16; ++r) pmax = fmaxf(pmax, p1[r]);
;   { auto rr = __builtin_amdgcn_permlane32_swap(__float_as_uint(pmax), __float_as_uint(pmax), false, false);
;     pmax = fmaxf(__uint_as_float(rr[0]), __uint_as_float(rr[1])); }
;   if (!FIRST && __builtin_expect(__all(pmax <= THRL), 1)) { alpha = 1.f; }
;   else { const float dl = FIRST ? pmax : fmaxf(pmax, 0.f); m_reg += dl; alpha = FIRST ? 1.f : __builtin_amdgcn_exp2f(-dl);
; #pragma unroll
;     for (int r = 0; r < 16; ++r) { p0[r] -= dl; p1[r] -= dl; }
; #pragma unroll
;     for (int r = 0; r < 16; ++r) negm[r] = -m_reg;
;     asm volatile("" : "+v"(negm)); }
	v_max_f32_e32 v114, v133, v133
	v_max_f32_e32 v115, v132, v132
	v_max_f32_e32 v114, v115, v114
	v_max3_f32 v114, v114, v134, v135
	v_max3_f32 v114, v114, v136, v137
	v_max3_f32 v114, v114, v138, v139
	v_max3_f32 v114, v114, v140, v141
	v_max3_f32 v114, v114, v142, v143
	v_max3_f32 v114, v114, v144, v145
	v_max3_f32 v114, v114, v146, v147
	v_max3_f32 v114, v114, v98, v99
	v_max3_f32 v114, v114, v100, v101
	v_max3_f32 v114, v114, v102, v103
	v_max3_f32 v114, v114, v104, v105
	v_max3_f32 v114, v114, v106, v107
	v_max3_f32 v114, v114, v108, v109
	v_max3_f32 v114, v114, v110, v111
	v_max3_f32 v114, v114, v112, v113
	v_mov_b32_e32 v115, v114
	s_nop 1
	v_permlane32_swap_b32_e32 v114, v115
	v_max_f32_e32 v115, v115, v115
	v_max_f32_e32 v114, v114, v114
	v_max_f32_e32 v114, v114, v115
	v_cmp_ge_f32_e32 vcc, s69, v114
	s_cmp_eq_u64 vcc, exec
	v_mov_b32_e32 v130, 1.0
	s_cbranch_scc1 .LBB0_457
	v_max_f32_e32 v66, v114, v114
	v_max_f32_e32 v66, 0, v66
	v_exp_f32_e64 v130, -v66
	v_add_f32_e32 v222, v222, v66
	v_sub_f32_e32 v147, v147, v66
	v_sub_f32_e32 v146, v146, v66
	v_sub_f32_e32 v145, v145, v66
	v_sub_f32_e32 v144, v144, v66
	v_sub_f32_e32 v143, v143, v66
	v_sub_f32_e32 v142, v142, v66
	v_sub_f32_e32 v141, v141, v66
	v_sub_f32_e32 v140, v140, v66
	v_sub_f32_e32 v139, v139, v66
	v_sub_f32_e32 v138, v138, v66
	v_sub_f32_e32 v137, v137, v66
	v_sub_f32_e32 v136, v136, v66
	v_sub_f32_e32 v135, v135, v66
	v_sub_f32_e32 v134, v134, v66
	v_sub_f32_e32 v133, v133, v66
	v_sub_f32_e32 v132, v132, v66
	v_sub_f32_e32 v113, v113, v66
	v_sub_f32_e32 v112, v112, v66
	v_sub_f32_e32 v111, v111, v66
	v_sub_f32_e32 v110, v110, v66
	v_sub_f32_e32 v109, v109, v66
	v_sub_f32_e32 v108, v108, v66
	v_sub_f32_e32 v107, v107, v66
	v_sub_f32_e32 v106, v106, v66
	v_sub_f32_e32 v105, v105, v66
	v_sub_f32_e32 v104, v104, v66
	v_sub_f32_e32 v103, v103, v66
	v_sub_f32_e32 v102, v102, v66
	v_sub_f32_e32 v101, v101, v66
	v_sub_f32_e32 v100, v100, v66
	v_sub_f32_e32 v99, v99, v66
	v_sub_f32_e32 v98, v98, v66
	v_xor_b32_e32 v66, 0x80000000, v222
	v_mov_b32_e32 v67, v66
	v_mov_b32_e32 v68, v66
	v_mov_b32_e32 v69, v66
	v_mov_b32_e32 v70, v66
	v_mov_b32_e32 v71, v66
	v_mov_b32_e32 v72, v66
	v_mov_b32_e32 v73, v66
	v_mov_b32_e32 v74, v66
	v_mov_b32_e32 v75, v66
	v_mov_b32_e32 v76, v66
	v_mov_b32_e32 v77, v66
	v_mov_b32_e32 v78, v66
	v_mov_b32_e32 v79, v66
	v_mov_b32_e32 v80, v66
	v_mov_b32_e32 v81, v66
	s_branch .LBB0_457

; #define SBAR() __builtin_amdgcn_sched_barrier(0)
; #define PVE_M(OD, PA, L, H, IDX) do { OD = __builtin_amdgcn_mfma_f32_32x32x16_bf16(PA, PKV(L, H), OD, 0, 0, 0); SBAR(); p[IDX] = __builtin_amdgcn_exp2f(p[IDX]); asm volatile("" : "+v"(p)); SBAR(); } while (0)
; #define SWRITE(so) do { *(bf16x8*)(lds + (so) + vst0) = sr_.vs0; *(bf16x8*)(lds + (so) + vst1) = sr_.vs1;          \
;     *(bf16x8*)(lds + (so) + kst0) = sr_.ks0; *(bf16x8*)(lds + (so) + kst1) = sr_.ks1; } while (0)
; #define SWAIT() asm volatile("s_waitcnt vmcnt(0)" ::: "memory")
; #define RESC(a) do { if (__any((a) < 1.f)) { if (hi == 0) al_l[r32] = (a); asm volatile("s_waitcnt lgkmcnt(0)" ::: "memory"); \
;     _Pragma("unroll") for (int d = 0; d < 4; ++d) _Pragma("unroll") for (int r = 0; r < 16; ++r) o[d][r] *= al_l[crow(r, hi)]; } } while (0)
; #define ROT() do { const int t_ = s_prev; s_prev = s_cur; s_cur = s_next; s_next = t_; } while (0)
; __device__ __forceinline__ void pv_exp(f32x16* o, int vb, bf16x8 pa0, bf16x8 pa1, bf16x8 pa2, bf16x8 pa3, f32x16& p, VF8& fa) {
;   VF8 fb;
;   asm volatile("s_waitcnt lgkmcnt(0)" ::: "memory"); SBAR();
;   PVE_M(o[0], pa0, fa.l0, fa.h0, 0); PVE_M(o[0], pa1, fa.l1, fa.h1, 1); vf8_read<1>(fb, vb); SBAR(); PVE_M(o[0], pa2, fa.l2, fa.h2, 2); PVE_M(o[0], pa3, fa.l3, fa.h3, 3);
;   asm volatile("s_waitcnt lgkmcnt(0)" ::: "memory"); SBAR();
;   PVE_M(o[1], pa0, fb.l0, fb.h0, 4); PVE_M(o[1], pa1, fb.l1, fb.h1, 5); vf8_read<2>(fa, vb); SBAR(); PVE_M(o[1], pa2, fb.l2, fb.h2, 6); PVE_M(o[1], pa3, fb.l3, fb.h3, 7);
;   asm volatile("s_waitcnt lgkmcnt(0)" ::: "memory"); SBAR();
;   PVE_M(o[2], pa0, fa.l0, fa.h0, 8); PVE_M(o[2], pa1, fa.l1, fa.h1, 9); vf8_read<3>(fb, vb); SBAR(); PVE_M(o[2], pa2, fa.l2, fa.h2, 10); PVE_M(o[2], pa3, fa.l3, fa.h3, 11);
;   asm volatile("s_waitcnt lgkmcnt(0)" ::: "memory"); SBAR();
;   PVE_M(o[3], pa0, fb.l0, fb.h0, 12); PVE_M(o[3], pa1, fb.l1, fb.h1, 13); PVE_M(o[3], pa2, fb.l2, fb.h2, 14); PVE_M(o[3], pa3, fb.l3, fb.h3, 15);
; }
; __device__ __forceinline__ void attn_item(const bf16_t* __restrict__ Qb, const bf16_t* __restrict__ Kh, const bf16_t* __restrict__ Vh, const bf16_t* __restrict__ Zb, ...
;     ...
;     partialSM<false, false>(pB0, pB1, m_reg, negm, alB, track); SBAR(); pv_exp(o, vb0 + s_prev, pa0, pa1, pa2, pa3, pB0, vfa);
;     SWAIT(); SWRITE(s_next);
;     RESC(alB); __syncthreads(); ROT();
.LBB0_457:
	s_barrier
	s_waitcnt lgkmcnt(0)
	v_mfma_f32_32x32x16_bf16 v[50:65], v[196:199], v[94:97], v[50:65]
	v_exp_f32_e32 v132, v132
	v_mfma_f32_32x32x16_bf16 v[50:65], v[204:207], v[90:93], v[50:65]
	v_exp_f32_e32 v133, v133
	ds_read_b64_tr_b16 v[90:91], v0 offset:0x200
	ds_read_b64_tr_b16 v[92:93], v0 offset:0xa00
	ds_read_b64_tr_b16 v[94:95], v0 offset:0x1200
	ds_read_b64_tr_b16 v[96:97], v0 offset:0x1a00
	ds_read_b64_tr_b16 v[114:115], v0 offset:0x2200
	ds_read_b64_tr_b16 v[116:117], v0 offset:0x2a00
	ds_read_b64_tr_b16 v[118:119], v0 offset:0x3200
	ds_read_b64_tr_b16 v[120:121], v0 offset:0x3a00
	s_waitcnt vmcnt(3)
	v_add_u32_e32 v248, s98, v228
	ds_write_b128 v248, v[180:183]
	v_mfma_f32_32x32x16_bf16 v[50:65], v[200:203], v[86:89], v[50:65]
	v_exp_f32_e32 v134, v134
	v_mfma_f32_32x32x16_bf16 v[50:65], v[208:211], v[82:85], v[50:65]
	v_exp_f32_e32 v135, v135
	s_waitcnt lgkmcnt(1)
	v_mfma_f32_32x32x16_bf16 v[34:49], v[196:199], v[90:93], v[34:49]
	v_exp_f32_e32 v136, v136
	v_mfma_f32_32x32x16_bf16 v[34:49], v[204:207], v[94:97], v[34:49]
	v_exp_f32_e32 v137, v137
	ds_read_b64_tr_b16 v[82:83], v0 offset:0x400
	ds_read_b64_tr_b16 v[84:85], v0 offset:0xc00
	ds_read_b64_tr_b16 v[86:87], v0 offset:0x1400
	ds_read_b64_tr_b16 v[88:89], v0 offset:0x1c00
	ds_read_b64_tr_b16 v[90:91], v0 offset:0x2400
	ds_read_b64_tr_b16 v[92:93], v0 offset:0x2c00
	ds_read_b64_tr_b16 v[94:95], v0 offset:0x3400
	ds_read_b64_tr_b16 v[96:97], v0 offset:0x3c00
	s_waitcnt vmcnt(2)
	v_add_u32_e32 v249, s98, v231
	ds_write_b128 v249, v[184:187] offset:16384
	v_mfma_f32_32x32x16_bf16 v[34:49], v[200:203], v[114:117], v[34:49]
	v_exp_f32_e32 v138, v138
	v_mfma_f32_32x32x16_bf16 v[34:49], v[208:211], v[118:121], v[34:49]
	v_exp_f32_e32 v139, v139
	s_waitcnt lgkmcnt(1)
	v_mfma_f32_32x32x16_bf16 v[18:33], v[196:199], v[82:85], v[18:33]
	v_exp_f32_e32 v140, v140
	v_mfma_f32_32x32x16_bf16 v[18:33], v[204:207], v[86:89], v[18:33]
	v_exp_f32_e32 v141, v141
	ds_read_b64_tr_b16 v[82:83], v0 offset:0x600
	ds_read_b64_tr_b16 v[84:85], v0 offset:0xe00
	ds_read_b64_tr_b16 v[86:87], v0 offset:0x1600
	ds_read_b64_tr_b16 v[88:89], v0 offset:0x1e00
	ds_read_b64_tr_b16 v[114:115], v0 offset:0x2600
	ds_read_b64_tr_b16 v[116:117], v0 offset:0x2e00
	ds_read_b64_tr_b16 v[118:119], v0 offset:0x3600
	ds_read_b64_tr_b16 v[120:121], v0 offset:0x3e00
	s_waitcnt vmcnt(1)
	v_add_u32_e32 v250, s98, v229
	ds_write_b128 v250, v[192:195]
	v_mfma_f32_32x32x16_bf16 v[18:33], v[200:203], v[90:93], v[18:33]
	v_exp_f32_e32 v142, v142
	v_mfma_f32_32x32x16_bf16 v[18:33], v[208:211], v[94:97], v[18:33]
	v_exp_f32_e32 v143, v143
	s_waitcnt lgkmcnt(1)
	v_mfma_f32_32x32x16_bf16 v[2:17], v[196:199], v[82:85], v[2:17]
	v_exp_f32_e32 v144, v144
	s_waitcnt vmcnt(0)
	v_add_u32_e32 v251, s98, v232
	ds_write_b128 v251, v[188:191] offset:16384
	v_add_co_u32_e32 v252, vcc, 0x41000, v214
	s_nop 1
	v_addc_co_u32_e32 v253, vcc, 0, v215, vcc
	v_add_co_u32_e32 v254, vcc, 0x82000, v214
	s_nop 1
	v_addc_co_u32_e32 v255, vcc, 0, v215, vcc
	global_load_dwordx4 v[188:191], v[252:253], off
	global_load_dwordx4 v[180:183], v[252:253], off offset:-512
	global_load_dwordx4 v[192:195], v[254:255], off
	global_load_dwordx4 v[184:187], v[254:255], off offset:-512
	v_mfma_f32_32x32x16_bf16 v[2:17], v[204:207], v[86:89], v[2:17]
	v_exp_f32_e32 v145, v145
	v_mfma_f32_32x32x16_bf16 v[2:17], v[200:203], v[114:117], v[2:17]
	v_exp_f32_e32 v146, v146
	v_mfma_f32_32x32x16_bf16 v[2:17], v[208:211], v[118:121], v[2:17]
	v_exp_f32_e32 v147, v147
	v_cmp_gt_f32_e32 vcc, 1.0, v130
	s_cbranch_vccz .LBB0_461
	s_and_saveexec_b64 s[36:37], s[6:7]
	ds_write_b32 v220, v130 offset:128
	s_or_b64 exec, exec, s[36:37]
	s_waitcnt lgkmcnt(0)
	v_add_u32_e32 v94, v213, v212
	ds_read_b128 v[82:85], v94 offset:224
	ds_read_b128 v[86:89], v94 offset:192
	ds_read_b128 v[90:93], v94 offset:160
	ds_read_b128 v[94:97], v94 offset:128
	s_waitcnt lgkmcnt(3)
	v_pk_mul_f32 v[62:63], v[62:63], v[82:83]
	s_waitcnt lgkmcnt(2)
	v_pk_mul_f32 v[58:59], v[58:59], v[86:87]
	s_waitcnt lgkmcnt(1)
	v_pk_mul_f32 v[54:55], v[54:55], v[90:91]
	v_pk_mul_f32 v[64:65], v[64:65], v[84:85]
	v_pk_mul_f32 v[60:61], v[60:61], v[88:89]
	v_pk_mul_f32 v[56:57], v[56:57], v[92:93]
	s_waitcnt lgkmcnt(0)
	v_pk_mul_f32 v[52:53], v[52:53], v[96:97]
	v_pk_mul_f32 v[50:51], v[50:51], v[94:95]
	v_pk_mul_f32 v[46:47], v[46:47], v[82:83]
	v_pk_mul_f32 v[42:43], v[42:43], v[86:87]
	v_pk_mul_f32 v[38:39], v[38:39], v[90:91]
	v_pk_mul_f32 v[48:49], v[48:49], v[84:85]
	v_pk_mul_f32 v[44:45], v[44:45], v[88:89]
	v_pk_mul_f32 v[40:41], v[40:41], v[92:93]
	v_pk_mul_f32 v[36:37], v[36:37], v[96:97]
	v_pk_mul_f32 v[34:35], v[34:35], v[94:95]
	v_pk_mul_f32 v[30:31], v[30:31], v[82:83]
	v_pk_mul_f32 v[26:27], v[26:27], v[86:87]
	v_pk_mul_f32 v[22:23], v[22:23], v[90:91]
	v_pk_mul_f32 v[32:33], v[32:33], v[84:85]
	v_pk_mul_f32 v[28:29], v[28:29], v[88:89]
	v_pk_mul_f32 v[24:25], v[24:25], v[92:93]
	v_pk_mul_f32 v[20:21], v[20:21], v[96:97]
	v_pk_mul_f32 v[18:19], v[18:19], v[94:95]
	v_pk_mul_f32 v[14:15], v[14:15], v[82:83]
	v_pk_mul_f32 v[10:11], v[10:11], v[86:87]
	v_pk_mul_f32 v[6:7], v[6:7], v[90:91]
	v_pk_mul_f32 v[16:17], v[16:17], v[84:85]
	v_pk_mul_f32 v[12:13], v[12:13], v[88:89]
	v_pk_mul_f32 v[8:9], v[8:9], v[92:93]
	v_pk_mul_f32 v[4:5], v[4:5], v[96:97]
	v_pk_mul_f32 v[2:3], v[2:3], v[94:95]
; #define SBAR() __builtin_amdgcn_sched_barrier(0)
; __device__ __forceinline__ unsigned cvtpk(float lo, float hi) { unsigned r; asm volatile("v_cvt_pk_bf16_f32 %0, %1, %2" : "=v"(r) : "v"(lo), "v"(hi)); return r; }
; #define SLOAD(k0) do { sr_.vs0 = *(const bf16x8*)(&Vh[(long)((k0) + sr) * LDK + sc]); sr_.vs1 = *(const bf16x8*)(&Vh[(long)((k0) + 32 + sr) * LDK + sc]); \
;     sr_.ks0 = *(const bf16x8*)(&Kh[(long)((k0) + sr) * LDK + sc]); sr_.ks1 = *(const bf16x8*)(&Kh[(long)((k0) + 32 + sr) * LDK + sc]); } while (0)
; __device__ __forceinline__ void qkt_fin(f32x16& n0, f32x16& n1, const bf16_t* Ks, const bf16x8* qr, const f32x16& negm, int r32, int hi, ...
;   float psa = 0.f, psb = 0.f; u32x4 wa, wb, wc, wd;
;     ...
; #pragma unroll
;   for (int d0 = 0; d0 < 8; ++d0) { int cb = (d0 * 16 + hi * 8) * 2;
;     bf16x8 b0 = *reinterpret_cast<const bf16x8*>((const char*)Ks + KSWZ(r32, cb));
;     bf16x8 b1 = *reinterpret_cast<const bf16x8*>((const char*)Ks + KSWZ(32 + r32, cb));
;     SBAR(); if (d0 == 0) n0 = __builtin_amdgcn_mfma_f32_32x32x16_bf16(b0, qr[0], negm, 0, 0, 0); else n0 = __builtin_amdgcn_mfma_f32_32x32x16_bf16(b0, qr[d0], n0, 0, 0, 0);
;     SBAR(); QF_CHUNK(2 * d0); SBAR();
;     if (d0 == 0) n1 = __builtin_amdgcn_mfma_f32_32x32x16_bf16(b1, qr[0], negm, 0, 0, 0); else n1 = __builtin_amdgcn_mfma_f32_32x32x16_bf16(b1, qr[d0], n1, 0, 0, 0);
;     SBAR(); QF_CHUNK(2 * d0 + 1); SBAR();
;     if (d0 == 7) { vf8_read<0>(vf0, vbv); SBAR(); } }
;     ...
;   psb += P1[15]; wd[3] = cvtpk(P1[14], P1[15]);
;   l_reg = l_reg * alpha + (psa + psb);
;   pa0 = *reinterpret_cast<bf16x8*>(&wa); pa1 = *reinterpret_cast<bf16x8*>(&wb); pa2 = *reinterpret_cast<bf16x8*>(&wc); pa3 = *reinterpret_cast<bf16x8*>(&wd);
; }
; __device__ __forceinline__ void attn_item(const bf16_t* __restrict__ Qb, const bf16_t* __restrict__ Kh, const bf16_t* __restrict__ Vh, const bf16_t* __restrict__ Zb, ...
;     ...
;     SBAR(); SLOAD((j + 2) * KVBLK); SBAR();
;     qkt_fin(pA0, pA1, (const bf16_t*)(lds + s_cur + KOFF), qr, negm, r32, hi, pB0, pB1, alB, l_reg, pa0, pa1, pa2, pa3, vfa, vb0 + s_prev); SBAR();
;     partialSM<false, false>(pA0, pA1, m_reg, negm, alA, track); SBAR(); pv_exp(o, vb0 + s_prev, pa0, pa1, pa2, pa3, pA0, vfa);
.LBB0_461:
	s_waitcnt lgkmcnt(0)
	v_add_u32_e32 v208, s99, v236
	ds_read_b128 v[204:207], v208 offset:16384
	ds_read_b128 v[208:211], v208 offset:24576
	v_add_u32_e32 v252, s99, v237
	ds_read_b128 v[248:251], v252 offset:16384
	ds_read_b128 v[252:255], v252 offset:24576
	v_add_u32_e32 v203, s96, v235
	s_waitcnt lgkmcnt(3)
	v_mfma_f32_32x32x16_bf16 v[114:129], v[204:207], v[152:155], v[66:81]
	v_exp_f32_e32 v98, v98
	s_waitcnt lgkmcnt(2)
	v_mfma_f32_32x32x16_bf16 v[82:97], v[208:211], v[152:155], v[66:81]
	v_exp_f32_e32 v99, v99
	v_add_f32_e32 v201, v133, v132
	v_cvt_pk_bf16_f32 v132, v132, v133
	v_add_u32_e32 v208, s99, v238
	ds_read_b128 v[204:207], v208 offset:16384
	ds_read_b128 v[208:211], v208 offset:24576
	s_waitcnt lgkmcnt(3)
	v_mfma_f32_32x32x16_bf16 v[114:129], v[248:251], v[160:163], v[114:129]
	v_exp_f32_e32 v100, v100
	v_add_f32_e32 v201, v134, v201
	v_add_f32_e32 v202, v98, v99
	s_waitcnt lgkmcnt(2)
	v_mfma_f32_32x32x16_bf16 v[82:97], v[252:255], v[160:163], v[82:97]
	v_exp_f32_e32 v101, v101
	v_add_f32_e32 v201, v135, v201
	v_add_f32_e32 v202, v202, v100
	v_cvt_pk_bf16_f32 v133, v134, v135
	v_cvt_pk_bf16_f32 v196, v98, v99
	v_add_u32_e32 v252, s99, v239
	ds_read_b128 v[248:251], v252 offset:16384
	ds_read_b128 v[252:255], v252 offset:24576
	s_waitcnt lgkmcnt(3)
	v_mfma_f32_32x32x16_bf16 v[114:129], v[204:207], v[148:151], v[114:129]
	v_exp_f32_e32 v102, v102
	v_add_f32_e32 v201, v136, v201
	v_add_f32_e32 v202, v202, v101
	s_waitcnt lgkmcnt(2)
	v_mfma_f32_32x32x16_bf16 v[82:97], v[208:211], v[148:151], v[82:97]
	v_exp_f32_e32 v103, v103
	v_add_f32_e32 v201, v137, v201
	v_add_f32_e32 v202, v202, v102
	v_cvt_pk_bf16_f32 v134, v136, v137
	v_cvt_pk_bf16_f32 v197, v100, v101
	v_add_u32_e32 v208, s99, v240
	ds_read_b128 v[204:207], v208 offset:16384
	ds_read_b128 v[208:211], v208 offset:24576
	s_waitcnt lgkmcnt(3)
	v_mfma_f32_32x32x16_bf16 v[114:129], v[248:251], v[156:159], v[114:129]
	v_exp_f32_e32 v104, v104
	v_add_f32_e32 v201, v138, v201
	v_add_f32_e32 v202, v202, v103
	s_waitcnt lgkmcnt(2)
	v_mfma_f32_32x32x16_bf16 v[82:97], v[252:255], v[156:159], v[82:97]
	v_exp_f32_e32 v105, v105
	v_add_f32_e32 v201, v139, v201
	v_add_f32_e32 v202, v202, v104
	v_cvt_pk_bf16_f32 v135, v138, v139
	v_cvt_pk_bf16_f32 v198, v102, v103
	v_add_u32_e32 v252, s99, v241
	ds_read_b128 v[248:251], v252 offset:16384
	ds_read_b128 v[252:255], v252 offset:24576
	s_waitcnt lgkmcnt(3)
	v_mfma_f32_32x32x16_bf16 v[114:129], v[204:207], v[168:171], v[114:129]
	v_exp_f32_e32 v106, v106
	v_add_f32_e32 v201, v140, v201
	v_add_f32_e32 v202, v202, v105
	s_waitcnt lgkmcnt(2)
	v_mfma_f32_32x32x16_bf16 v[82:97], v[208:211], v[168:171], v[82:97]
	v_exp_f32_e32 v107, v107
	v_add_f32_e32 v201, v141, v201
	v_add_f32_e32 v202, v202, v106
	v_cvt_pk_bf16_f32 v136, v140, v141
	v_cvt_pk_bf16_f32 v199, v104, v105
	v_add_u32_e32 v208, s99, v242
	ds_read_b128 v[204:207], v208 offset:16384
	ds_read_b128 v[208:211], v208 offset:24576
	s_waitcnt lgkmcnt(3)
	v_mfma_f32_32x32x16_bf16 v[114:129], v[248:251], v[176:179], v[114:129]
	v_exp_f32_e32 v108, v108
	v_add_f32_e32 v201, v142, v201
	v_add_f32_e32 v202, v202, v107
	s_waitcnt lgkmcnt(2)
	v_mfma_f32_32x32x16_bf16 v[82:97], v[252:255], v[176:179], v[82:97]
	v_exp_f32_e32 v109, v109
	v_add_f32_e32 v201, v143, v201
	v_add_f32_e32 v202, v202, v108
	v_cvt_pk_bf16_f32 v137, v142, v143
	v_cvt_pk_bf16_f32 v140, v106, v107
	v_add_u32_e32 v252, s99, v243
	ds_read_b128 v[248:251], v252 offset:16384
	ds_read_b128 v[252:255], v252 offset:24576
	s_waitcnt lgkmcnt(3)
	v_mfma_f32_32x32x16_bf16 v[114:129], v[204:207], v[164:167], v[114:129]
	v_exp_f32_e32 v110, v110
	v_add_f32_e32 v201, v144, v201
	v_add_f32_e32 v202, v202, v109
	s_waitcnt lgkmcnt(2)
	v_mfma_f32_32x32x16_bf16 v[82:97], v[208:211], v[164:167], v[82:97]
	v_exp_f32_e32 v111, v111
	v_add_f32_e32 v201, v145, v201
	v_add_f32_e32 v202, v202, v110
	v_cvt_pk_bf16_f32 v138, v144, v145
	v_cvt_pk_bf16_f32 v141, v108, v109
	s_waitcnt lgkmcnt(1)
	v_mfma_f32_32x32x16_bf16 v[114:129], v[248:251], v[172:175], v[114:129]
	v_exp_f32_e32 v112, v112
	v_add_f32_e32 v201, v146, v201
	v_add_f32_e32 v202, v202, v111
	s_waitcnt lgkmcnt(0)
	v_mfma_f32_32x32x16_bf16 v[82:97], v[252:255], v[172:175], v[82:97]
	v_exp_f32_e32 v113, v113
	v_add_f32_e32 v201, v147, v201
	v_add_f32_e32 v202, v202, v112
	v_cvt_pk_bf16_f32 v139, v146, v147
	v_cvt_pk_bf16_f32 v142, v110, v111
	ds_read_b64_tr_b16 v[144:145], v203 offset:0
	ds_read_b64_tr_b16 v[146:147], v203 offset:2048
	s_nop 0
	ds_read_b64_tr_b16 v[106:107], v203 offset:4096
	ds_read_b64_tr_b16 v[108:109], v203 offset:6144
	ds_read_b64_tr_b16 v[102:103], v203 offset:8192
	ds_read_b64_tr_b16 v[104:105], v203 offset:10240
	ds_read_b64_tr_b16 v[98:99], v203 offset:12288
	ds_read_b64_tr_b16 v[100:101], v203 offset:14336
	v_cvt_pk_bf16_f32 v143, v112, v113
	s_and_b64 vcc, exec, s[8:9]
	v_mov_b32_e32 v200, 1.0
	s_cbranch_vccnz .LBB0_463
	v_max_f32_e32 v110, v115, v115
	v_max_f32_e32 v111, v114, v114
	v_max_f32_e32 v110, v111, v110
	v_max3_f32 v110, v110, v116, v117
	v_max3_f32 v110, v110, v118, v119
	v_max3_f32 v110, v110, v120, v121
	v_max3_f32 v110, v110, v122, v123
	v_max3_f32 v110, v110, v124, v125
	v_max3_f32 v110, v110, v126, v127
	v_max3_f32 v110, v110, v128, v129
	v_max3_f32 v110, v110, v82, v83
	v_max3_f32 v110, v110, v84, v85
	v_max3_f32 v110, v110, v86, v87
	v_max3_f32 v110, v110, v88, v89
	v_max3_f32 v110, v110, v90, v91
	v_max3_f32 v110, v110, v92, v93
	v_max3_f32 v110, v110, v94, v95
	v_max3_f32 v110, v110, v96, v97
	v_mov_b32_e32 v111, v110
	s_nop 1
	v_permlane32_swap_b32_e32 v110, v111
	v_max_f32_e32 v111, v111, v111
	v_max_f32_e32 v110, v110, v110
	v_max_f32_e32 v110, v110, v111
	v_cmp_ge_f32_e32 vcc, s69, v110
	s_cmp_eq_u64 vcc, exec
	v_mov_b32_e32 v200, 1.0
	s_cbranch_scc0 .LBB0_469
; #define SBAR() __builtin_amdgcn_sched_barrier(0)
; #define PVE_M(OD, PA, L, H, IDX) do { OD = __builtin_amdgcn_mfma_f32_32x32x16_bf16(PA, PKV(L, H), OD, 0, 0, 0); SBAR(); p[IDX] = __builtin_amdgcn_exp2f(p[IDX]); asm volatile("" : "+v"(p)); SBAR(); } while (0)
; #define SWRITE(so) do { *(bf16x8*)(lds + (so) + vst0) = sr_.vs0; *(bf16x8*)(lds + (so) + vst1) = sr_.vs1;          \
;     *(bf16x8*)(lds + (so) + kst0) = sr_.ks0; *(bf16x8*)(lds + (so) + kst1) = sr_.ks1; } while (0)
; #define SWAIT() asm volatile("s_waitcnt vmcnt(0)" ::: "memory")
; #define RESC(a) do { if (__any((a) < 1.f)) { if (hi == 0) al_l[r32] = (a); asm volatile("s_waitcnt lgkmcnt(0)" ::: "memory"); \
;     _Pragma("unroll") for (int d = 0; d < 4; ++d) _Pragma("unroll") for (int r = 0; r < 16; ++r) o[d][r] *= al_l[crow(r, hi)]; } } while (0)
; #define ROT() do { const int t_ = s_prev; s_prev = s_cur; s_cur = s_next; s_next = t_; } while (0)
; __device__ __forceinline__ void pv_exp(f32x16* o, int vb, bf16x8 pa0, bf16x8 pa1, bf16x8 pa2, bf16x8 pa3, f32x16& p, VF8& fa) {
;   VF8 fb;
;   asm volatile("s_waitcnt lgkmcnt(0)" ::: "memory"); SBAR();
;   PVE_M(o[0], pa0, fa.l0, fa.h0, 0); PVE_M(o[0], pa1, fa.l1, fa.h1, 1); vf8_read<1>(fb, vb); SBAR(); PVE_M(o[0], pa2, fa.l2, fa.h2, 2); PVE_M(o[0], pa3, fa.l3, fa.h3, 3);
;   asm volatile("s_waitcnt lgkmcnt(0)" ::: "memory"); SBAR();
;   PVE_M(o[1], pa0, fb.l0, fb.h0, 4); PVE_M(o[1], pa1, fb.l1, fb.h1, 5); vf8_read<2>(fa, vb); SBAR(); PVE_M(o[1], pa2, fb.l2, fb.h2, 6); PVE_M(o[1], pa3, fb.l3, fb.h3, 7);
;   asm volatile("s_waitcnt lgkmcnt(0)" ::: "memory"); SBAR();
;   PVE_M(o[2], pa0, fa.l0, fa.h0, 8); PVE_M(o[2], pa1, fa.l1, fa.h1, 9); vf8_read<3>(fb, vb); SBAR(); PVE_M(o[2], pa2, fa.l2, fa.h2, 10); PVE_M(o[2], pa3, fa.l3, fa.h3, 11);
;   asm volatile("s_waitcnt lgkmcnt(0)" ::: "memory"); SBAR();
;   PVE_M(o[3], pa0, fb.l0, fb.h0, 12); PVE_M(o[3], pa1, fb.l1, fb.h1, 13); PVE_M(o[3], pa2, fb.l2, fb.h2, 14); PVE_M(o[3], pa3, fb.l3, fb.h3, 15);
; }
; __device__ __forceinline__ void attn_item(const bf16_t* __restrict__ Qb, const bf16_t* __restrict__ Kh, const bf16_t* __restrict__ Vh, const bf16_t* __restrict__ Zb, ...
;     ...
;     partialSM<false, false>(pA0, pA1, m_reg, negm, alA, track); SBAR(); pv_exp(o, vb0 + s_prev, pa0, pa1, pa2, pa3, pA0, vfa);
;     SWAIT(); SWRITE(s_next);
;     RESC(alA); __syncthreads(); ROT();
;   }
.LBB0_463:
	s_barrier
	s_waitcnt lgkmcnt(0)
	v_mfma_f32_32x32x16_bf16 v[50:65], v[132:135], v[144:147], v[50:65]
	v_exp_f32_e32 v114, v114
	v_mfma_f32_32x32x16_bf16 v[50:65], v[136:139], v[106:109], v[50:65]
	v_exp_f32_e32 v115, v115
	ds_read_b64_tr_b16 v[106:107], v203 offset:0x200
	ds_read_b64_tr_b16 v[108:109], v203 offset:0xa00
	ds_read_b64_tr_b16 v[144:145], v203 offset:0x1200
	ds_read_b64_tr_b16 v[146:147], v203 offset:0x1a00
	ds_read_b64_tr_b16 v[204:205], v203 offset:0x2200
	ds_read_b64_tr_b16 v[206:207], v203 offset:0x2a00
	ds_read_b64_tr_b16 v[208:209], v203 offset:0x3200
	ds_read_b64_tr_b16 v[210:211], v203 offset:0x3a00
	s_waitcnt vmcnt(3)
	v_add_u32_e32 v248, s97, v228
	ds_write_b128 v248, v[188:191]
	v_mfma_f32_32x32x16_bf16 v[50:65], v[196:199], v[102:105], v[50:65]
	v_exp_f32_e32 v116, v116
	v_mfma_f32_32x32x16_bf16 v[50:65], v[140:143], v[98:101], v[50:65]
	v_exp_f32_e32 v117, v117
	s_waitcnt lgkmcnt(1)
	v_mfma_f32_32x32x16_bf16 v[34:49], v[132:135], v[106:109], v[34:49]
	v_exp_f32_e32 v118, v118
	v_mfma_f32_32x32x16_bf16 v[34:49], v[136:139], v[144:147], v[34:49]
	v_exp_f32_e32 v119, v119
	ds_read_b64_tr_b16 v[98:99], v203 offset:0x400
	ds_read_b64_tr_b16 v[100:101], v203 offset:0xc00
	ds_read_b64_tr_b16 v[102:103], v203 offset:0x1400
	ds_read_b64_tr_b16 v[104:105], v203 offset:0x1c00
	ds_read_b64_tr_b16 v[106:107], v203 offset:0x2400
	ds_read_b64_tr_b16 v[108:109], v203 offset:0x2c00
	ds_read_b64_tr_b16 v[144:145], v203 offset:0x3400
	ds_read_b64_tr_b16 v[146:147], v203 offset:0x3c00
	s_waitcnt vmcnt(2)
	v_add_u32_e32 v249, s97, v231
	ds_write_b128 v249, v[180:183] offset:16384
	v_mfma_f32_32x32x16_bf16 v[34:49], v[196:199], v[204:207], v[34:49]
	v_exp_f32_e32 v120, v120
	v_mfma_f32_32x32x16_bf16 v[34:49], v[140:143], v[208:211], v[34:49]
	v_exp_f32_e32 v121, v121
	s_waitcnt lgkmcnt(1)
	v_mfma_f32_32x32x16_bf16 v[18:33], v[132:135], v[98:101], v[18:33]
	v_exp_f32_e32 v122, v122
	v_mfma_f32_32x32x16_bf16 v[18:33], v[136:139], v[102:105], v[18:33]
	v_exp_f32_e32 v123, v123
	ds_read_b64_tr_b16 v[98:99], v203 offset:0x600
	ds_read_b64_tr_b16 v[100:101], v203 offset:0xe00
	ds_read_b64_tr_b16 v[102:103], v203 offset:0x1600
	ds_read_b64_tr_b16 v[104:105], v203 offset:0x1e00
	ds_read_b64_tr_b16 v[204:205], v203 offset:0x2600
	ds_read_b64_tr_b16 v[206:207], v203 offset:0x2e00
	ds_read_b64_tr_b16 v[208:209], v203 offset:0x3600
	ds_read_b64_tr_b16 v[210:211], v203 offset:0x3e00
	s_waitcnt vmcnt(1)
	v_add_u32_e32 v250, s97, v229
	ds_write_b128 v250, v[192:195]
	v_mfma_f32_32x32x16_bf16 v[18:33], v[196:199], v[106:109], v[18:33]
	v_exp_f32_e32 v124, v124
	v_mfma_f32_32x32x16_bf16 v[18:33], v[140:143], v[144:147], v[18:33]
	v_exp_f32_e32 v125, v125
	s_waitcnt lgkmcnt(1)
	v_mfma_f32_32x32x16_bf16 v[2:17], v[132:135], v[98:101], v[2:17]
	v_exp_f32_e32 v126, v126
	s_waitcnt vmcnt(0)
	v_add_u32_e32 v251, s97, v232
	ds_write_b128 v251, v[184:187] offset:16384
	v_add_co_u32_e32 v252, vcc, 0xc3000, v214
	s_nop 1
	v_addc_co_u32_e32 v253, vcc, 0, v215, vcc
	v_add_co_u32_e32 v254, vcc, 0x104000, v214
	s_nop 1
	v_addc_co_u32_e32 v255, vcc, 0, v215, vcc
	global_load_dwordx4 v[180:183], v[252:253], off
	global_load_dwordx4 v[184:187], v[252:253], off offset:-512
	global_load_dwordx4 v[192:195], v[254:255], off
	global_load_dwordx4 v[188:191], v[254:255], off offset:-512
	v_mfma_f32_32x32x16_bf16 v[2:17], v[136:139], v[102:105], v[2:17]
	v_exp_f32_e32 v127, v127
	v_mfma_f32_32x32x16_bf16 v[2:17], v[196:199], v[204:207], v[2:17]
	v_exp_f32_e32 v128, v128
	v_mfma_f32_32x32x16_bf16 v[2:17], v[140:143], v[208:211], v[2:17]
	v_exp_f32_e32 v129, v129
	v_cmp_gt_f32_e32 vcc, 1.0, v200
	s_cbranch_vccz .LBB0_467
	s_and_saveexec_b64 s[36:37], s[6:7]
	ds_write_b32 v220, v200 offset:128
	s_or_b64 exec, exec, s[36:37]
	s_waitcnt lgkmcnt(0)
	v_add_u32_e32 v110, v213, v212
	ds_read_b128 v[98:101], v110 offset:224
	ds_read_b128 v[102:105], v110 offset:192
	ds_read_b128 v[106:109], v110 offset:160
	ds_read_b128 v[132:135], v110 offset:128
	s_waitcnt lgkmcnt(3)
	v_pk_mul_f32 v[62:63], v[62:63], v[98:99]
	s_waitcnt lgkmcnt(2)
	v_pk_mul_f32 v[58:59], v[58:59], v[102:103]
	s_waitcnt lgkmcnt(1)
	v_pk_mul_f32 v[54:55], v[54:55], v[106:107]
	v_pk_mul_f32 v[64:65], v[64:65], v[100:101]
	v_pk_mul_f32 v[60:61], v[60:61], v[104:105]
	v_pk_mul_f32 v[56:57], v[56:57], v[108:109]
	s_waitcnt lgkmcnt(0)
	v_pk_mul_f32 v[52:53], v[52:53], v[134:135]
	v_pk_mul_f32 v[50:51], v[50:51], v[132:133]
	v_pk_mul_f32 v[46:47], v[46:47], v[98:99]
	v_pk_mul_f32 v[42:43], v[42:43], v[102:103]
	v_pk_mul_f32 v[38:39], v[38:39], v[106:107]
	v_pk_mul_f32 v[48:49], v[48:49], v[100:101]
	v_pk_mul_f32 v[44:45], v[44:45], v[104:105]
	v_pk_mul_f32 v[40:41], v[40:41], v[108:109]
	v_pk_mul_f32 v[36:37], v[36:37], v[134:135]
	v_pk_mul_f32 v[34:35], v[34:35], v[132:133]
	v_pk_mul_f32 v[30:31], v[30:31], v[98:99]
	v_pk_mul_f32 v[26:27], v[26:27], v[102:103]
	v_pk_mul_f32 v[22:23], v[22:23], v[106:107]
	v_pk_mul_f32 v[32:33], v[32:33], v[100:101]
	v_pk_mul_f32 v[28:29], v[28:29], v[104:105]
	v_pk_mul_f32 v[24:25], v[24:25], v[108:109]
	v_pk_mul_f32 v[20:21], v[20:21], v[134:135]
	v_pk_mul_f32 v[18:19], v[18:19], v[132:133]
	v_pk_mul_f32 v[14:15], v[14:15], v[98:99]
	v_pk_mul_f32 v[10:11], v[10:11], v[102:103]
	v_pk_mul_f32 v[6:7], v[6:7], v[106:107]
	v_pk_mul_f32 v[16:17], v[16:17], v[100:101]
	v_pk_mul_f32 v[12:13], v[12:13], v[104:105]
	v_pk_mul_f32 v[8:9], v[8:9], v[108:109]
	v_pk_mul_f32 v[4:5], v[4:5], v[134:135]
	v_pk_mul_f32 v[2:3], v[2:3], v[132:133]
.LBB0_467:
	v_add_f32_e32 v98, v246, v131
	v_add_f32_e32 v98, v245, v98
	v_add_f32_e32 v99, v202, v113
	v_fmac_f32_e32 v98, v244, v219
	v_add_f32_e32 v219, v201, v99
	s_add_i32 s78, s78, 2
	v_fmac_f32_e32 v219, v98, v130
	s_cmpk_gt_u32 s78, 0xfc
	v_lshl_add_u64 v[214:215], v[214:215], 0, s[22:23]
	s_waitcnt lgkmcnt(0)
	s_cbranch_scc1 .LBB0_470
	s_xor_b32 s96, s96, 0x10000
	v_mov_b32_e32 v244, v200
	s_branch .LBB0_453

; #define SWRITE(so) do { *(bf16x8*)(lds + (so) + vst0) = sr_.vs0; *(bf16x8*)(lds + (so) + vst1) = sr_.vs1;          \
;     *(bf16x8*)(lds + (so) + kst0) = sr_.ks0; *(bf16x8*)(lds + (so) + kst1) = sr_.ks1; } while (0)
; #define SWAIT() asm volatile("s_waitcnt vmcnt(0)" ::: "memory")
; __device__ __forceinline__ void attn_item(const bf16_t* __restrict__ Qb, const bf16_t* __restrict__ Kh, const bf16_t* __restrict__ Vh, const bf16_t* __restrict__ Zb, ...
;     ...
;   SWAIT(); SWRITE(SLOT); __syncthreads();
;   for (int j = 1; j + 1 < NT; j += 2) {
.Lh2_pro:
	s_mov_b32 s96, 0x8000
	s_mov_b32 s8, 0
	s_waitcnt lgkmcnt(0)
	s_barrier

; #define SBAR() __builtin_amdgcn_sched_barrier(0)
; #define PVE_M(OD, PA, L, H, IDX) do { OD = __builtin_amdgcn_mfma_f32_32x32x16_bf16(PA, PKV(L, H), OD, 0, 0, 0); SBAR(); p[IDX] = __builtin_amdgcn_exp2f(p[IDX]); asm volatile("" : "+v"(p)); SBAR(); } while (0)
; #define SWRITE(so) do { *(bf16x8*)(lds + (so) + vst0) = sr_.vs0; *(bf16x8*)(lds + (so) + vst1) = sr_.vs1;          \
;     *(bf16x8*)(lds + (so) + kst0) = sr_.ks0; *(bf16x8*)(lds + (so) + kst1) = sr_.ks1; } while (0)
; #define SWAIT() asm volatile("s_waitcnt vmcnt(0)" ::: "memory")
; #define RESC(a) do { if (__any((a) < 1.f)) { if (hi == 0) al_l[r32] = (a); asm volatile("s_waitcnt lgkmcnt(0)" ::: "memory"); \
;     _Pragma("unroll") for (int d = 0; d < 4; ++d) _Pragma("unroll") for (int r = 0; r < 16; ++r) o[d][r] *= al_l[crow(r, hi)]; } } while (0)
; #define ROT() do { const int t_ = s_prev; s_prev = s_cur; s_cur = s_next; s_next = t_; } while (0)
; __device__ __forceinline__ void pv_exp(f32x16* o, int vb, bf16x8 pa0, bf16x8 pa1, bf16x8 pa2, bf16x8 pa3, f32x16& p, VF8& fa) {
;   VF8 fb;
;   asm volatile("s_waitcnt lgkmcnt(0)" ::: "memory"); SBAR();
;   PVE_M(o[0], pa0, fa.l0, fa.h0, 0); PVE_M(o[0], pa1, fa.l1, fa.h1, 1); vf8_read<1>(fb, vb); SBAR(); PVE_M(o[0], pa2, fa.l2, fa.h2, 2); PVE_M(o[0], pa3, fa.l3, fa.h3, 3);
;   asm volatile("s_waitcnt lgkmcnt(0)" ::: "memory"); SBAR();
;   PVE_M(o[1], pa0, fb.l0, fb.h0, 4); PVE_M(o[1], pa1, fb.l1, fb.h1, 5); vf8_read<2>(fa, vb); SBAR(); PVE_M(o[1], pa2, fb.l2, fb.h2, 6); PVE_M(o[1], pa3, fb.l3, fb.h3, 7);
;   asm volatile("s_waitcnt lgkmcnt(0)" ::: "memory"); SBAR();
;   PVE_M(o[2], pa0, fa.l0, fa.h0, 8); PVE_M(o[2], pa1, fa.l1, fa.h1, 9); vf8_read<3>(fb, vb); SBAR(); PVE_M(o[2], pa2, fa.l2, fa.h2, 10); PVE_M(o[2], pa3, fa.l3, fa.h3, 11);
;   asm volatile("s_waitcnt lgkmcnt(0)" ::: "memory"); SBAR();
;   PVE_M(o[3], pa0, fb.l0, fb.h0, 12); PVE_M(o[3], pa1, fb.l1, fb.h1, 13); PVE_M(o[3], pa2, fb.l2, fb.h2, 14); PVE_M(o[3], pa3, fb.l3, fb.h3, 15);
; }
; __device__ __forceinline__ void attn_item(const bf16_t* __restrict__ Qb, const bf16_t* __restrict__ Kh, const bf16_t* __restrict__ Vh, const bf16_t* __restrict__ Zb, ...
;     ...
;     partialSM<false, false>(pB0, pB1, m_reg, negm, alB, track); SBAR(); pv_exp(o, vb0 + s_prev, pa0, pa1, pa2, pa3, pB0, vfa);
;     SWAIT(); SWRITE(s_next);
;     RESC(alB); __syncthreads(); ROT();
.Lh2_457:
	s_waitcnt lgkmcnt(0)
	v_mfma_f32_32x32x16_bf16 v[50:65], v[196:199], v[94:97], v[50:65]
	v_exp_f32_e32 v132, v132
	v_mfma_f32_32x32x16_bf16 v[50:65], v[204:207], v[90:93], v[50:65]
	v_exp_f32_e32 v133, v133
	ds_read_b64_tr_b16 v[90:91], v0 offset:0x200
	ds_read_b64_tr_b16 v[92:93], v0 offset:0xa00
	ds_read_b64_tr_b16 v[94:95], v0 offset:0x1200
	ds_read_b64_tr_b16 v[96:97], v0 offset:0x1a00
	ds_read_b64_tr_b16 v[114:115], v0 offset:0x2200
	ds_read_b64_tr_b16 v[116:117], v0 offset:0x2a00
	ds_read_b64_tr_b16 v[118:119], v0 offset:0x3200
	ds_read_b64_tr_b16 v[120:121], v0 offset:0x3a00
	s_waitcnt vmcnt(3)
	v_add_u32_e32 v248, s99, v228
	ds_write_b128 v248, v[180:183]
	v_mfma_f32_32x32x16_bf16 v[50:65], v[200:203], v[86:89], v[50:65]
	v_exp_f32_e32 v134, v134
	v_mfma_f32_32x32x16_bf16 v[50:65], v[208:211], v[82:85], v[50:65]
	v_exp_f32_e32 v135, v135
	s_waitcnt lgkmcnt(1)
	v_mfma_f32_32x32x16_bf16 v[34:49], v[196:199], v[90:93], v[34:49]
	v_exp_f32_e32 v136, v136
	v_mfma_f32_32x32x16_bf16 v[34:49], v[204:207], v[94:97], v[34:49]
	v_exp_f32_e32 v137, v137
	ds_read_b64_tr_b16 v[82:83], v0 offset:0x400
	ds_read_b64_tr_b16 v[84:85], v0 offset:0xc00
	ds_read_b64_tr_b16 v[86:87], v0 offset:0x1400
	ds_read_b64_tr_b16 v[88:89], v0 offset:0x1c00
	ds_read_b64_tr_b16 v[90:91], v0 offset:0x2400
	ds_read_b64_tr_b16 v[92:93], v0 offset:0x2c00
	ds_read_b64_tr_b16 v[94:95], v0 offset:0x3400
	ds_read_b64_tr_b16 v[96:97], v0 offset:0x3c00
	s_waitcnt vmcnt(2)
	v_add_u32_e32 v249, s99, v231
	ds_write_b128 v249, v[184:187] offset:16384
	v_mfma_f32_32x32x16_bf16 v[34:49], v[200:203], v[114:117], v[34:49]
	v_exp_f32_e32 v138, v138
	v_mfma_f32_32x32x16_bf16 v[34:49], v[208:211], v[118:121], v[34:49]
	v_exp_f32_e32 v139, v139
	s_waitcnt lgkmcnt(1)
	v_mfma_f32_32x32x16_bf16 v[18:33], v[196:199], v[82:85], v[18:33]
	v_exp_f32_e32 v140, v140
	v_mfma_f32_32x32x16_bf16 v[18:33], v[204:207], v[86:89], v[18:33]
	v_exp_f32_e32 v141, v141
	ds_read_b64_tr_b16 v[82:83], v0 offset:0x600
	ds_read_b64_tr_b16 v[84:85], v0 offset:0xe00
	ds_read_b64_tr_b16 v[86:87], v0 offset:0x1600
	ds_read_b64_tr_b16 v[88:89], v0 offset:0x1e00
	ds_read_b64_tr_b16 v[114:115], v0 offset:0x2600
	ds_read_b64_tr_b16 v[116:117], v0 offset:0x2e00
	ds_read_b64_tr_b16 v[118:119], v0 offset:0x3600
	ds_read_b64_tr_b16 v[120:121], v0 offset:0x3e00
	s_waitcnt vmcnt(1)
	v_add_u32_e32 v250, s99, v229
	ds_write_b128 v250, v[192:195]
	v_mfma_f32_32x32x16_bf16 v[18:33], v[200:203], v[90:93], v[18:33]
	v_exp_f32_e32 v142, v142
	v_mfma_f32_32x32x16_bf16 v[18:33], v[208:211], v[94:97], v[18:33]
	v_exp_f32_e32 v143, v143
	s_waitcnt lgkmcnt(1)
	v_mfma_f32_32x32x16_bf16 v[2:17], v[196:199], v[82:85], v[2:17]
	v_exp_f32_e32 v144, v144
	s_waitcnt vmcnt(0)
	v_add_u32_e32 v251, s99, v232
	ds_write_b128 v251, v[188:191] offset:16384
	v_add_co_u32_e32 v252, vcc, 0xfffbf000, v214
	s_nop 1
	v_addc_co_u32_e32 v253, vcc, -1, v215, vcc
	global_load_dwordx4 v[188:191], v[252:253], off
	global_load_dwordx4 v[180:183], v[252:253], off offset:-512
	global_load_dwordx4 v[192:195], v[214:215], off
	global_load_dwordx4 v[184:187], v[214:215], off offset:-512
	v_mfma_f32_32x32x16_bf16 v[2:17], v[204:207], v[86:89], v[2:17]
	v_exp_f32_e32 v145, v145
	v_mfma_f32_32x32x16_bf16 v[2:17], v[200:203], v[114:117], v[2:17]
	v_exp_f32_e32 v146, v146
	v_mfma_f32_32x32x16_bf16 v[2:17], v[208:211], v[118:121], v[2:17]
	v_exp_f32_e32 v147, v147
	v_cmp_gt_f32_e32 vcc, 1.0, v130
	s_cbranch_vccz .Lh2_461
	s_and_saveexec_b64 s[36:37], s[6:7]
	ds_write_b32 v220, v130 offset:128
	s_or_b64 exec, exec, s[36:37]
	s_waitcnt lgkmcnt(0)
	v_add_u32_e32 v94, v213, v212
	ds_read_b128 v[82:85], v94 offset:224
	ds_read_b128 v[86:89], v94 offset:192
	ds_read_b128 v[90:93], v94 offset:160
	ds_read_b128 v[94:97], v94 offset:128
	s_waitcnt lgkmcnt(3)
	v_pk_mul_f32 v[62:63], v[62:63], v[82:83]
	s_waitcnt lgkmcnt(2)
	v_pk_mul_f32 v[58:59], v[58:59], v[86:87]
	s_waitcnt lgkmcnt(1)
	v_pk_mul_f32 v[54:55], v[54:55], v[90:91]
	v_pk_mul_f32 v[64:65], v[64:65], v[84:85]
	v_pk_mul_f32 v[60:61], v[60:61], v[88:89]
	v_pk_mul_f32 v[56:57], v[56:57], v[92:93]
	s_waitcnt lgkmcnt(0)
	v_pk_mul_f32 v[52:53], v[52:53], v[96:97]
	v_pk_mul_f32 v[50:51], v[50:51], v[94:95]
	v_pk_mul_f32 v[46:47], v[46:47], v[82:83]
	v_pk_mul_f32 v[42:43], v[42:43], v[86:87]
	v_pk_mul_f32 v[38:39], v[38:39], v[90:91]
	v_pk_mul_f32 v[48:49], v[48:49], v[84:85]
	v_pk_mul_f32 v[44:45], v[44:45], v[88:89]
	v_pk_mul_f32 v[40:41], v[40:41], v[92:93]
	v_pk_mul_f32 v[36:37], v[36:37], v[96:97]
	v_pk_mul_f32 v[34:35], v[34:35], v[94:95]
	v_pk_mul_f32 v[30:31], v[30:31], v[82:83]
	v_pk_mul_f32 v[26:27], v[26:27], v[86:87]
	v_pk_mul_f32 v[22:23], v[22:23], v[90:91]
	v_pk_mul_f32 v[32:33], v[32:33], v[84:85]
	v_pk_mul_f32 v[28:29], v[28:29], v[88:89]
	v_pk_mul_f32 v[24:25], v[24:25], v[92:93]
	v_pk_mul_f32 v[20:21], v[20:21], v[96:97]
	v_pk_mul_f32 v[18:19], v[18:19], v[94:95]
	v_pk_mul_f32 v[14:15], v[14:15], v[82:83]
	v_pk_mul_f32 v[10:11], v[10:11], v[86:87]
	v_pk_mul_f32 v[6:7], v[6:7], v[90:91]
	v_pk_mul_f32 v[16:17], v[16:17], v[84:85]
	v_pk_mul_f32 v[12:13], v[12:13], v[88:89]
	v_pk_mul_f32 v[8:9], v[8:9], v[92:93]
	v_pk_mul_f32 v[4:5], v[4:5], v[96:97]
	v_pk_mul_f32 v[2:3], v[2:3], v[94:95]
; #define SBAR() __builtin_amdgcn_sched_barrier(0)
; __device__ __forceinline__ unsigned cvtpk(float lo, float hi) { unsigned r; asm volatile("v_cvt_pk_bf16_f32 %0, %1, %2" : "=v"(r) : "v"(lo), "v"(hi)); return r; }
; #define SLOAD(k0) do { sr_.vs0 = *(const bf16x8*)(&Vh[(long)((k0) + sr) * LDK + sc]); sr_.vs1 = *(const bf16x8*)(&Vh[(long)((k0) + 32 + sr) * LDK + sc]); \
;     sr_.ks0 = *(const bf16x8*)(&Kh[(long)((k0) + sr) * LDK + sc]); sr_.ks1 = *(const bf16x8*)(&Kh[(long)((k0) + 32 + sr) * LDK + sc]); } while (0)
; __device__ __forceinline__ void qkt_fin(f32x16& n0, f32x16& n1, const bf16_t* Ks, const bf16x8* qr, const f32x16& negm, int r32, int hi, ...
;   float psa = 0.f, psb = 0.f; u32x4 wa, wb, wc, wd;
;     ...
; #pragma unroll
;   for (int d0 = 0; d0 < 8; ++d0) { int cb = (d0 * 16 + hi * 8) * 2;
;     bf16x8 b0 = *reinterpret_cast<const bf16x8*>((const char*)Ks + KSWZ(r32, cb));
;     bf16x8 b1 = *reinterpret_cast<const bf16x8*>((const char*)Ks + KSWZ(32 + r32, cb));
;     SBAR(); if (d0 == 0) n0 = __builtin_amdgcn_mfma_f32_32x32x16_bf16(b0, qr[0], negm, 0, 0, 0); else n0 = __builtin_amdgcn_mfma_f32_32x32x16_bf16(b0, qr[d0], n0, 0, 0, 0);
;     SBAR(); QF_CHUNK(2 * d0); SBAR();
;     if (d0 == 0) n1 = __builtin_amdgcn_mfma_f32_32x32x16_bf16(b1, qr[0], negm, 0, 0, 0); else n1 = __builtin_amdgcn_mfma_f32_32x32x16_bf16(b1, qr[d0], n1, 0, 0, 0);
;     SBAR(); QF_CHUNK(2 * d0 + 1); SBAR();
;     if (d0 == 7) { vf8_read<0>(vf0, vbv); SBAR(); } }
;     ...
;   psb += P1[15]; wd[3] = cvtpk(P1[14], P1[15]);
;   l_reg = l_reg * alpha + (psa + psb);
;   pa0 = *reinterpret_cast<bf16x8*>(&wa); pa1 = *reinterpret_cast<bf16x8*>(&wb); pa2 = *reinterpret_cast<bf16x8*>(&wc); pa3 = *reinterpret_cast<bf16x8*>(&wd);
; }
; __device__ __forceinline__ void attn_item(const bf16_t* __restrict__ Qb, const bf16_t* __restrict__ Kh, const bf16_t* __restrict__ Vh, const bf16_t* __restrict__ Zb, ...
;     ...
;     SBAR(); SLOAD((j + 2) * KVBLK); SBAR();
;     qkt_fin(pA0, pA1, (const bf16_t*)(lds + s_cur + KOFF), qr, negm, r32, hi, pB0, pB1, alB, l_reg, pa0, pa1, pa2, pa3, vfa, vb0 + s_prev); SBAR();
;     partialSM<false, false>(pA0, pA1, m_reg, negm, alA, track); SBAR(); pv_exp(o, vb0 + s_prev, pa0, pa1, pa2, pa3, pA0, vfa);
.Lh2_461:
	s_waitcnt lgkmcnt(0)
	s_barrier
	v_add_u32_e32 v208, s99, v236
	ds_read_b128 v[204:207], v208 offset:16384
	ds_read_b128 v[208:211], v208 offset:24576
	v_add_u32_e32 v252, s99, v237
	ds_read_b128 v[248:251], v252 offset:16384
	ds_read_b128 v[252:255], v252 offset:24576
	v_add_u32_e32 v203, s96, v235
	s_waitcnt lgkmcnt(3)
	v_mfma_f32_32x32x16_bf16 v[114:129], v[204:207], v[152:155], v[66:81]
	v_exp_f32_e32 v98, v98
	s_waitcnt lgkmcnt(2)
	v_mfma_f32_32x32x16_bf16 v[82:97], v[208:211], v[152:155], v[66:81]
	v_exp_f32_e32 v99, v99
	v_add_f32_e32 v201, v133, v132
	v_cvt_pk_bf16_f32 v132, v132, v133
	v_add_u32_e32 v208, s99, v238
	ds_read_b128 v[204:207], v208 offset:16384
	ds_read_b128 v[208:211], v208 offset:24576
	s_waitcnt lgkmcnt(3)
	v_mfma_f32_32x32x16_bf16 v[114:129], v[248:251], v[160:163], v[114:129]
	v_exp_f32_e32 v100, v100
	v_add_f32_e32 v201, v134, v201
	v_add_f32_e32 v202, v98, v99
	s_waitcnt lgkmcnt(2)
	v_mfma_f32_32x32x16_bf16 v[82:97], v[252:255], v[160:163], v[82:97]
	v_exp_f32_e32 v101, v101
	v_add_f32_e32 v201, v135, v201
	v_add_f32_e32 v202, v202, v100
	v_cvt_pk_bf16_f32 v133, v134, v135
	v_cvt_pk_bf16_f32 v196, v98, v99
	v_add_u32_e32 v252, s99, v239
	ds_read_b128 v[248:251], v252 offset:16384
	ds_read_b128 v[252:255], v252 offset:24576
	s_waitcnt lgkmcnt(3)
	v_mfma_f32_32x32x16_bf16 v[114:129], v[204:207], v[148:151], v[114:129]
	v_exp_f32_e32 v102, v102
	v_add_f32_e32 v201, v136, v201
	v_add_f32_e32 v202, v202, v101
	s_waitcnt lgkmcnt(2)
	v_mfma_f32_32x32x16_bf16 v[82:97], v[208:211], v[148:151], v[82:97]
	v_exp_f32_e32 v103, v103
	v_add_f32_e32 v201, v137, v201
	v_add_f32_e32 v202, v202, v102
	v_cvt_pk_bf16_f32 v134, v136, v137
	v_cvt_pk_bf16_f32 v197, v100, v101
	v_add_u32_e32 v208, s99, v240
	ds_read_b128 v[204:207], v208 offset:16384
	ds_read_b128 v[208:211], v208 offset:24576
	s_waitcnt lgkmcnt(3)
	v_mfma_f32_32x32x16_bf16 v[114:129], v[248:251], v[156:159], v[114:129]
	v_exp_f32_e32 v104, v104
	v_add_f32_e32 v201, v138, v201
	v_add_f32_e32 v202, v202, v103
	s_waitcnt lgkmcnt(2)
	v_mfma_f32_32x32x16_bf16 v[82:97], v[252:255], v[156:159], v[82:97]
	v_exp_f32_e32 v105, v105
	v_add_f32_e32 v201, v139, v201
	v_add_f32_e32 v202, v202, v104
	v_cvt_pk_bf16_f32 v135, v138, v139
	v_cvt_pk_bf16_f32 v198, v102, v103
	v_add_u32_e32 v252, s99, v241
	ds_read_b128 v[248:251], v252 offset:16384
	ds_read_b128 v[252:255], v252 offset:24576
	s_waitcnt lgkmcnt(3)
	v_mfma_f32_32x32x16_bf16 v[114:129], v[204:207], v[168:171], v[114:129]
	v_exp_f32_e32 v106, v106
	v_add_f32_e32 v201, v140, v201
	v_add_f32_e32 v202, v202, v105
	s_waitcnt lgkmcnt(2)
	v_mfma_f32_32x32x16_bf16 v[82:97], v[208:211], v[168:171], v[82:97]
	v_exp_f32_e32 v107, v107
	v_add_f32_e32 v201, v141, v201
	v_add_f32_e32 v202, v202, v106
	v_cvt_pk_bf16_f32 v136, v140, v141
	v_cvt_pk_bf16_f32 v199, v104, v105
	v_add_u32_e32 v208, s99, v242
	ds_read_b128 v[204:207], v208 offset:16384
	ds_read_b128 v[208:211], v208 offset:24576
	s_waitcnt lgkmcnt(3)
	v_mfma_f32_32x32x16_bf16 v[114:129], v[248:251], v[176:179], v[114:129]
	v_exp_f32_e32 v108, v108
	v_add_f32_e32 v201, v142, v201
	v_add_f32_e32 v202, v202, v107
	s_waitcnt lgkmcnt(2)
	v_mfma_f32_32x32x16_bf16 v[82:97], v[252:255], v[176:179], v[82:97]
	v_exp_f32_e32 v109, v109
	v_add_f32_e32 v201, v143, v201
	v_add_f32_e32 v202, v202, v108
	v_cvt_pk_bf16_f32 v137, v142, v143
	v_cvt_pk_bf16_f32 v140, v106, v107
	v_add_u32_e32 v252, s99, v243
	ds_read_b128 v[248:251], v252 offset:16384
	ds_read_b128 v[252:255], v252 offset:24576
	s_waitcnt lgkmcnt(3)
	v_mfma_f32_32x32x16_bf16 v[114:129], v[204:207], v[164:167], v[114:129]
	v_exp_f32_e32 v110, v110
	v_add_f32_e32 v201, v144, v201
	v_add_f32_e32 v202, v202, v109
	s_waitcnt lgkmcnt(2)
	v_mfma_f32_32x32x16_bf16 v[82:97], v[208:211], v[164:167], v[82:97]
	v_exp_f32_e32 v111, v111
	v_add_f32_e32 v201, v145, v201
	v_add_f32_e32 v202, v202, v110
	v_cvt_pk_bf16_f32 v138, v144, v145
	v_cvt_pk_bf16_f32 v141, v108, v109
	s_waitcnt lgkmcnt(1)
	v_mfma_f32_32x32x16_bf16 v[114:129], v[248:251], v[172:175], v[114:129]
	v_exp_f32_e32 v112, v112
	v_add_f32_e32 v201, v146, v201
	v_add_f32_e32 v202, v202, v111
	s_waitcnt lgkmcnt(0)
	v_mfma_f32_32x32x16_bf16 v[82:97], v[252:255], v[172:175], v[82:97]
	v_exp_f32_e32 v113, v113
	v_add_f32_e32 v201, v147, v201
	v_add_f32_e32 v202, v202, v112
	v_cvt_pk_bf16_f32 v139, v146, v147
	v_cvt_pk_bf16_f32 v142, v110, v111
	ds_read_b64_tr_b16 v[144:145], v203 offset:0
	ds_read_b64_tr_b16 v[146:147], v203 offset:2048
	s_nop 0
	ds_read_b64_tr_b16 v[106:107], v203 offset:4096
	ds_read_b64_tr_b16 v[108:109], v203 offset:6144
	ds_read_b64_tr_b16 v[102:103], v203 offset:8192
	ds_read_b64_tr_b16 v[104:105], v203 offset:10240
	ds_read_b64_tr_b16 v[98:99], v203 offset:12288
	ds_read_b64_tr_b16 v[100:101], v203 offset:14336
	v_cvt_pk_bf16_f32 v143, v112, v113
	s_and_b64 vcc, exec, s[8:9]
	v_mov_b32_e32 v200, 1.0
	s_cbranch_vccnz .Lh2_463
	v_max_f32_e32 v110, v115, v115
	v_max_f32_e32 v111, v114, v114
	v_max_f32_e32 v110, v111, v110
	v_max3_f32 v110, v110, v116, v117
	v_max3_f32 v110, v110, v118, v119
	v_max3_f32 v110, v110, v120, v121
	v_max3_f32 v110, v110, v122, v123
	v_max3_f32 v110, v110, v124, v125
	v_max3_f32 v110, v110, v126, v127
	v_max3_f32 v110, v110, v128, v129
	v_max3_f32 v110, v110, v82, v83
	v_max3_f32 v110, v110, v84, v85
	v_max3_f32 v110, v110, v86, v87
	v_max3_f32 v110, v110, v88, v89
	v_max3_f32 v110, v110, v90, v91
	v_max3_f32 v110, v110, v92, v93
	v_max3_f32 v110, v110, v94, v95
	v_max3_f32 v110, v110, v96, v97
	v_mov_b32_e32 v111, v110
	s_nop 1
	v_permlane32_swap_b32_e32 v110, v111
	v_max_f32_e32 v111, v111, v111
	v_max_f32_e32 v110, v110, v110
	v_max_f32_e32 v110, v110, v111
	v_cmp_ge_f32_e32 vcc, s69, v110
	s_cmp_eq_u64 vcc, exec
	v_mov_b32_e32 v200, 1.0
	s_cbranch_scc0 .Lh2_469
; #define SBAR() __builtin_amdgcn_sched_barrier(0)
; #define PVE_M(OD, PA, L, H, IDX) do { OD = __builtin_amdgcn_mfma_f32_32x32x16_bf16(PA, PKV(L, H), OD, 0, 0, 0); SBAR(); p[IDX] = __builtin_amdgcn_exp2f(p[IDX]); asm volatile("" : "+v"(p)); SBAR(); } while (0)
; __device__ __forceinline__ void pv_exp(f32x16* o, int vb, bf16x8 pa0, bf16x8 pa1, bf16x8 pa2, bf16x8 pa3, f32x16& p, VF8& fa) {
;   VF8 fb;
;   asm volatile("s_waitcnt lgkmcnt(0)" ::: "memory"); SBAR();
;   PVE_M(o[0], pa0, fa.l0, fa.h0, 0); PVE_M(o[0], pa1, fa.l1, fa.h1, 1); vf8_read<1>(fb, vb); SBAR(); PVE_M(o[0], pa2, fa.l2, fa.h2, 2); PVE_M(o[0], pa3, fa.l3, fa.h3, 3);
;   asm volatile("s_waitcnt lgkmcnt(0)" ::: "memory"); SBAR();
;   PVE_M(o[1], pa0, fb.l0, fb.h0, 4); PVE_M(o[1], pa1, fb.l1, fb.h1, 5); vf8_read<2>(fa, vb); SBAR(); PVE_M(o[1], pa2, fb.l2, fb.h2, 6); PVE_M(o[1], pa3, fb.l3, fb.h3, 7);
;   asm volatile("s_waitcnt lgkmcnt(0)" ::: "memory"); SBAR();
;   PVE_M(o[2], pa0, fa.l0, fa.h0, 8); PVE_M(o[2], pa1, fa.l1, fa.h1, 9); vf8_read<3>(fb, vb); SBAR(); PVE_M(o[2], pa2, fa.l2, fa.h2, 10); PVE_M(o[2], pa3, fa.l3, fa.h3, 11);
;   asm volatile("s_waitcnt lgkmcnt(0)" ::: "memory"); SBAR();
;   PVE_M(o[3], pa0, fb.l0, fb.h0, 12); PVE_M(o[3], pa1, fb.l1, fb.h1, 13); PVE_M(o[3], pa2, fb.l2, fb.h2, 14); PVE_M(o[3], pa3, fb.l3, fb.h3, 15);
; }
.Lh2_463:
	s_waitcnt lgkmcnt(0)
	v_mfma_f32_32x32x16_bf16 v[50:65], v[132:135], v[144:147], v[50:65]
	v_exp_f32_e32 v114, v114
	v_mfma_f32_32x32x16_bf16 v[50:65], v[136:139], v[106:109], v[50:65]
	v_exp_f32_e32 v115, v115
	ds_read_b64_tr_b16 v[106:107], v203 offset:0x200
	ds_read_b64_tr_b16 v[108:109], v203 offset:0xa00
	ds_read_b64_tr_b16 v[144:145], v203 offset:0x1200
	ds_read_b64_tr_b16 v[146:147], v203 offset:0x1a00
	ds_read_b64_tr_b16 v[204:205], v203 offset:0x2200
	ds_read_b64_tr_b16 v[206:207], v203 offset:0x2a00
	ds_read_b64_tr_b16 v[208:209], v203 offset:0x3200
	ds_read_b64_tr_b16 v[210:211], v203 offset:0x3a00
	s_waitcnt vmcnt(3)
	v_add_u32_e32 v248, s98, v228
	ds_write_b128 v248, v[188:191]
	v_mfma_f32_32x32x16_bf16 v[50:65], v[196:199], v[102:105], v[50:65]
	v_exp_f32_e32 v116, v116
	v_mfma_f32_32x32x16_bf16 v[50:65], v[140:143], v[98:101], v[50:65]
	v_exp_f32_e32 v117, v117
	s_waitcnt lgkmcnt(1)
	v_mfma_f32_32x32x16_bf16 v[34:49], v[132:135], v[106:109], v[34:49]
	v_exp_f32_e32 v118, v118
	v_mfma_f32_32x32x16_bf16 v[34:49], v[136:139], v[144:147], v[34:49]
	v_exp_f32_e32 v119, v119
	ds_read_b64_tr_b16 v[98:99], v203 offset:0x400
	ds_read_b64_tr_b16 v[100:101], v203 offset:0xc00
	ds_read_b64_tr_b16 v[102:103], v203 offset:0x1400
	ds_read_b64_tr_b16 v[104:105], v203 offset:0x1c00
	ds_read_b64_tr_b16 v[106:107], v203 offset:0x2400
	ds_read_b64_tr_b16 v[108:109], v203 offset:0x2c00
	ds_read_b64_tr_b16 v[144:145], v203 offset:0x3400
	ds_read_b64_tr_b16 v[146:147], v203 offset:0x3c00
	s_waitcnt vmcnt(2)
	v_add_u32_e32 v249, s98, v231
	ds_write_b128 v249, v[180:183] offset:16384
	v_mfma_f32_32x32x16_bf16 v[34:49], v[196:199], v[204:207], v[34:49]
	v_exp_f32_e32 v120, v120
	v_mfma_f32_32x32x16_bf16 v[34:49], v[140:143], v[208:211], v[34:49]
	v_exp_f32_e32 v121, v121
	s_waitcnt lgkmcnt(1)
	v_mfma_f32_32x32x16_bf16 v[18:33], v[132:135], v[98:101], v[18:33]
	v_exp_f32_e32 v122, v122
	v_mfma_f32_32x32x16_bf16 v[18:33], v[136:139], v[102:105], v[18:33]
	v_exp_f32_e32 v123, v123
	ds_read_b64_tr_b16 v[98:99], v203 offset:0x600
	ds_read_b64_tr_b16 v[100:101], v203 offset:0xe00
	ds_read_b64_tr_b16 v[102:103], v203 offset:0x1600
	ds_read_b64_tr_b16 v[104:105], v203 offset:0x1e00
	ds_read_b64_tr_b16 v[204:205], v203 offset:0x2600
	ds_read_b64_tr_b16 v[206:207], v203 offset:0x2e00
	ds_read_b64_tr_b16 v[208:209], v203 offset:0x3600
	ds_read_b64_tr_b16 v[210:211], v203 offset:0x3e00
	s_waitcnt vmcnt(1)
	v_add_u32_e32 v250, s98, v229
	ds_write_b128 v250, v[192:195]
	v_mfma_f32_32x32x16_bf16 v[18:33], v[196:199], v[106:109], v[18:33]
	v_exp_f32_e32 v124, v124
	v_mfma_f32_32x32x16_bf16 v[18:33], v[140:143], v[144:147], v[18:33]
	v_exp_f32_e32 v125, v125
	s_waitcnt lgkmcnt(1)
	v_mfma_f32_32x32x16_bf16 v[2:17], v[132:135], v[98:101], v[2:17]
	v_exp_f32_e32 v126, v126
	s_waitcnt vmcnt(0)
	v_add_u32_e32 v251, s98, v232
	ds_write_b128 v251, v[184:187] offset:16384
	v_add_co_u32_e32 v252, vcc, 0x41000, v214
	s_nop 1
	v_addc_co_u32_e32 v253, vcc, 0, v215, vcc
	v_add_co_u32_e32 v254, vcc, 0x82000, v214
	s_nop 1
	v_addc_co_u32_e32 v255, vcc, 0, v215, vcc
	global_load_dwordx4 v[180:183], v[252:253], off
	global_load_dwordx4 v[184:187], v[252:253], off offset:-512
	global_load_dwordx4 v[192:195], v[254:255], off
	global_load_dwordx4 v[188:191], v[254:255], off offset:-512
	v_mfma_f32_32x32x16_bf16 v[2:17], v[136:139], v[102:105], v[2:17]
	v_exp_f32_e32 v127, v127
	v_mfma_f32_32x32x16_bf16 v[2:17], v[196:199], v[204:207], v[2:17]
	v_exp_f32_e32 v128, v128
	v_mfma_f32_32x32x16_bf16 v[2:17], v[140:143], v[208:211], v[2:17]
	v_exp_f32_e32 v129, v129
	v_cmp_gt_f32_e32 vcc, 1.0, v200
	s_cbranch_vccz .Lh2_467
	s_and_saveexec_b64 s[36:37], s[6:7]
	ds_write_b32 v220, v200 offset:128
	s_or_b64 exec, exec, s[36:37]
	s_waitcnt lgkmcnt(0)
	v_add_u32_e32 v110, v213, v212
	ds_read_b128 v[98:101], v110 offset:224
	ds_read_b128 v[102:105], v110 offset:192
	ds_read_b128 v[106:109], v110 offset:160
	ds_read_b128 v[132:135], v110 offset:128
	s_waitcnt lgkmcnt(3)
	v_pk_mul_f32 v[62:63], v[62:63], v[98:99]
	s_waitcnt lgkmcnt(2)
	v_pk_mul_f32 v[58:59], v[58:59], v[102:103]
	s_waitcnt lgkmcnt(1)
	v_pk_mul_f32 v[54:55], v[54:55], v[106:107]
	v_pk_mul_f32 v[64:65], v[64:65], v[100:101]
	v_pk_mul_f32 v[60:61], v[60:61], v[104:105]
	v_pk_mul_f32 v[56:57], v[56:57], v[108:109]
	s_waitcnt lgkmcnt(0)
	v_pk_mul_f32 v[52:53], v[52:53], v[134:135]
	v_pk_mul_f32 v[50:51], v[50:51], v[132:133]
	v_pk_mul_f32 v[46:47], v[46:47], v[98:99]
	v_pk_mul_f32 v[42:43], v[42:43], v[102:103]
	v_pk_mul_f32 v[38:39], v[38:39], v[106:107]
	v_pk_mul_f32 v[48:49], v[48:49], v[100:101]
	v_pk_mul_f32 v[44:45], v[44:45], v[104:105]
	v_pk_mul_f32 v[40:41], v[40:41], v[108:109]
	v_pk_mul_f32 v[36:37], v[36:37], v[134:135]
	v_pk_mul_f32 v[34:35], v[34:35], v[132:133]
	v_pk_mul_f32 v[30:31], v[30:31], v[98:99]
	v_pk_mul_f32 v[26:27], v[26:27], v[102:103]
	v_pk_mul_f32 v[22:23], v[22:23], v[106:107]
	v_pk_mul_f32 v[32:33], v[32:33], v[100:101]
	v_pk_mul_f32 v[28:29], v[28:29], v[104:105]
	v_pk_mul_f32 v[24:25], v[24:25], v[108:109]
	v_pk_mul_f32 v[20:21], v[20:21], v[134:135]
	v_pk_mul_f32 v[18:19], v[18:19], v[132:133]
	v_pk_mul_f32 v[14:15], v[14:15], v[98:99]
	v_pk_mul_f32 v[10:11], v[10:11], v[102:103]
	v_pk_mul_f32 v[6:7], v[6:7], v[106:107]
	v_pk_mul_f32 v[16:17], v[16:17], v[100:101]
	v_pk_mul_f32 v[12:13], v[12:13], v[104:105]
	v_pk_mul_f32 v[8:9], v[8:9], v[108:109]
	v_pk_mul_f32 v[4:5], v[4:5], v[134:135]
	v_pk_mul_f32 v[2:3], v[2:3], v[132:133]
.Lh2_467:
	v_add_f32_e32 v98, v246, v131
	v_add_f32_e32 v98, v245, v98
	v_add_f32_e32 v99, v202, v113
	v_fmac_f32_e32 v98, v244, v219
	v_add_f32_e32 v219, v201, v99
	s_add_i32 s78, s78, 2
	v_fmac_f32_e32 v219, v98, v130
	s_cmpk_gt_u32 s78, 0xfc
	v_lshl_add_u64 v[214:215], v[214:215], 0, s[22:23]
	s_waitcnt lgkmcnt(0)
	s_barrier
	s_cbranch_scc1 .LBB0_470
	s_xor_b32 s96, s96, 0x10000
	v_mov_b32_e32 v244, v200
	s_branch .Lh2_453

; #define SBAR() __builtin_amdgcn_sched_barrier(0)
; __device__ __forceinline__ unsigned cvtpk(float lo, float hi) { unsigned r; asm volatile("v_cvt_pk_bf16_f32 %0, %1, %2" : "=v"(r) : "v"(lo), "v"(hi)); return r; }
; __device__ __forceinline__ void qkt_fin(f32x16& n0, f32x16& n1, const bf16_t* Ks, const bf16x8* qr, const f32x16& negm, int r32, int hi, ...
;   float psa = 0.f, psb = 0.f; u32x4 wa, wb, wc, wd;
;     ...
; #pragma unroll
;   for (int d0 = 0; d0 < 8; ++d0) { int cb = (d0 * 16 + hi * 8) * 2;
;     bf16x8 b0 = *reinterpret_cast<const bf16x8*>((const char*)Ks + KSWZ(r32, cb));
;     bf16x8 b1 = *reinterpret_cast<const bf16x8*>((const char*)Ks + KSWZ(32 + r32, cb));
;     SBAR(); if (d0 == 0) n0 = __builtin_amdgcn_mfma_f32_32x32x16_bf16(b0, qr[0], negm, 0, 0, 0); else n0 = __builtin_amdgcn_mfma_f32_32x32x16_bf16(b0, qr[d0], n0, 0, 0, 0);
;     SBAR(); QF_CHUNK(2 * d0); SBAR();
;     if (d0 == 0) n1 = __builtin_amdgcn_mfma_f32_32x32x16_bf16(b1, qr[0], negm, 0, 0, 0); else n1 = __builtin_amdgcn_mfma_f32_32x32x16_bf16(b1, qr[d0], n1, 0, 0, 0);
;     SBAR(); QF_CHUNK(2 * d0 + 1); SBAR();
;     if (d0 == 7) { vf8_read<0>(vf0, vbv); SBAR(); } }
;     ...
;   psb += P1[15]; wd[3] = cvtpk(P1[14], P1[15]);
;   l_reg = l_reg * alpha + (psa + psb);
;   pa0 = *reinterpret_cast<bf16x8*>(&wa); pa1 = *reinterpret_cast<bf16x8*>(&wb); pa2 = *reinterpret_cast<bf16x8*>(&wc); pa3 = *reinterpret_cast<bf16x8*>(&wd);
; }
; __device__ __forceinline__ void attn_item(const bf16_t* __restrict__ Qb, const bf16_t* __restrict__ Kh, const bf16_t* __restrict__ Vh, const bf16_t* __restrict__ Zb, ...
;     ...
;   SBAR(); qkt_fin(pB0, pB1, (const bf16_t*)(lds + s_cur + KOFF), qr, negm, r32, hi, pA0, pA1, alA, l_reg, pa0, pa1, pa2, pa3, vfa, vb0 + s_prev); SBAR();
;   partialSM<false, false>(pB0, pB1, m_reg, negm, alB, track); SBAR(); pv_exp(o, vb0 + s_prev, pa0, pa1, pa2, pa3, pB0, vfa);
.LBB0_470:
	s_waitcnt vmcnt(0)
	s_mov_b32 s80, 0x18000
	s_mov_b32 s76, 0x10000
	v_add_u32_e32 v0, 0x18000, v235
	v_add3_u32 v98, s80, v234, v221
	ds_read_b128 v[130:133], v98 offset:16384
	ds_read_b128 v[134:137], v98 offset:24576
	v_add_u32_e32 v180, s76, v235
	s_waitcnt lgkmcnt(1)
	v_mfma_f32_32x32x16_bf16 v[98:113], v[130:133], v[152:155], v[66:81]
	v_exp_f32_e32 v82, v82
	v_add_f32_e32 v130, 0, v114
	v_mov_b32_e32 v131, v1
	s_waitcnt lgkmcnt(0)
	v_mfma_f32_32x32x16_bf16 v[66:81], v[134:137], v[152:155], v[66:81]
	v_exp_f32_e32 v83, v83
	v_add_f32_e32 v140, v115, v130
	v_add_f32_e32 v131, v131, v82
	v_cvt_pk_bf16_f32 v130, v114, v115
	v_add3_u32 v114, s80, v233, v221
	ds_read_b128 v[132:135], v114 offset:16384
	ds_read_b128 v[136:139], v114 offset:24576
	s_waitcnt lgkmcnt(1)
	v_mfma_f32_32x32x16_bf16 v[98:113], v[132:135], v[160:163], v[98:113]
	v_exp_f32_e32 v84, v84
	v_add_f32_e32 v114, v116, v140
	v_add_f32_e32 v115, v131, v83
	s_waitcnt lgkmcnt(0)
	v_mfma_f32_32x32x16_bf16 v[66:81], v[136:139], v[160:163], v[66:81]
	v_exp_f32_e32 v85, v85
	v_add_f32_e32 v132, v117, v114
	v_add_f32_e32 v133, v115, v84
	v_cvt_pk_bf16_f32 v131, v116, v117
	v_cvt_pk_bf16_f32 v134, v82, v83
	v_add3_u32 v135, s80, v230, v221
	ds_read_b128 v[114:117], v135 offset:16384
	ds_read_b128 v[136:139], v135 offset:24576
	s_waitcnt lgkmcnt(1)
	v_mfma_f32_32x32x16_bf16 v[98:113], v[114:117], v[148:151], v[98:113]
	v_exp_f32_e32 v86, v86
	v_add_f32_e32 v114, v118, v132
	v_add_f32_e32 v115, v133, v85
	s_waitcnt lgkmcnt(0)
	v_mfma_f32_32x32x16_bf16 v[66:81], v[136:139], v[148:151], v[66:81]
	v_exp_f32_e32 v87, v87
	v_add_f32_e32 v133, v119, v114
	v_add_f32_e32 v140, v115, v86
	v_cvt_pk_bf16_f32 v132, v118, v119
	v_cvt_pk_bf16_f32 v135, v84, v85
	v_add3_u32 v118, s80, v227, v221
	ds_read_b128 v[114:117], v118 offset:16384
	ds_read_b128 v[136:139], v118 offset:24576
	s_waitcnt lgkmcnt(1)
	v_mfma_f32_32x32x16_bf16 v[98:113], v[114:117], v[156:159], v[98:113]
	v_exp_f32_e32 v88, v88
	v_add_f32_e32 v114, v120, v133
	v_add_f32_e32 v115, v140, v87
	s_waitcnt lgkmcnt(0)
	v_mfma_f32_32x32x16_bf16 v[66:81], v[136:139], v[156:159], v[66:81]
	v_exp_f32_e32 v89, v89
	v_add_f32_e32 v137, v121, v114
	v_add_f32_e32 v138, v115, v88
	v_cvt_pk_bf16_f32 v133, v120, v121
	v_cvt_pk_bf16_f32 v136, v86, v87
	v_add3_u32 v118, s80, v226, v221
	ds_read_b128 v[114:117], v118 offset:16384
	ds_read_b128 v[118:121], v118 offset:24576
	s_waitcnt lgkmcnt(1)
	v_mfma_f32_32x32x16_bf16 v[98:113], v[114:117], v[168:171], v[98:113]
	v_exp_f32_e32 v90, v90
	v_add_f32_e32 v114, v122, v137
	v_add_f32_e32 v115, v138, v89
	s_waitcnt lgkmcnt(0)
	v_mfma_f32_32x32x16_bf16 v[66:81], v[118:121], v[168:171], v[66:81]
	v_exp_f32_e32 v91, v91
	v_add_f32_e32 v139, v123, v114
	v_add_f32_e32 v140, v115, v90
	v_cvt_pk_bf16_f32 v138, v122, v123
	v_cvt_pk_bf16_f32 v137, v88, v89
	v_add3_u32 v118, s80, v225, v221
	ds_read_b128 v[114:117], v118 offset:16384
	ds_read_b128 v[118:121], v118 offset:24576
	s_waitcnt lgkmcnt(1)
	v_mfma_f32_32x32x16_bf16 v[98:113], v[114:117], v[176:179], v[98:113]
	v_exp_f32_e32 v92, v92
	v_add_f32_e32 v114, v124, v139
	v_add_f32_e32 v115, v140, v91
	s_waitcnt lgkmcnt(0)
	v_mfma_f32_32x32x16_bf16 v[66:81], v[118:121], v[176:179], v[66:81]
	v_exp_f32_e32 v93, v93
	v_add_f32_e32 v122, v125, v114
	v_add_f32_e32 v123, v115, v92
	v_cvt_pk_bf16_f32 v139, v124, v125
	v_cvt_pk_bf16_f32 v142, v90, v91
	v_add3_u32 v118, s80, v224, v221
	ds_read_b128 v[114:117], v118 offset:16384
	ds_read_b128 v[118:121], v118 offset:24576
	s_waitcnt lgkmcnt(1)
	v_mfma_f32_32x32x16_bf16 v[98:113], v[114:117], v[164:167], v[98:113]
	v_exp_f32_e32 v94, v94
	v_add_f32_e32 v114, v126, v122
	v_add_f32_e32 v115, v123, v93
	s_waitcnt lgkmcnt(0)
	v_mfma_f32_32x32x16_bf16 v[66:81], v[118:121], v[164:167], v[66:81]
	v_exp_f32_e32 v95, v95
	v_add_f32_e32 v122, v127, v114
	v_add_f32_e32 v123, v115, v94
	v_cvt_pk_bf16_f32 v140, v126, v127
	v_cvt_pk_bf16_f32 v143, v92, v93
	v_add3_u32 v118, s80, v223, v221
	ds_read_b128 v[114:117], v118 offset:16384
	ds_read_b128 v[118:121], v118 offset:24576
	s_waitcnt lgkmcnt(1)
	v_mfma_f32_32x32x16_bf16 v[98:113], v[114:117], v[172:175], v[98:113]
	v_exp_f32_e32 v96, v96
	v_add_f32_e32 v114, v128, v122
	v_add_f32_e32 v115, v123, v95
	s_waitcnt lgkmcnt(0)
	v_mfma_f32_32x32x16_bf16 v[66:81], v[118:121], v[172:175], v[66:81]
	v_exp_f32_e32 v97, v97
	v_add_f32_e32 v150, v129, v114
	v_add_f32_e32 v151, v115, v96
	v_cvt_pk_bf16_f32 v141, v128, v129
	v_cvt_pk_bf16_f32 v144, v94, v95
	ds_read_b64_tr_b16 v[146:147], v180 offset:0
	ds_read_b64_tr_b16 v[148:149], v180 offset:0x800
	s_nop 0
	ds_read_b64_tr_b16 v[90:91], v180 offset:0x1000
	ds_read_b64_tr_b16 v[92:93], v180 offset:0x1800
	ds_read_b64_tr_b16 v[86:87], v180 offset:0x2000
	ds_read_b64_tr_b16 v[88:89], v180 offset:0x2800
	ds_read_b64_tr_b16 v[82:83], v180 offset:0x3000
	ds_read_b64_tr_b16 v[84:85], v180 offset:0x3800
	v_cvt_pk_bf16_f32 v145, v96, v97
	s_and_b64 vcc, exec, s[8:9]
	v_mov_b32_e32 v94, 1.0
	s_cbranch_vccnz .LBB0_472
	v_max_f32_e32 v94, v99, v99
	v_max_f32_e32 v95, v98, v98
	v_max_f32_e32 v94, v95, v94
	v_max3_f32 v94, v94, v100, v101
	v_max3_f32 v94, v94, v102, v103
	v_max3_f32 v94, v94, v104, v105
	v_max3_f32 v94, v94, v106, v107
	v_max3_f32 v94, v94, v108, v109
	v_max3_f32 v94, v94, v110, v111
	v_max3_f32 v94, v94, v112, v113
	v_max3_f32 v94, v94, v66, v67
	v_max3_f32 v94, v94, v68, v69
	v_max3_f32 v94, v94, v70, v71
	v_max3_f32 v94, v94, v72, v73
	v_max3_f32 v94, v94, v74, v75
	v_max3_f32 v94, v94, v76, v77
	v_max3_f32 v94, v94, v78, v79
	v_max3_f32 v94, v94, v80, v81
	v_mov_b32_e32 v95, v94
	s_nop 1
	v_permlane32_swap_b32_e32 v94, v95
	v_max_f32_e32 v95, v95, v95
	v_max_f32_e32 v94, v94, v94
	v_max_f32_e32 v95, v94, v95
	v_cmp_ge_f32_e32 vcc, s69, v95
	s_cmp_eq_u64 vcc, exec
	v_mov_b32_e32 v94, 1.0
	s_cbranch_scc0 .LBB0_478

; __global__ void __launch_bounds__(512, 2) fwd_megakernel(Args a) {
;   extern __shared__ __attribute__((aligned(16))) unsigned char lds[];
;   cg::grid_group grid = cg::this_grid();
;   const int G = gridDim.x, c = blockIdx.x, wid_s = __builtin_amdgcn_readfirstlane((int)threadIdx.x >> 6);
	.amdhsa_kernel _Z14fwd_megakernel4Args
		.amdhsa_group_segment_fixed_size 0
		.amdhsa_private_segment_fixed_size 0
		.amdhsa_kernarg_size 352
		.amdhsa_user_sgpr_count 2
		.amdhsa_user_sgpr_dispatch_ptr 0
		.amdhsa_user_sgpr_queue_ptr 0
		.amdhsa_user_sgpr_kernarg_segment_ptr 1
		.amdhsa_user_sgpr_dispatch_id 0
		.amdhsa_user_sgpr_kernarg_preload_length 0
		.amdhsa_user_sgpr_kernarg_preload_offset 0
		.amdhsa_user_sgpr_private_segment_size 0
		.amdhsa_uses_dynamic_stack 0
		.amdhsa_enable_private_segment 0
		.amdhsa_system_sgpr_workgroup_id_x 1
		.amdhsa_system_sgpr_workgroup_id_y 0
		.amdhsa_system_sgpr_workgroup_id_z 0
		.amdhsa_system_sgpr_workgroup_info 0
		.amdhsa_system_vgpr_workitem_id 2
		.amdhsa_next_free_vgpr 256
		.amdhsa_next_free_sgpr 100
		.amdhsa_accum_offset 256
		.amdhsa_reserve_vcc 1
		.amdhsa_float_round_mode_32 0
		.amdhsa_float_round_mode_16_64 0
		.amdhsa_float_denorm_mode_32 3
		.amdhsa_float_denorm_mode_16_64 3
		.amdhsa_dx10_clamp 1
		.amdhsa_ieee_mode 1
		.amdhsa_fp16_overflow 0
		.amdhsa_tg_split 0
		.amdhsa_exception_fp_ieee_invalid_op 0
		.amdhsa_exception_fp_denorm_src 0
		.amdhsa_exception_fp_ieee_div_zero 0
		.amdhsa_exception_fp_ieee_overflow 0
		.amdhsa_exception_fp_ieee_underflow 0
		.amdhsa_exception_fp_ieee_inexact 0
		.amdhsa_exception_int_div_zero 0
	.end_amdhsa_kernel

; __global__ void __launch_bounds__(512, 2) fwd_megakernel(Args a) {
;   extern __shared__ __attribute__((aligned(16))) unsigned char lds[];
;   cg::grid_group grid = cg::this_grid();
;   const int G = gridDim.x, c = blockIdx.x, wid_s = __builtin_amdgcn_readfirstlane((int)threadIdx.x >> 6);
amdhsa.kernels:
  - .agpr_count:     0
    .args:
      - .offset:         0
        .size:           96
        .value_kind:     by_value
      - .offset:         96
        .size:           4
        .value_kind:     hidden_block_count_x
      - .offset:         100
        .size:           4
        .value_kind:     hidden_block_count_y
      - .offset:         104
        .size:           4
        .value_kind:     hidden_block_count_z
      - .offset:         108
        .size:           2
        .value_kind:     hidden_group_size_x
      - .offset:         110
        .size:           2
        .value_kind:     hidden_group_size_y
      - .offset:         112
        .size:           2
        .value_kind:     hidden_group_size_z
      - .offset:         114
        .size:           2
        .value_kind:     hidden_remainder_x
      - .offset:         116
        .size:           2
        .value_kind:     hidden_remainder_y
      - .offset:         118
        .size:           2
        .value_kind:     hidden_remainder_z
      - .offset:         136
        .size:           8
        .value_kind:     hidden_global_offset_x
      - .offset:         144
        .size:           8
        .value_kind:     hidden_global_offset_y
      - .offset:         152
        .size:           8
        .value_kind:     hidden_global_offset_z
      - .offset:         160
        .size:           2
        .value_kind:     hidden_grid_dims
      - .offset:         184
        .size:           8
        .value_kind:     hidden_multigrid_sync_arg
      - .offset:         216
        .size:           4
        .value_kind:     hidden_dynamic_lds_size
    .group_segment_fixed_size: 0
    .kernarg_segment_align: 8
    .kernarg_segment_size: 352
    .language:       OpenCL C
    .language_version:
      - 2
      - 0
    .max_flat_workgroup_size: 512
    .name:           _Z14fwd_megakernel4Args
    .private_segment_fixed_size: 0
    .sgpr_count:     106
    .sgpr_spill_count: 0
    .symbol:         _Z14fwd_megakernel4Args.kd
    .uniform_work_group_size: 1
    .uses_dynamic_stack: false
    .vgpr_count:     256
    .vgpr_spill_count: 0
    .wavefront_size: 64
